# combo1 + the 181 satisfied s_waitcnt lgkmcnt(N) inside GEMM MMA phases deleted (setprio flips kept)
# speedup vs baseline: 1.0046x; 1.0046x over previous
; #define PG8_STAGE(bufoff, gbase, voff) glds16s2((voff)[0], (voff)[1], (const void*)(gbase), ldsn + (unsigned)(bufoff))
; #define PG8_LDA(dst, b, h) do { _Pragma("unroll") for (int m = 0; m < 4; ++m) _Pragma("unroll") for (int k = 0; k < 2; ++k) dst[m][k] = *(const LAS bf16x8*)(lds + PG8_SA(b, h) + aoff + m * 2048 + k * 1024); } while (0)
; #define PG8_LDB(dst, b, h) do { _Pragma("unroll") for (int n = 0; n < 2; ++n) _Pragma("unroll") for (int k = 0; k < 2; ++k) dst[n][k] = *(const LAS bf16x8*)(lds + PG8_SB(b, h) + boff + n * 2048 + k * 1024); } while (0)
; #define PG8_MMA(ai, bj, At, Bt) do { __builtin_amdgcn_s_setprio(1); _Pragma("unroll") for (int m = 0; m < 4; ++m) _Pragma("unroll") for (int n = 0; n < 2; ++n) _Pragma("unroll") for (int k = 0; k < 2; ++k) \
;         acc[ai][bj][m][n] = __builtin_amdgcn_mfma_f32_16x16x32_bf16(Bt[n][k], At[m][k], acc[ai][bj][m][n], 0, 0, 0); __builtin_amdgcn_s_setprio(0); } while (0)
; #define PG8_WAIT_V(n) asm volatile("s_waitcnt vmcnt(" #n ")" ::: "memory")
; #define PG8_WAIT_L(n) asm volatile("s_waitcnt lgkmcnt(" #n ")" ::: "memory")
; #define PG8_BAR __builtin_amdgcn_s_barrier()
; #define PG8_SCHED __builtin_amdgcn_sched_barrier(0)
; template <class Epi, bool ALIGN_EPI, bool EARLY_DRAIN = true, class Pre = NoPre>
; __device__ __forceinline__ void gemm_phase(LAS unsigned char* lds, const Gemm g, const StaticOrder& S, const Epi& E, int wv, const Pre& pre = Pre()) {
;     ...
;             PG8_WAIT_L(0); PG8_BAR; PG8_MMA(0, 0, At, B0); PG8_MMA(0, 1, At, B1); PG8_BAR; PG8_SCHED;
;             PG8_LDA(At, 0, 1); PG8_STAGE(PG8_SB(0, 0), b2, voffB); PG8_STAGE(PG8_SB(0, 1), b2 + bhs, voffB); PG8_STAGE(PG8_SA(0, 0), a2, voffA);
;             if (!lf_) PG8_WAIT_V(8);
;             PG8_WAIT_L(0); PG8_BAR; PG8_MMA(1, 0, At, B0); PG8_MMA(1, 1, At, B1); PG8_BAR; PG8_SCHED;
;             PG8_LDB(B0, 1, 0); PG8_LDB(B1, 1, 1); PG8_SCHED; PG8_LDA(At, 1, 0); PG8_STAGE(PG8_SA(0, 1), a2 + ahs, voffA);
;             if (!lf_) PG8_WAIT_V(8);
.LBB0_172:
	s_add_u32 s50, s70, 0x100
	s_addc_u32 s51, s71, 0
	s_waitcnt lgkmcnt(0)
	s_add_u32 s38, s68, 0x100
	s_addc_u32 s39, s69, 0
	s_barrier
	s_setprio 1
	v_mfma_f32_16x16x32_bf16 v[2:5], v[86:89], v[38:41], 0
	v_mfma_f32_16x16x32_bf16 v[6:9], v[94:97], v[38:41], 0
	v_mfma_f32_16x16x32_bf16 v[10:13], v[86:89], v[46:49], 0
	v_mfma_f32_16x16x32_bf16 v[14:17], v[94:97], v[46:49], 0
	v_mfma_f32_16x16x32_bf16 v[18:21], v[86:89], v[58:61], 0
	v_mfma_f32_16x16x32_bf16 v[22:25], v[94:97], v[58:61], 0
	v_mfma_f32_16x16x32_bf16 v[26:29], v[86:89], v[74:77], 0
	v_mfma_f32_16x16x32_bf16 v[30:33], v[94:97], v[74:77], 0
	v_mfma_f32_16x16x32_bf16 v[2:5], v[90:93], v[42:45], v[2:5]
	v_mfma_f32_16x16x32_bf16 v[6:9], v[98:101], v[42:45], v[6:9]
	v_mfma_f32_16x16x32_bf16 v[10:13], v[90:93], v[54:57], v[10:13]
	v_mfma_f32_16x16x32_bf16 v[14:17], v[98:101], v[54:57], v[14:17]
	v_mfma_f32_16x16x32_bf16 v[18:21], v[90:93], v[66:69], v[18:21]
	v_mfma_f32_16x16x32_bf16 v[22:25], v[98:101], v[66:69], v[22:25]
	v_mfma_f32_16x16x32_bf16 v[26:29], v[90:93], v[78:81], v[26:29]
	v_mfma_f32_16x16x32_bf16 v[30:33], v[98:101], v[78:81], v[30:33]
	s_setprio 0
	s_setprio 1
	v_mfma_f32_16x16x32_bf16 v[34:37], v[50:53], v[38:41], 0
	v_mfma_f32_16x16x32_bf16 v[38:41], v[70:73], v[38:41], 0
	v_mfma_f32_16x16x32_bf16 v[34:37], v[62:65], v[42:45], v[34:37]
	v_mfma_f32_16x16x32_bf16 v[38:41], v[82:85], v[42:45], v[38:41]
	v_mfma_f32_16x16x32_bf16 v[42:45], v[50:53], v[46:49], 0
	v_mfma_f32_16x16x32_bf16 v[46:49], v[70:73], v[46:49], 0
	v_mfma_f32_16x16x32_bf16 v[42:45], v[62:65], v[54:57], v[42:45]
	v_mfma_f32_16x16x32_bf16 v[46:49], v[82:85], v[54:57], v[46:49]
	v_mfma_f32_16x16x32_bf16 v[54:57], v[50:53], v[58:61], 0
	v_mfma_f32_16x16x32_bf16 v[58:61], v[70:73], v[58:61], 0
	v_mfma_f32_16x16x32_bf16 v[54:57], v[62:65], v[66:69], v[54:57]
	v_mfma_f32_16x16x32_bf16 v[58:61], v[82:85], v[66:69], v[58:61]
	v_mfma_f32_16x16x32_bf16 v[66:69], v[50:53], v[74:77], 0
	v_mfma_f32_16x16x32_bf16 v[74:77], v[70:73], v[74:77], 0
	v_mfma_f32_16x16x32_bf16 v[66:69], v[62:65], v[78:81], v[66:69]
	v_mfma_f32_16x16x32_bf16 v[74:77], v[82:85], v[78:81], v[74:77]
	s_setprio 0
	s_barrier
	ds_read_b128 v[126:129], v244 offset:16384
	ds_read_b128 v[162:165], v244 offset:17408
	ds_read_b128 v[118:121], v244 offset:18432
	ds_read_b128 v[122:125], v244 offset:19456
	ds_read_b128 v[110:113], v244 offset:20480
	ds_read_b128 v[114:117], v244 offset:21504
	ds_read_b128 v[102:105], v244 offset:22528
	ds_read_b128 v[106:109], v244 offset:23552
	s_mov_b32 m0, s10
	s_nop 0
	global_load_lds_dwordx4 v230, s[38:39]
	s_add_u32 m0, m0, 0x2000
	s_nop 0
	global_load_lds_dwordx4 v232, s[38:39]
	s_add_u32 s38, s68, 0x40100
	s_addc_u32 s39, s69, 0
	s_mov_b32 m0, s12
	s_nop 0
	global_load_lds_dwordx4 v230, s[38:39]
	s_add_u32 m0, m0, 0x2000
	s_nop 0
	global_load_lds_dwordx4 v232, s[38:39]
	v_cndmask_b32_e64 v78, 0, 1, s[84:85]
	s_mov_b32 m0, s5
	s_nop 0
	global_load_lds_dwordx4 v0, s[50:51]
	s_add_u32 m0, m0, 0x2000
	s_nop 0
	global_load_lds_dwordx4 v231, s[50:51]
	v_cmp_ne_u32_e64 s[38:39], 1, v78
	s_andn2_b64 vcc, exec, s[84:85]
	s_cbranch_vccnz .LBB0_174
	s_waitcnt vmcnt(8)
.LBB0_174:
	s_waitcnt lgkmcnt(0)
	s_barrier
	s_setprio 1
	v_mfma_f32_16x16x32_bf16 v[78:81], v[86:89], v[126:129], 0
	v_mfma_f32_16x16x32_bf16 v[134:137], v[86:89], v[118:121], 0
	v_mfma_f32_16x16x32_bf16 v[142:145], v[86:89], v[110:113], 0
	v_mfma_f32_16x16x32_bf16 v[86:89], v[86:89], v[102:105], 0
	v_mfma_f32_16x16x32_bf16 v[130:133], v[94:97], v[126:129], 0
	v_mfma_f32_16x16x32_bf16 v[138:141], v[94:97], v[118:121], 0
	v_mfma_f32_16x16x32_bf16 v[146:149], v[94:97], v[110:113], 0
	v_mfma_f32_16x16x32_bf16 v[150:153], v[90:93], v[106:109], v[86:89]
	v_mfma_f32_16x16x32_bf16 v[86:89], v[94:97], v[102:105], 0
	v_mfma_f32_16x16x32_bf16 v[78:81], v[90:93], v[162:165], v[78:81]
	v_mfma_f32_16x16x32_bf16 v[130:133], v[98:101], v[162:165], v[130:133]
	v_mfma_f32_16x16x32_bf16 v[134:137], v[90:93], v[122:125], v[134:137]
	v_mfma_f32_16x16x32_bf16 v[138:141], v[98:101], v[122:125], v[138:141]
	v_mfma_f32_16x16x32_bf16 v[142:145], v[90:93], v[114:117], v[142:145]
	v_mfma_f32_16x16x32_bf16 v[146:149], v[98:101], v[114:117], v[146:149]
	v_mfma_f32_16x16x32_bf16 v[154:157], v[98:101], v[106:109], v[86:89]
	s_setprio 0
	s_setprio 1
	v_mfma_f32_16x16x32_bf16 v[86:89], v[50:53], v[126:129], 0
	v_mfma_f32_16x16x32_bf16 v[158:161], v[62:65], v[162:165], v[86:89]
	v_mfma_f32_16x16x32_bf16 v[86:89], v[70:73], v[126:129], 0
	v_mfma_f32_16x16x32_bf16 v[162:165], v[82:85], v[162:165], v[86:89]
	v_mfma_f32_16x16x32_bf16 v[86:89], v[50:53], v[118:121], 0
	v_mfma_f32_16x16x32_bf16 v[166:169], v[62:65], v[122:125], v[86:89]
	v_mfma_f32_16x16x32_bf16 v[86:89], v[70:73], v[118:121], 0
	v_mfma_f32_16x16x32_bf16 v[170:173], v[82:85], v[122:125], v[86:89]
	v_mfma_f32_16x16x32_bf16 v[86:89], v[50:53], v[110:113], 0
	v_mfma_f32_16x16x32_bf16 v[50:53], v[50:53], v[102:105], 0
	v_mfma_f32_16x16x32_bf16 v[174:177], v[62:65], v[114:117], v[86:89]
	v_mfma_f32_16x16x32_bf16 v[86:89], v[70:73], v[110:113], 0
	v_mfma_f32_16x16x32_bf16 v[182:185], v[62:65], v[106:109], v[50:53]
	v_mfma_f32_16x16x32_bf16 v[50:53], v[70:73], v[102:105], 0
	v_mfma_f32_16x16x32_bf16 v[178:181], v[82:85], v[114:117], v[86:89]
	v_mfma_f32_16x16x32_bf16 v[186:189], v[82:85], v[106:109], v[50:53]
	s_setprio 0
	s_barrier
	v_add_u32_e32 v234, 0x18000, v233
	v_add_u32_e32 v235, 0x1c000, v233
	ds_read_b128 v[206:209], v234
	ds_read_b128 v[210:213], v234 offset:1024
	ds_read_b128 v[214:217], v234 offset:2048
	ds_read_b128 v[218:221], v234 offset:3072
	ds_read_b128 v[190:193], v235
	ds_read_b128 v[194:197], v235 offset:1024
	ds_read_b128 v[198:201], v235 offset:2048
	ds_read_b128 v[202:205], v235 offset:3072
	ds_read_b128 v[110:113], v244 offset:32768
	ds_read_b128 v[118:121], v244 offset:33792
	ds_read_b128 v[94:97], v244 offset:34816
	ds_read_b128 v[102:105], v244 offset:35840
	ds_read_b128 v[70:73], v244 offset:36864
	ds_read_b128 v[86:89], v244 offset:37888
	ds_read_b128 v[222:225], v244 offset:38912
	ds_read_b128 v[226:229], v244 offset:39936
	s_add_u32 s50, s70, 0x40100
	s_addc_u32 s51, s71, 0
	s_mov_b32 m0, s13
	s_nop 0
	global_load_lds_dwordx4 v0, s[50:51]
	s_add_u32 m0, m0, 0x2000
	s_nop 0
	global_load_lds_dwordx4 v231, s[50:51]
	s_and_b64 vcc, exec, s[38:39]
	s_cbranch_vccnz .LBB0_176
	s_waitcnt vmcnt(8)
; #define PG8_WAIT_V(n) asm volatile("s_waitcnt vmcnt(" #n ")" ::: "memory")
; template <class Epi, bool ALIGN_EPI, bool EARLY_DRAIN = true, class Pre = NoPre>
; __device__ __forceinline__ void gemm_phase(LAS unsigned char* lds, const Gemm g, const StaticOrder& S, const Epi& E, int wv, const Pre& pre = Pre()) {
;     ...
;         const char* nA = has_next ? g.A + (size_t)nxt.pm * g.a_tstep + (size_t)(nxt.pm >> 6) * g.a_pad : cA; const char* nB = has_next ? g.Bt + (size_t)nxt.pn * g.b_tstep : cB;
;         int landed_flag = fresh ? 1 : 0;
;         typename Epi::PF pf;
;         if constexpr (Epi::PREF) { int pt_ = lane_now(); asm volatile("" : "+v"(pt_)); E.prefetch(pf, cur, wr, wc, pt_ & 15, pt_ >> 4); }
;         for (int th = 0; th < nt; th += (Epi::MIDK ? nt / 2 : nt)) {
;         if constexpr (Epi::MIDK) { if (th) E.midk(acc, ui, wr, fr); }
;         for (int t = th; t < th + (Epi::MIDK ? nt / 2 : nt); t += 2) {
;             const bool last = (t == nt - 2);
;             const char* a1 = cA + (size_t)(t + 1) * kstep;
;             const char* a2 = last ? nA : cA + (size_t)(t + 2) * kstep; const char* b2 = last ? nB : cB + (size_t)(t + 2) * kstep;
;             const char* a3 = a2 + kstep; const char* b3 = b2 + kstep;
;             int lf_ = EARLY_DRAIN ? __builtin_amdgcn_readfirstlane(landed_flag) : landed_flag; if constexpr (EARLY_DRAIN) asm volatile("" : "+s"(lf_)); landed_flag = 0;
;             PG8_LDB(B0, 0, 0); PG8_LDB(B1, 0, 1); PG8_SCHED; PG8_LDA(At, 0, 0); PG8_STAGE(PG8_SA(1, 1), a1 + ahs, voffA);
;             if (!lf_) PG8_WAIT_V(8);
;             PG8_WAIT_L(0); PG8_BAR; PG8_MMA(0, 0, At, B0); PG8_MMA(0, 1, At, B1); PG8_BAR; PG8_SCHED;
;             PG8_LDA(At, 0, 1); PG8_STAGE(PG8_SB(0, 0), b2, voffB); PG8_STAGE(PG8_SB(0, 1), b2 + bhs, voffB); PG8_STAGE(PG8_SA(0, 0), a2, voffA);
;             if (!lf_) PG8_WAIT_V(8);
;             PG8_WAIT_L(0); PG8_BAR; PG8_MMA(1, 0, At, B0); PG8_MMA(1, 1, At, B1); PG8_BAR; PG8_SCHED;
;             PG8_LDB(B0, 1, 0); PG8_LDB(B1, 1, 1); PG8_SCHED; PG8_LDA(At, 1, 0); PG8_STAGE(PG8_SA(0, 1), a2 + ahs, voffA);
;             if (!lf_) PG8_WAIT_V(8);
;             PG8_WAIT_L(0); PG8_BAR; PG8_MMA(0, 0, At, B0); PG8_MMA(0, 1, At, B1); PG8_BAR; PG8_SCHED;
;             PG8_LDA(At, 1, 1); PG8_STAGE(PG8_SB(1, 0), b3, voffB); PG8_STAGE(PG8_SB(1, 1), b3 + bhs, voffB); PG8_STAGE(PG8_SA(1, 0), a3, voffA);
.LBB0_176:
	s_ashr_i32 s43, s42, 31
	s_lshl_b64 s[38:39], s[42:43], 19
	s_add_u32 s38, s4, s38
	s_addc_u32 s39, s9, s39
	s_and_b64 s[36:37], s[36:37], exec
	s_cselect_b32 s43, s39, s69
	s_cselect_b32 s47, s38, s68
	s_add_u32 s36, s70, 0x180
	s_addc_u32 s37, s71, 0
	s_waitcnt lgkmcnt(0)
	s_add_u32 s50, s68, 0x180
	s_addc_u32 s51, s69, 0
	s_barrier
	s_setprio 1
	v_mfma_f32_16x16x32_bf16 v[2:5], v[206:209], v[110:113], v[2:5]
	v_mfma_f32_16x16x32_bf16 v[122:125], v[210:213], v[118:121], v[2:5]
	v_mfma_f32_16x16x32_bf16 v[2:5], v[214:217], v[110:113], v[6:9]
	v_mfma_f32_16x16x32_bf16 v[114:117], v[218:221], v[118:121], v[2:5]
	v_mfma_f32_16x16x32_bf16 v[2:5], v[206:209], v[94:97], v[10:13]
	v_mfma_f32_16x16x32_bf16 v[106:109], v[210:213], v[102:105], v[2:5]
	v_mfma_f32_16x16x32_bf16 v[2:5], v[214:217], v[94:97], v[14:17]
	v_mfma_f32_16x16x32_bf16 v[98:101], v[218:221], v[102:105], v[2:5]
	v_mfma_f32_16x16x32_bf16 v[2:5], v[206:209], v[70:73], v[18:21]
	v_mfma_f32_16x16x32_bf16 v[90:93], v[210:213], v[86:89], v[2:5]
	v_mfma_f32_16x16x32_bf16 v[2:5], v[214:217], v[70:73], v[22:25]
	v_mfma_f32_16x16x32_bf16 v[82:85], v[218:221], v[86:89], v[2:5]
	v_mfma_f32_16x16x32_bf16 v[2:5], v[206:209], v[222:225], v[26:29]
	v_mfma_f32_16x16x32_bf16 v[62:65], v[210:213], v[226:229], v[2:5]
	v_mfma_f32_16x16x32_bf16 v[2:5], v[214:217], v[222:225], v[30:33]
	v_mfma_f32_16x16x32_bf16 v[50:53], v[218:221], v[226:229], v[2:5]
	s_setprio 0
	s_setprio 1
	v_mfma_f32_16x16x32_bf16 v[2:5], v[190:193], v[110:113], v[34:37]
	v_mfma_f32_16x16x32_bf16 v[126:129], v[194:197], v[118:121], v[2:5]
	v_mfma_f32_16x16x32_bf16 v[2:5], v[198:201], v[110:113], v[38:41]
	v_mfma_f32_16x16x32_bf16 v[118:121], v[202:205], v[118:121], v[2:5]
	v_mfma_f32_16x16x32_bf16 v[2:5], v[190:193], v[94:97], v[42:45]
	v_mfma_f32_16x16x32_bf16 v[110:113], v[194:197], v[102:105], v[2:5]
	v_mfma_f32_16x16x32_bf16 v[2:5], v[198:201], v[94:97], v[46:49]
	v_mfma_f32_16x16x32_bf16 v[102:105], v[202:205], v[102:105], v[2:5]
	v_mfma_f32_16x16x32_bf16 v[2:5], v[190:193], v[70:73], v[54:57]
	v_mfma_f32_16x16x32_bf16 v[94:97], v[194:197], v[86:89], v[2:5]
	v_mfma_f32_16x16x32_bf16 v[2:5], v[198:201], v[70:73], v[58:61]
	v_mfma_f32_16x16x32_bf16 v[86:89], v[202:205], v[86:89], v[2:5]
	v_mfma_f32_16x16x32_bf16 v[2:5], v[190:193], v[222:225], v[66:69]
	v_mfma_f32_16x16x32_bf16 v[70:73], v[194:197], v[226:229], v[2:5]
	v_mfma_f32_16x16x32_bf16 v[2:5], v[198:201], v[222:225], v[74:77]
	v_mfma_f32_16x16x32_bf16 v[54:57], v[202:205], v[226:229], v[2:5]
	s_setprio 0
	s_barrier
	ds_read_b128 v[6:9], v244 offset:49152
	ds_read_b128 v[14:17], v244 offset:50176
	ds_read_b128 v[22:25], v244 offset:51200
	ds_read_b128 v[30:33], v244 offset:52224
	ds_read_b128 v[222:225], v244 offset:53248
	ds_read_b128 v[226:229], v244 offset:54272
	ds_read_b128 v[236:239], v244 offset:55296
	ds_read_b128 v[240:243], v244 offset:56320
	s_mov_b32 m0, s23
	s_nop 0
	global_load_lds_dwordx4 v230, s[50:51]
	s_add_u32 m0, m0, 0x2000
	s_nop 0
	global_load_lds_dwordx4 v232, s[50:51]
	s_add_u32 s50, s68, 0x40180
	s_addc_u32 s51, s69, 0
	s_mov_b32 m0, s25
	s_nop 0
	global_load_lds_dwordx4 v230, s[50:51]
	s_add_u32 m0, m0, 0x2000
	s_nop 0
	global_load_lds_dwordx4 v232, s[50:51]
	s_nop 0
	s_mov_b32 m0, s24
	s_nop 0
	global_load_lds_dwordx4 v0, s[36:37]
	s_add_u32 m0, m0, 0x2000
	s_nop 0
	global_load_lds_dwordx4 v231, s[36:37]
	s_waitcnt vmcnt(8)
	s_waitcnt lgkmcnt(0)
	s_barrier
	s_setprio 1
	v_mfma_f32_16x16x32_bf16 v[2:5], v[206:209], v[6:9], v[78:81]
	v_mfma_f32_16x16x32_bf16 v[74:77], v[210:213], v[14:17], v[2:5]
	v_mfma_f32_16x16x32_bf16 v[2:5], v[214:217], v[6:9], v[130:133]
	v_mfma_f32_16x16x32_bf16 v[58:61], v[218:221], v[14:17], v[2:5]
	v_mfma_f32_16x16x32_bf16 v[2:5], v[206:209], v[22:25], v[134:137]
	v_mfma_f32_16x16x32_bf16 v[42:45], v[210:213], v[30:33], v[2:5]
	v_mfma_f32_16x16x32_bf16 v[2:5], v[214:217], v[22:25], v[138:141]
	v_mfma_f32_16x16x32_bf16 v[34:37], v[218:221], v[30:33], v[2:5]
	v_mfma_f32_16x16x32_bf16 v[2:5], v[206:209], v[222:225], v[142:145]
	v_mfma_f32_16x16x32_bf16 v[26:29], v[210:213], v[226:229], v[2:5]
	v_mfma_f32_16x16x32_bf16 v[2:5], v[214:217], v[222:225], v[146:149]
	v_mfma_f32_16x16x32_bf16 v[18:21], v[218:221], v[226:229], v[2:5]
	v_mfma_f32_16x16x32_bf16 v[2:5], v[206:209], v[236:239], v[150:153]
	v_mfma_f32_16x16x32_bf16 v[10:13], v[210:213], v[240:243], v[2:5]
	v_mfma_f32_16x16x32_bf16 v[2:5], v[214:217], v[236:239], v[154:157]
	v_mfma_f32_16x16x32_bf16 v[2:5], v[218:221], v[240:243], v[2:5]
	s_setprio 0
	s_setprio 1
	v_mfma_f32_16x16x32_bf16 v[38:41], v[190:193], v[6:9], v[158:161]
	v_mfma_f32_16x16x32_bf16 v[6:9], v[198:201], v[6:9], v[162:165]
	v_mfma_f32_16x16x32_bf16 v[66:69], v[202:205], v[14:17], v[6:9]
	v_mfma_f32_16x16x32_bf16 v[6:9], v[190:193], v[22:25], v[166:169]
	v_mfma_f32_16x16x32_bf16 v[46:49], v[194:197], v[30:33], v[6:9]
	v_mfma_f32_16x16x32_bf16 v[6:9], v[198:201], v[22:25], v[170:173]
	v_mfma_f32_16x16x32_bf16 v[78:81], v[194:197], v[14:17], v[38:41]
	v_mfma_f32_16x16x32_bf16 v[38:41], v[202:205], v[30:33], v[6:9]
	v_mfma_f32_16x16x32_bf16 v[6:9], v[190:193], v[222:225], v[174:177]
	v_mfma_f32_16x16x32_bf16 v[30:33], v[194:197], v[226:229], v[6:9]
	v_mfma_f32_16x16x32_bf16 v[6:9], v[198:201], v[222:225], v[178:181]
	v_mfma_f32_16x16x32_bf16 v[22:25], v[202:205], v[226:229], v[6:9]
	v_mfma_f32_16x16x32_bf16 v[6:9], v[190:193], v[236:239], v[182:185]
	v_mfma_f32_16x16x32_bf16 v[14:17], v[194:197], v[240:243], v[6:9]
	v_mfma_f32_16x16x32_bf16 v[6:9], v[198:201], v[236:239], v[186:189]
	v_mfma_f32_16x16x32_bf16 v[6:9], v[202:205], v[240:243], v[6:9]
	s_setprio 0
	s_barrier
	s_add_u32 s50, s70, 0x200
	s_addc_u32 s51, s71, 0
	s_add_u32 s52, s68, 0x200
	s_addc_u32 s53, s69, 0
	s_add_u32 s68, s70, 0x40180
	s_addc_u32 s69, s71, 0
	s_mov_b32 s64, 0
	s_branch .LBB0_178
; #define PG8_STAGE(bufoff, gbase, voff) glds16s2((voff)[0], (voff)[1], (const void*)(gbase), ldsn + (unsigned)(bufoff))
; #define PG8_LDA(dst, b, h) do { _Pragma("unroll") for (int m = 0; m < 4; ++m) _Pragma("unroll") for (int k = 0; k < 2; ++k) dst[m][k] = *(const LAS bf16x8*)(lds + PG8_SA(b, h) + aoff + m * 2048 + k * 1024); } while (0)
; #define PG8_WAIT_V(n) asm volatile("s_waitcnt vmcnt(" #n ")" ::: "memory")
; #define PG8_WAIT_L(n) asm volatile("s_waitcnt lgkmcnt(" #n ")" ::: "memory")
; template <class Epi, bool ALIGN_EPI, bool EARLY_DRAIN = true, class Pre = NoPre>
; __device__ __forceinline__ void gemm_phase(LAS unsigned char* lds, const Gemm g, const StaticOrder& S, const Epi& E, int wv, const Pre& pre = Pre()) {
;     ...
;         for (int t = th; t < th + (Epi::MIDK ? nt / 2 : nt); t += 2) {
;             const bool last = (t == nt - 2);
;             const char* a1 = cA + (size_t)(t + 1) * kstep;
;             const char* a2 = last ? nA : cA + (size_t)(t + 2) * kstep; const char* b2 = last ? nB : cB + (size_t)(t + 2) * kstep;
;             const char* a3 = a2 + kstep; const char* b3 = b2 + kstep;
;             int lf_ = EARLY_DRAIN ? __builtin_amdgcn_readfirstlane(landed_flag) : landed_flag; if constexpr (EARLY_DRAIN) asm volatile("" : "+s"(lf_)); landed_flag = 0;
;             PG8_LDB(B0, 0, 0); PG8_LDB(B1, 0, 1); PG8_SCHED; PG8_LDA(At, 0, 0); PG8_STAGE(PG8_SA(1, 1), a1 + ahs, voffA);
;             if (!lf_) PG8_WAIT_V(8);
;             PG8_WAIT_L(0); PG8_BAR; PG8_MMA(0, 0, At, B0); PG8_MMA(0, 1, At, B1); PG8_BAR; PG8_SCHED;
;             PG8_LDA(At, 0, 1); PG8_STAGE(PG8_SB(0, 0), b2, voffB); PG8_STAGE(PG8_SB(0, 1), b2 + bhs, voffB); PG8_STAGE(PG8_SA(0, 0), a2, voffA);
;             if (!lf_) PG8_WAIT_V(8);
;             PG8_WAIT_L(0); PG8_BAR; PG8_MMA(1, 0, At, B0); PG8_MMA(1, 1, At, B1); PG8_BAR; PG8_SCHED;
;             PG8_LDB(B0, 1, 0); PG8_LDB(B1, 1, 1); PG8_SCHED; PG8_LDA(At, 1, 0); PG8_STAGE(PG8_SA(0, 1), a2 + ahs, voffA);
;             if (!lf_) PG8_WAIT_V(8);
;             PG8_WAIT_L(0); PG8_BAR; PG8_MMA(0, 0, At, B0); PG8_MMA(0, 1, At, B1); PG8_BAR; PG8_SCHED;
;             PG8_LDA(At, 1, 1); PG8_STAGE(PG8_SB(1, 0), b3, voffB); PG8_STAGE(PG8_SB(1, 1), b3 + bhs, voffB); PG8_STAGE(PG8_SA(1, 0), a3, voffA);
;             PG8_WAIT_V(8); PG8_WAIT_L(0); PG8_BAR; PG8_MMA(1, 0, At, B0); PG8_MMA(1, 1, At, B1); PG8_BAR; PG8_SCHED;
.LBB0_177:
	s_add_u32 s36, s84, 0x80
	s_waitcnt lgkmcnt(0)
	s_addc_u32 s37, s85, 0
	s_add_u32 s66, s70, 0x80
	s_addc_u32 s67, s71, 0
	s_barrier
	s_setprio 1
	v_mfma_f32_16x16x32_bf16 v[122:125], v[146:149], v[186:189], v[122:125]
	v_mfma_f32_16x16x32_bf16 v[114:117], v[154:157], v[186:189], v[114:117]
	v_mfma_f32_16x16x32_bf16 v[106:109], v[146:149], v[178:181], v[106:109]
	v_mfma_f32_16x16x32_bf16 v[98:101], v[154:157], v[178:181], v[98:101]
	v_mfma_f32_16x16x32_bf16 v[90:93], v[146:149], v[170:173], v[90:93]
	v_mfma_f32_16x16x32_bf16 v[82:85], v[154:157], v[170:173], v[82:85]
	v_mfma_f32_16x16x32_bf16 v[62:65], v[146:149], v[162:165], v[62:65]
	v_mfma_f32_16x16x32_bf16 v[50:53], v[154:157], v[162:165], v[50:53]
	v_mfma_f32_16x16x32_bf16 v[122:125], v[150:153], v[190:193], v[122:125]
	v_mfma_f32_16x16x32_bf16 v[114:117], v[158:161], v[190:193], v[114:117]
	v_mfma_f32_16x16x32_bf16 v[106:109], v[150:153], v[182:185], v[106:109]
	v_mfma_f32_16x16x32_bf16 v[98:101], v[158:161], v[182:185], v[98:101]
	v_mfma_f32_16x16x32_bf16 v[90:93], v[150:153], v[174:177], v[90:93]
	v_mfma_f32_16x16x32_bf16 v[82:85], v[158:161], v[174:177], v[82:85]
	v_mfma_f32_16x16x32_bf16 v[62:65], v[150:153], v[166:169], v[62:65]
	v_mfma_f32_16x16x32_bf16 v[50:53], v[158:161], v[166:169], v[50:53]
	s_setprio 0
	s_setprio 1
	v_mfma_f32_16x16x32_bf16 v[126:129], v[130:133], v[186:189], v[126:129]
	v_mfma_f32_16x16x32_bf16 v[118:121], v[138:141], v[186:189], v[118:121]
	v_mfma_f32_16x16x32_bf16 v[110:113], v[130:133], v[178:181], v[110:113]
	v_mfma_f32_16x16x32_bf16 v[102:105], v[138:141], v[178:181], v[102:105]
	v_mfma_f32_16x16x32_bf16 v[94:97], v[130:133], v[170:173], v[94:97]
	v_mfma_f32_16x16x32_bf16 v[86:89], v[138:141], v[170:173], v[86:89]
	v_mfma_f32_16x16x32_bf16 v[70:73], v[130:133], v[162:165], v[70:73]
	v_mfma_f32_16x16x32_bf16 v[54:57], v[138:141], v[162:165], v[54:57]
	v_mfma_f32_16x16x32_bf16 v[126:129], v[134:137], v[190:193], v[126:129]
	v_mfma_f32_16x16x32_bf16 v[118:121], v[142:145], v[190:193], v[118:121]
	v_mfma_f32_16x16x32_bf16 v[110:113], v[134:137], v[182:185], v[110:113]
	v_mfma_f32_16x16x32_bf16 v[102:105], v[142:145], v[182:185], v[102:105]
	v_mfma_f32_16x16x32_bf16 v[94:97], v[134:137], v[174:177], v[94:97]
	v_mfma_f32_16x16x32_bf16 v[86:89], v[142:145], v[174:177], v[86:89]
	v_mfma_f32_16x16x32_bf16 v[70:73], v[134:137], v[166:169], v[70:73]
	v_mfma_f32_16x16x32_bf16 v[54:57], v[142:145], v[166:169], v[54:57]
	s_setprio 0
	s_barrier
	ds_read_b128 v[162:165], v244 offset:49152
	ds_read_b128 v[166:169], v244 offset:50176
	ds_read_b128 v[170:173], v244 offset:51200
	ds_read_b128 v[174:177], v244 offset:52224
	ds_read_b128 v[178:181], v244 offset:53248
	ds_read_b128 v[182:185], v244 offset:54272
	ds_read_b128 v[186:189], v244 offset:55296
	ds_read_b128 v[190:193], v244 offset:56320
	s_mov_b32 m0, s23
	s_nop 0
	global_load_lds_dwordx4 v230, s[66:67]
	s_add_u32 m0, m0, 0x2000
	s_nop 0
	global_load_lds_dwordx4 v232, s[66:67]
	s_add_u32 s66, s70, 0x40080
	s_addc_u32 s67, s71, 0
	s_mov_b32 m0, s25
	s_nop 0
	global_load_lds_dwordx4 v230, s[66:67]
	s_add_u32 m0, m0, 0x2000
	s_nop 0
	global_load_lds_dwordx4 v232, s[66:67]
	s_nop 0
	s_mov_b32 m0, s24
	s_nop 0
	global_load_lds_dwordx4 v0, s[36:37]
	s_add_u32 m0, m0, 0x2000
	s_nop 0
	global_load_lds_dwordx4 v231, s[36:37]
	s_waitcnt vmcnt(8)
	s_waitcnt lgkmcnt(0)
	s_barrier
	s_setprio 1
	v_mfma_f32_16x16x32_bf16 v[74:77], v[146:149], v[162:165], v[74:77]
	v_mfma_f32_16x16x32_bf16 v[58:61], v[154:157], v[162:165], v[58:61]
	v_mfma_f32_16x16x32_bf16 v[42:45], v[146:149], v[170:173], v[42:45]
	v_mfma_f32_16x16x32_bf16 v[34:37], v[154:157], v[170:173], v[34:37]
	v_mfma_f32_16x16x32_bf16 v[26:29], v[146:149], v[178:181], v[26:29]
	v_mfma_f32_16x16x32_bf16 v[18:21], v[154:157], v[178:181], v[18:21]
	v_mfma_f32_16x16x32_bf16 v[10:13], v[146:149], v[186:189], v[10:13]
	v_mfma_f32_16x16x32_bf16 v[2:5], v[154:157], v[186:189], v[2:5]
	v_mfma_f32_16x16x32_bf16 v[74:77], v[150:153], v[166:169], v[74:77]
	v_mfma_f32_16x16x32_bf16 v[58:61], v[158:161], v[166:169], v[58:61]
	v_mfma_f32_16x16x32_bf16 v[42:45], v[150:153], v[174:177], v[42:45]
	v_mfma_f32_16x16x32_bf16 v[34:37], v[158:161], v[174:177], v[34:37]
	v_mfma_f32_16x16x32_bf16 v[26:29], v[150:153], v[182:185], v[26:29]
	v_mfma_f32_16x16x32_bf16 v[18:21], v[158:161], v[182:185], v[18:21]
	v_mfma_f32_16x16x32_bf16 v[10:13], v[150:153], v[190:193], v[10:13]
	v_mfma_f32_16x16x32_bf16 v[2:5], v[158:161], v[190:193], v[2:5]
	s_setprio 0
	s_setprio 1
	v_mfma_f32_16x16x32_bf16 v[78:81], v[130:133], v[162:165], v[78:81]
	v_mfma_f32_16x16x32_bf16 v[66:69], v[138:141], v[162:165], v[66:69]
	v_mfma_f32_16x16x32_bf16 v[46:49], v[130:133], v[170:173], v[46:49]
	v_mfma_f32_16x16x32_bf16 v[38:41], v[138:141], v[170:173], v[38:41]
	v_mfma_f32_16x16x32_bf16 v[30:33], v[130:133], v[178:181], v[30:33]
	v_mfma_f32_16x16x32_bf16 v[22:25], v[138:141], v[178:181], v[22:25]
	v_mfma_f32_16x16x32_bf16 v[14:17], v[130:133], v[186:189], v[14:17]
	v_mfma_f32_16x16x32_bf16 v[6:9], v[138:141], v[186:189], v[6:9]
	v_mfma_f32_16x16x32_bf16 v[78:81], v[134:137], v[166:169], v[78:81]
	v_mfma_f32_16x16x32_bf16 v[66:69], v[142:145], v[166:169], v[66:69]
	v_mfma_f32_16x16x32_bf16 v[46:49], v[134:137], v[174:177], v[46:49]
	v_mfma_f32_16x16x32_bf16 v[38:41], v[142:145], v[174:177], v[38:41]
	v_mfma_f32_16x16x32_bf16 v[30:33], v[134:137], v[182:185], v[30:33]
	v_mfma_f32_16x16x32_bf16 v[22:25], v[142:145], v[182:185], v[22:25]
	v_mfma_f32_16x16x32_bf16 v[14:17], v[134:137], v[190:193], v[14:17]
	v_mfma_f32_16x16x32_bf16 v[6:9], v[142:145], v[190:193], v[6:9]
	s_setprio 0
	s_barrier
	s_add_i32 s64, s64, 2
	s_add_u32 s50, s50, 0x100
	s_addc_u32 s51, s51, 0
	s_add_u32 s52, s52, 0x100
	s_addc_u32 s53, s53, 0
	s_add_u32 s68, s68, 0x100
	s_addc_u32 s69, s69, 0
	s_cmp_gt_u32 s64, 13
	s_cbranch_scc1 .LBB0_184

; #define PG8_STAGE(bufoff, gbase, voff) glds16s2((voff)[0], (voff)[1], (const void*)(gbase), ldsn + (unsigned)(bufoff))
; #define PG8_LDA(dst, b, h) do { _Pragma("unroll") for (int m = 0; m < 4; ++m) _Pragma("unroll") for (int k = 0; k < 2; ++k) dst[m][k] = *(const LAS bf16x8*)(lds + PG8_SA(b, h) + aoff + m * 2048 + k * 1024); } while (0)
; #define PG8_LDB(dst, b, h) do { _Pragma("unroll") for (int n = 0; n < 2; ++n) _Pragma("unroll") for (int k = 0; k < 2; ++k) dst[n][k] = *(const LAS bf16x8*)(lds + PG8_SB(b, h) + boff + n * 2048 + k * 1024); } while (0)
; #define PG8_WAIT_V(n) asm volatile("s_waitcnt vmcnt(" #n ")" ::: "memory")
; #define PG8_WAIT_L(n) asm volatile("s_waitcnt lgkmcnt(" #n ")" ::: "memory")
; #define PG8_BAR __builtin_amdgcn_s_barrier()
; #define PG8_SCHED __builtin_amdgcn_sched_barrier(0)
; template <class Epi, bool ALIGN_EPI, bool EARLY_DRAIN = true, class Pre = NoPre>
; __device__ __forceinline__ void gemm_phase(LAS unsigned char* lds, const Gemm g, const StaticOrder& S, const Epi& E, int wv, const Pre& pre = Pre()) {
;     ...
;             const bool last = (t == nt - 2);
;             const char* a1 = cA + (size_t)(t + 1) * kstep;
;             const char* a2 = last ? nA : cA + (size_t)(t + 2) * kstep; const char* b2 = last ? nB : cB + (size_t)(t + 2) * kstep;
;             const char* a3 = a2 + kstep; const char* b3 = b2 + kstep;
;             int lf_ = EARLY_DRAIN ? __builtin_amdgcn_readfirstlane(landed_flag) : landed_flag; if constexpr (EARLY_DRAIN) asm volatile("" : "+s"(lf_)); landed_flag = 0;
;             PG8_LDB(B0, 0, 0); PG8_LDB(B1, 0, 1); PG8_SCHED; PG8_LDA(At, 0, 0); PG8_STAGE(PG8_SA(1, 1), a1 + ahs, voffA);
;             if (!lf_) PG8_WAIT_V(8);
;             PG8_WAIT_L(0); PG8_BAR; PG8_MMA(0, 0, At, B0); PG8_MMA(0, 1, At, B1); PG8_BAR; PG8_SCHED;
;             PG8_LDA(At, 0, 1); PG8_STAGE(PG8_SB(0, 0), b2, voffB); PG8_STAGE(PG8_SB(0, 1), b2 + bhs, voffB); PG8_STAGE(PG8_SA(0, 0), a2, voffA);
;             if (!lf_) PG8_WAIT_V(8);
;             PG8_WAIT_L(0); PG8_BAR; PG8_MMA(1, 0, At, B0); PG8_MMA(1, 1, At, B1); PG8_BAR; PG8_SCHED;
;             PG8_LDB(B0, 1, 0); PG8_LDB(B1, 1, 1); PG8_SCHED; PG8_LDA(At, 1, 0); PG8_STAGE(PG8_SA(0, 1), a2 + ahs, voffA);
;             if (!lf_) PG8_WAIT_V(8);
;             PG8_WAIT_L(0); PG8_BAR; PG8_MMA(0, 0, At, B0); PG8_MMA(0, 1, At, B1); PG8_BAR; PG8_SCHED;
.LBB0_180:
	s_waitcnt lgkmcnt(0)
	s_cmp_eq_u32 s64, 12
	s_cselect_b32 s85, s61, s51
	s_cselect_b32 s84, s60, s50
	s_cselect_b32 s71, s43, s53
	s_cselect_b32 s70, s47, s52
	s_barrier
	s_setprio 1
	v_mfma_f32_16x16x32_bf16 v[122:125], v[146:149], v[186:189], v[122:125]
	v_mfma_f32_16x16x32_bf16 v[114:117], v[154:157], v[186:189], v[114:117]
	v_mfma_f32_16x16x32_bf16 v[106:109], v[146:149], v[178:181], v[106:109]
	v_mfma_f32_16x16x32_bf16 v[98:101], v[154:157], v[178:181], v[98:101]
	v_mfma_f32_16x16x32_bf16 v[90:93], v[146:149], v[170:173], v[90:93]
	v_mfma_f32_16x16x32_bf16 v[82:85], v[154:157], v[170:173], v[82:85]
	v_mfma_f32_16x16x32_bf16 v[62:65], v[146:149], v[162:165], v[62:65]
	v_mfma_f32_16x16x32_bf16 v[50:53], v[154:157], v[162:165], v[50:53]
	v_mfma_f32_16x16x32_bf16 v[122:125], v[150:153], v[190:193], v[122:125]
	v_mfma_f32_16x16x32_bf16 v[114:117], v[158:161], v[190:193], v[114:117]
	v_mfma_f32_16x16x32_bf16 v[106:109], v[150:153], v[182:185], v[106:109]
	v_mfma_f32_16x16x32_bf16 v[98:101], v[158:161], v[182:185], v[98:101]
	v_mfma_f32_16x16x32_bf16 v[90:93], v[150:153], v[174:177], v[90:93]
	v_mfma_f32_16x16x32_bf16 v[82:85], v[158:161], v[174:177], v[82:85]
	v_mfma_f32_16x16x32_bf16 v[62:65], v[150:153], v[166:169], v[62:65]
	v_mfma_f32_16x16x32_bf16 v[50:53], v[158:161], v[166:169], v[50:53]
	s_setprio 0
	s_setprio 1
	v_mfma_f32_16x16x32_bf16 v[126:129], v[130:133], v[186:189], v[126:129]
	v_mfma_f32_16x16x32_bf16 v[118:121], v[138:141], v[186:189], v[118:121]
	v_mfma_f32_16x16x32_bf16 v[110:113], v[130:133], v[178:181], v[110:113]
	v_mfma_f32_16x16x32_bf16 v[102:105], v[138:141], v[178:181], v[102:105]
	v_mfma_f32_16x16x32_bf16 v[94:97], v[130:133], v[170:173], v[94:97]
	v_mfma_f32_16x16x32_bf16 v[86:89], v[138:141], v[170:173], v[86:89]
	v_mfma_f32_16x16x32_bf16 v[70:73], v[130:133], v[162:165], v[70:73]
	v_mfma_f32_16x16x32_bf16 v[54:57], v[138:141], v[162:165], v[54:57]
	v_mfma_f32_16x16x32_bf16 v[126:129], v[134:137], v[190:193], v[126:129]
	v_mfma_f32_16x16x32_bf16 v[118:121], v[142:145], v[190:193], v[118:121]
	v_mfma_f32_16x16x32_bf16 v[110:113], v[134:137], v[182:185], v[110:113]
	v_mfma_f32_16x16x32_bf16 v[102:105], v[142:145], v[182:185], v[102:105]
	v_mfma_f32_16x16x32_bf16 v[94:97], v[134:137], v[174:177], v[94:97]
	v_mfma_f32_16x16x32_bf16 v[86:89], v[142:145], v[174:177], v[86:89]
	v_mfma_f32_16x16x32_bf16 v[70:73], v[134:137], v[166:169], v[70:73]
	v_mfma_f32_16x16x32_bf16 v[54:57], v[142:145], v[166:169], v[54:57]
	s_setprio 0
	s_barrier
	ds_read_b128 v[186:189], v244 offset:16384
	ds_read_b128 v[190:193], v244 offset:17408
	ds_read_b128 v[178:181], v244 offset:18432
	ds_read_b128 v[182:185], v244 offset:19456
	ds_read_b128 v[170:173], v244 offset:20480
	ds_read_b128 v[174:177], v244 offset:21504
	ds_read_b128 v[162:165], v244 offset:22528
	ds_read_b128 v[166:169], v244 offset:23552
	s_mov_b32 m0, s10
	s_nop 0
	global_load_lds_dwordx4 v230, s[70:71]
	s_add_u32 m0, m0, 0x2000
	s_nop 0
	global_load_lds_dwordx4 v232, s[70:71]
	s_add_u32 s36, s70, 0x40000
	s_addc_u32 s37, s71, 0
	s_mov_b32 m0, s12
	s_nop 0
	global_load_lds_dwordx4 v230, s[36:37]
	s_add_u32 m0, m0, 0x2000
	s_nop 0
	global_load_lds_dwordx4 v232, s[36:37]
	s_mov_b32 m0, s5
	s_nop 0
	global_load_lds_dwordx4 v0, s[84:85]
	s_add_u32 m0, m0, 0x2000
	s_nop 0
	global_load_lds_dwordx4 v231, s[84:85]
	s_waitcnt vmcnt(8)
.LBB0_182:
	s_waitcnt lgkmcnt(0)
	s_barrier
	s_setprio 1
	v_mfma_f32_16x16x32_bf16 v[74:77], v[146:149], v[186:189], v[74:77]
	v_mfma_f32_16x16x32_bf16 v[58:61], v[154:157], v[186:189], v[58:61]
	v_mfma_f32_16x16x32_bf16 v[42:45], v[146:149], v[178:181], v[42:45]
	v_mfma_f32_16x16x32_bf16 v[34:37], v[154:157], v[178:181], v[34:37]
	v_mfma_f32_16x16x32_bf16 v[26:29], v[146:149], v[170:173], v[26:29]
	v_mfma_f32_16x16x32_bf16 v[18:21], v[154:157], v[170:173], v[18:21]
	v_mfma_f32_16x16x32_bf16 v[10:13], v[146:149], v[162:165], v[10:13]
	v_mfma_f32_16x16x32_bf16 v[2:5], v[154:157], v[162:165], v[2:5]
	v_mfma_f32_16x16x32_bf16 v[74:77], v[150:153], v[190:193], v[74:77]
	v_mfma_f32_16x16x32_bf16 v[58:61], v[158:161], v[190:193], v[58:61]
	v_mfma_f32_16x16x32_bf16 v[42:45], v[150:153], v[182:185], v[42:45]
	v_mfma_f32_16x16x32_bf16 v[34:37], v[158:161], v[182:185], v[34:37]
	v_mfma_f32_16x16x32_bf16 v[26:29], v[150:153], v[174:177], v[26:29]
	v_mfma_f32_16x16x32_bf16 v[18:21], v[158:161], v[174:177], v[18:21]
	v_mfma_f32_16x16x32_bf16 v[10:13], v[150:153], v[166:169], v[10:13]
	v_mfma_f32_16x16x32_bf16 v[2:5], v[158:161], v[166:169], v[2:5]
	s_setprio 0
	s_setprio 1
	v_mfma_f32_16x16x32_bf16 v[78:81], v[130:133], v[186:189], v[78:81]
	v_mfma_f32_16x16x32_bf16 v[66:69], v[138:141], v[186:189], v[66:69]
	v_mfma_f32_16x16x32_bf16 v[46:49], v[130:133], v[178:181], v[46:49]
	v_mfma_f32_16x16x32_bf16 v[38:41], v[138:141], v[178:181], v[38:41]
	v_mfma_f32_16x16x32_bf16 v[30:33], v[130:133], v[170:173], v[30:33]
	v_mfma_f32_16x16x32_bf16 v[22:25], v[138:141], v[170:173], v[22:25]
	v_mfma_f32_16x16x32_bf16 v[14:17], v[130:133], v[162:165], v[14:17]
	v_mfma_f32_16x16x32_bf16 v[6:9], v[138:141], v[162:165], v[6:9]
	v_mfma_f32_16x16x32_bf16 v[78:81], v[134:137], v[190:193], v[78:81]
	v_mfma_f32_16x16x32_bf16 v[66:69], v[142:145], v[190:193], v[66:69]
	v_mfma_f32_16x16x32_bf16 v[46:49], v[134:137], v[182:185], v[46:49]
	v_mfma_f32_16x16x32_bf16 v[38:41], v[142:145], v[182:185], v[38:41]
	v_mfma_f32_16x16x32_bf16 v[30:33], v[134:137], v[174:177], v[30:33]
	v_mfma_f32_16x16x32_bf16 v[22:25], v[142:145], v[174:177], v[22:25]
	v_mfma_f32_16x16x32_bf16 v[14:17], v[134:137], v[166:169], v[14:17]
	v_mfma_f32_16x16x32_bf16 v[6:9], v[142:145], v[166:169], v[6:9]
	s_setprio 0
	s_barrier
	ds_read_b128 v[146:149], v234
	ds_read_b128 v[150:153], v234 offset:1024
	ds_read_b128 v[154:157], v234 offset:2048
	ds_read_b128 v[158:161], v234 offset:3072
	ds_read_b128 v[130:133], v235
	ds_read_b128 v[134:137], v235 offset:1024
	ds_read_b128 v[138:141], v235 offset:2048
	ds_read_b128 v[142:145], v235 offset:3072
	ds_read_b128 v[186:189], v244 offset:32768
	ds_read_b128 v[190:193], v244 offset:33792
	ds_read_b128 v[178:181], v244 offset:34816
	ds_read_b128 v[182:185], v244 offset:35840
	ds_read_b128 v[170:173], v244 offset:36864
	ds_read_b128 v[174:177], v244 offset:37888
	ds_read_b128 v[162:165], v244 offset:38912
	ds_read_b128 v[166:169], v244 offset:39936
	s_add_u32 s66, s84, 0x40000
	s_addc_u32 s67, s85, 0
	s_mov_b32 m0, s13
	s_nop 0
	global_load_lds_dwordx4 v0, s[66:67]
	s_add_u32 m0, m0, 0x2000
	s_nop 0
	global_load_lds_dwordx4 v231, s[66:67]
	s_waitcnt vmcnt(8)
	s_branch .LBB0_177
	s_nop 0
	s_nop 0
	s_nop 0
	s_nop 0
	s_nop 0
	s_nop 0
	s_nop 0
	s_nop 0
	s_nop 0
	s_nop 0
	s_nop 0
	s_nop 0
	s_nop 0

; #define PG8_STAGE(bufoff, gbase, voff) glds16s2((voff)[0], (voff)[1], (const void*)(gbase), ldsn + (unsigned)(bufoff))
; #define PG8_LDA(dst, b, h) do { _Pragma("unroll") for (int m = 0; m < 4; ++m) _Pragma("unroll") for (int k = 0; k < 2; ++k) dst[m][k] = *(const LAS bf16x8*)(lds + PG8_SA(b, h) + aoff + m * 2048 + k * 1024); } while (0)
; #define PG8_LDB(dst, b, h) do { _Pragma("unroll") for (int n = 0; n < 2; ++n) _Pragma("unroll") for (int k = 0; k < 2; ++k) dst[n][k] = *(const LAS bf16x8*)(lds + PG8_SB(b, h) + boff + n * 2048 + k * 1024); } while (0)
; #define PG8_MMA(ai, bj, At, Bt) do { __builtin_amdgcn_s_setprio(1); _Pragma("unroll") for (int m = 0; m < 4; ++m) _Pragma("unroll") for (int n = 0; n < 2; ++n) _Pragma("unroll") for (int k = 0; k < 2; ++k) \
;         acc[ai][bj][m][n] = __builtin_amdgcn_mfma_f32_16x16x32_bf16(Bt[n][k], At[m][k], acc[ai][bj][m][n], 0, 0, 0); __builtin_amdgcn_s_setprio(0); } while (0)
; #define PG8_WAIT_V(n) asm volatile("s_waitcnt vmcnt(" #n ")" ::: "memory")
; template <class Epi, bool ALIGN_EPI, bool EARLY_DRAIN = true, class Pre = NoPre>
; __device__ __forceinline__ void gemm_phase(LAS unsigned char* lds, const Gemm g, const StaticOrder& S, const Epi& E, int wv, const Pre& pre = Pre()) {
;     ...
;         for (int t = th; t < th + (Epi::MIDK ? nt / 2 : nt); t += 2) {
;             const bool last = (t == nt - 2);
;             const char* a1 = cA + (size_t)(t + 1) * kstep;
;             const char* a2 = last ? nA : cA + (size_t)(t + 2) * kstep; const char* b2 = last ? nB : cB + (size_t)(t + 2) * kstep;
;             const char* a3 = a2 + kstep; const char* b3 = b2 + kstep;
;             int lf_ = EARLY_DRAIN ? __builtin_amdgcn_readfirstlane(landed_flag) : landed_flag; if constexpr (EARLY_DRAIN) asm volatile("" : "+s"(lf_)); landed_flag = 0;
;             PG8_LDB(B0, 0, 0); PG8_LDB(B1, 0, 1); PG8_SCHED; PG8_LDA(At, 0, 0); PG8_STAGE(PG8_SA(1, 1), a1 + ahs, voffA);
;             if (!lf_) PG8_WAIT_V(8);
;             PG8_WAIT_L(0); PG8_BAR; PG8_MMA(0, 0, At, B0); PG8_MMA(0, 1, At, B1); PG8_BAR; PG8_SCHED;
;             PG8_LDA(At, 0, 1); PG8_STAGE(PG8_SB(0, 0), b2, voffB); PG8_STAGE(PG8_SB(0, 1), b2 + bhs, voffB); PG8_STAGE(PG8_SA(0, 0), a2, voffA);
;             if (!lf_) PG8_WAIT_V(8);
;             PG8_WAIT_L(0); PG8_BAR; PG8_MMA(1, 0, At, B0); PG8_MMA(1, 1, At, B1); PG8_BAR; PG8_SCHED;
.LBB0_442:
	v_add_u32_e32 v0, 0x10000, v203
	ds_read_b128 v[166:169], v0
	ds_read_b128 v[170:173], v0 offset:1024
	ds_read_b128 v[174:177], v0 offset:2048
	ds_read_b128 v[178:181], v0 offset:3072
	v_add_u32_e32 v0, 0x14000, v203
	ds_read_b128 v[182:185], v0
	ds_read_b128 v[186:189], v0 offset:1024
	ds_read_b128 v[190:193], v0 offset:2048
	ds_read_b128 v[194:197], v0 offset:3072
	s_add_i32 s91, s20, 2
	s_cmp_eq_u32 s20, 14
	s_cselect_b32 s86, s45, vcc_lo
	s_cselect_b32 s87, s37, vcc_hi
	s_cselect_b32 s84, s67, s76
	s_cselect_b32 s85, s65, s77
	s_add_u32 s70, s86, 0x80
	s_addc_u32 s71, s87, 0
	ds_read_b128 v[206:209], v204
	ds_read_b128 v[210:213], v204 offset:1024
	ds_read_b128 v[214:217], v204 offset:2048
	ds_read_b128 v[218:221], v204 offset:3072
	ds_read_b128 v[222:225], v204 offset:4096
	ds_read_b128 v[226:229], v204 offset:5120
	ds_read_b128 v[230:233], v204 offset:6144
	ds_read_b128 v[234:237], v204 offset:7168
	s_mov_b32 m0, s26
	s_nop 0
	global_load_lds_dwordx4 v198, s[68:69]
	s_add_u32 m0, m0, 0x2000
	s_nop 0
	global_load_lds_dwordx4 v200, s[68:69]
	s_waitcnt vmcnt(8)
	s_waitcnt lgkmcnt(0)
	s_barrier
	s_setprio 1
	v_mfma_f32_16x16x32_bf16 v[160:163], v[166:169], v[206:209], v[160:163]
	v_mfma_f32_16x16x32_bf16 v[156:159], v[174:177], v[206:209], v[156:159]
	v_mfma_f32_16x16x32_bf16 v[144:147], v[166:169], v[214:217], v[144:147]
	v_mfma_f32_16x16x32_bf16 v[140:143], v[174:177], v[214:217], v[140:143]
	v_mfma_f32_16x16x32_bf16 v[124:127], v[166:169], v[222:225], v[124:127]
	v_mfma_f32_16x16x32_bf16 v[116:119], v[174:177], v[222:225], v[116:119]
	v_mfma_f32_16x16x32_bf16 v[96:99], v[166:169], v[230:233], v[96:99]
	v_mfma_f32_16x16x32_bf16 v[92:95], v[174:177], v[230:233], v[92:95]
	v_mfma_f32_16x16x32_bf16 v[160:163], v[170:173], v[210:213], v[160:163]
	v_mfma_f32_16x16x32_bf16 v[156:159], v[178:181], v[210:213], v[156:159]
	v_mfma_f32_16x16x32_bf16 v[144:147], v[170:173], v[218:221], v[144:147]
	v_mfma_f32_16x16x32_bf16 v[140:143], v[178:181], v[218:221], v[140:143]
	v_mfma_f32_16x16x32_bf16 v[124:127], v[170:173], v[226:229], v[124:127]
	v_mfma_f32_16x16x32_bf16 v[116:119], v[178:181], v[226:229], v[116:119]
	v_mfma_f32_16x16x32_bf16 v[96:99], v[170:173], v[234:237], v[96:99]
	v_mfma_f32_16x16x32_bf16 v[92:95], v[178:181], v[234:237], v[92:95]
	s_setprio 0
	s_setprio 1
	v_mfma_f32_16x16x32_bf16 v[152:155], v[182:185], v[206:209], v[152:155]
	v_mfma_f32_16x16x32_bf16 v[148:151], v[190:193], v[206:209], v[148:151]
	v_mfma_f32_16x16x32_bf16 v[136:139], v[182:185], v[214:217], v[136:139]
	v_mfma_f32_16x16x32_bf16 v[132:135], v[190:193], v[214:217], v[132:135]
	v_mfma_f32_16x16x32_bf16 v[112:115], v[182:185], v[222:225], v[112:115]
	v_mfma_f32_16x16x32_bf16 v[108:111], v[190:193], v[222:225], v[108:111]
	v_mfma_f32_16x16x32_bf16 v[88:91], v[182:185], v[230:233], v[88:91]
	v_mfma_f32_16x16x32_bf16 v[80:83], v[190:193], v[230:233], v[80:83]
	v_mfma_f32_16x16x32_bf16 v[152:155], v[186:189], v[210:213], v[152:155]
	v_mfma_f32_16x16x32_bf16 v[148:151], v[194:197], v[210:213], v[148:151]
	v_mfma_f32_16x16x32_bf16 v[136:139], v[186:189], v[218:221], v[136:139]
	v_mfma_f32_16x16x32_bf16 v[132:135], v[194:197], v[218:221], v[132:135]
	v_mfma_f32_16x16x32_bf16 v[112:115], v[186:189], v[226:229], v[112:115]
	v_mfma_f32_16x16x32_bf16 v[108:111], v[194:197], v[226:229], v[108:111]
	v_mfma_f32_16x16x32_bf16 v[88:91], v[186:189], v[234:237], v[88:91]
	v_mfma_f32_16x16x32_bf16 v[80:83], v[194:197], v[234:237], v[80:83]
	s_setprio 0
	s_barrier
	ds_read_b128 v[206:209], v204 offset:16384
	ds_read_b128 v[210:213], v204 offset:17408
	ds_read_b128 v[214:217], v204 offset:18432
	ds_read_b128 v[218:221], v204 offset:19456
	ds_read_b128 v[222:225], v204 offset:20480
	ds_read_b128 v[226:229], v204 offset:21504
	ds_read_b128 v[230:233], v204 offset:22528
	ds_read_b128 v[234:237], v204 offset:23552
	s_mov_b32 m0, s10
	s_nop 0
	global_load_lds_dwordx4 v199, s[84:85]
	s_add_u32 m0, m0, 0x2000
	s_nop 0
	global_load_lds_dwordx4 v201, s[84:85]
	s_add_u32 s14, s84, 0x40000
	s_addc_u32 s15, s85, 0
	s_mov_b32 m0, s12
	s_nop 0
	global_load_lds_dwordx4 v199, s[14:15]
	s_add_u32 m0, m0, 0x2000
	s_nop 0
	global_load_lds_dwordx4 v201, s[14:15]
	s_nop 0
	s_mov_b32 m0, s89
	s_nop 0
	global_load_lds_dwordx4 v198, s[86:87]
	s_add_u32 m0, m0, 0x2000
	s_nop 0
	global_load_lds_dwordx4 v200, s[86:87]
	s_waitcnt vmcnt(8)
	s_waitcnt lgkmcnt(0)
	s_barrier
	s_setprio 1
	v_mfma_f32_16x16x32_bf16 v[72:75], v[166:169], v[206:209], v[72:75]
	v_mfma_f32_16x16x32_bf16 v[68:71], v[174:177], v[206:209], v[68:71]
	v_mfma_f32_16x16x32_bf16 v[48:51], v[166:169], v[214:217], v[48:51]
	v_mfma_f32_16x16x32_bf16 v[44:47], v[174:177], v[214:217], v[44:47]
	v_mfma_f32_16x16x32_bf16 v[32:35], v[166:169], v[222:225], v[32:35]
	v_mfma_f32_16x16x32_bf16 v[28:31], v[174:177], v[222:225], v[28:31]
	v_mfma_f32_16x16x32_bf16 v[16:19], v[166:169], v[230:233], v[16:19]
	v_mfma_f32_16x16x32_bf16 v[12:15], v[174:177], v[230:233], v[12:15]
	v_mfma_f32_16x16x32_bf16 v[72:75], v[170:173], v[210:213], v[72:75]
	v_mfma_f32_16x16x32_bf16 v[68:71], v[178:181], v[210:213], v[68:71]
	v_mfma_f32_16x16x32_bf16 v[48:51], v[170:173], v[218:221], v[48:51]
	v_mfma_f32_16x16x32_bf16 v[44:47], v[178:181], v[218:221], v[44:47]
	v_mfma_f32_16x16x32_bf16 v[32:35], v[170:173], v[226:229], v[32:35]
	v_mfma_f32_16x16x32_bf16 v[28:31], v[178:181], v[226:229], v[28:31]
	v_mfma_f32_16x16x32_bf16 v[16:19], v[170:173], v[234:237], v[16:19]
	v_mfma_f32_16x16x32_bf16 v[12:15], v[178:181], v[234:237], v[12:15]
	s_setprio 0
	s_setprio 1
	v_mfma_f32_16x16x32_bf16 v[60:63], v[182:185], v[206:209], v[60:63]
	v_mfma_f32_16x16x32_bf16 v[56:59], v[190:193], v[206:209], v[56:59]
	v_mfma_f32_16x16x32_bf16 v[40:43], v[182:185], v[214:217], v[40:43]
	v_mfma_f32_16x16x32_bf16 v[36:39], v[190:193], v[214:217], v[36:39]
	v_mfma_f32_16x16x32_bf16 v[24:27], v[182:185], v[222:225], v[24:27]
	v_mfma_f32_16x16x32_bf16 v[20:23], v[190:193], v[222:225], v[20:23]
	v_mfma_f32_16x16x32_bf16 v[8:11], v[182:185], v[230:233], v[8:11]
	v_mfma_f32_16x16x32_bf16 v[2:5], v[190:193], v[230:233], v[4:7]
	v_mfma_f32_16x16x32_bf16 v[60:63], v[186:189], v[210:213], v[60:63]
	v_mfma_f32_16x16x32_bf16 v[56:59], v[194:197], v[210:213], v[56:59]
	v_mfma_f32_16x16x32_bf16 v[40:43], v[186:189], v[218:221], v[40:43]
	v_mfma_f32_16x16x32_bf16 v[36:39], v[194:197], v[218:221], v[36:39]
	v_mfma_f32_16x16x32_bf16 v[24:27], v[186:189], v[226:229], v[24:27]
	v_mfma_f32_16x16x32_bf16 v[20:23], v[194:197], v[226:229], v[20:23]
	v_mfma_f32_16x16x32_bf16 v[8:11], v[186:189], v[234:237], v[8:11]
	v_mfma_f32_16x16x32_bf16 v[2:5], v[194:197], v[234:237], v[2:5]
	s_setprio 0
	s_barrier
; #define PG8_STAGE(bufoff, gbase, voff) glds16s2((voff)[0], (voff)[1], (const void*)(gbase), ldsn + (unsigned)(bufoff))
; #define PG8_LDA(dst, b, h) do { _Pragma("unroll") for (int m = 0; m < 4; ++m) _Pragma("unroll") for (int k = 0; k < 2; ++k) dst[m][k] = *(const LAS bf16x8*)(lds + PG8_SA(b, h) + aoff + m * 2048 + k * 1024); } while (0)
; #define PG8_LDB(dst, b, h) do { _Pragma("unroll") for (int n = 0; n < 2; ++n) _Pragma("unroll") for (int k = 0; k < 2; ++k) dst[n][k] = *(const LAS bf16x8*)(lds + PG8_SB(b, h) + boff + n * 2048 + k * 1024); } while (0)
; #define PG8_MMA(ai, bj, At, Bt) do { __builtin_amdgcn_s_setprio(1); _Pragma("unroll") for (int m = 0; m < 4; ++m) _Pragma("unroll") for (int n = 0; n < 2; ++n) _Pragma("unroll") for (int k = 0; k < 2; ++k) \
;         acc[ai][bj][m][n] = __builtin_amdgcn_mfma_f32_16x16x32_bf16(Bt[n][k], At[m][k], acc[ai][bj][m][n], 0, 0, 0); __builtin_amdgcn_s_setprio(0); } while (0)
; #define PG8_WAIT_V(n) asm volatile("s_waitcnt vmcnt(" #n ")" ::: "memory")
; #define PG8_WAIT_L(n) asm volatile("s_waitcnt lgkmcnt(" #n ")" ::: "memory")
; #define PG8_BAR __builtin_amdgcn_s_barrier()
; #define PG8_SCHED __builtin_amdgcn_sched_barrier(0)
; template <class Epi, bool ALIGN_EPI, bool EARLY_DRAIN = true, class Pre = NoPre>
; __device__ __forceinline__ void gemm_phase(LAS unsigned char* lds, const Gemm g, const StaticOrder& S, const Epi& E, int wv, const Pre& pre = Pre()) {
;     ...
;             PG8_LDB(B0, 1, 0); PG8_LDB(B1, 1, 1); PG8_SCHED; PG8_LDA(At, 1, 0); PG8_STAGE(PG8_SA(0, 1), a2 + ahs, voffA);
;             if (!lf_) PG8_WAIT_V(8);
;             PG8_WAIT_L(0); PG8_BAR; PG8_MMA(0, 0, At, B0); PG8_MMA(0, 1, At, B1); PG8_BAR; PG8_SCHED;
;             PG8_LDA(At, 1, 1); PG8_STAGE(PG8_SB(1, 0), b3, voffB); PG8_STAGE(PG8_SB(1, 1), b3 + bhs, voffB); PG8_STAGE(PG8_SA(1, 0), a3, voffA);
;             PG8_WAIT_V(8); PG8_WAIT_L(0); PG8_BAR; PG8_MMA(1, 0, At, B0); PG8_MMA(1, 1, At, B1); PG8_BAR; PG8_SCHED;
;         }
;         }
;         if constexpr (ALIGN_EPI) { if (wr == 0) PG8_BAR; }
	v_add_u32_e32 v0, 0x18000, v203
	ds_read_b128 v[166:169], v0
	ds_read_b128 v[170:173], v0 offset:1024
	ds_read_b128 v[174:177], v0 offset:2048
	ds_read_b128 v[178:181], v0 offset:3072
	v_add_u32_e32 v0, 0x1c000, v203
	ds_read_b128 v[182:185], v0
	ds_read_b128 v[186:189], v0 offset:1024
	ds_read_b128 v[190:193], v0 offset:2048
	ds_read_b128 v[194:197], v0 offset:3072
	ds_read_b128 v[206:209], v204 offset:32768
	ds_read_b128 v[210:213], v204 offset:33792
	ds_read_b128 v[214:217], v204 offset:34816
	ds_read_b128 v[218:221], v204 offset:35840
	ds_read_b128 v[222:225], v204 offset:36864
	ds_read_b128 v[226:229], v204 offset:37888
	ds_read_b128 v[230:233], v204 offset:38912
	ds_read_b128 v[234:237], v204 offset:39936
	s_add_u32 s14, s86, 0x40000
	s_addc_u32 s15, s87, 0
	s_mov_b32 m0, s13
	s_nop 0
	global_load_lds_dwordx4 v198, s[14:15]
	s_add_u32 m0, m0, 0x2000
	s_nop 0
	global_load_lds_dwordx4 v200, s[14:15]
	s_waitcnt vmcnt(8)
	s_waitcnt lgkmcnt(0)
	s_barrier
	s_setprio 1
	v_mfma_f32_16x16x32_bf16 v[160:163], v[166:169], v[206:209], v[160:163]
	v_mfma_f32_16x16x32_bf16 v[156:159], v[174:177], v[206:209], v[156:159]
	v_mfma_f32_16x16x32_bf16 v[144:147], v[166:169], v[214:217], v[144:147]
	v_mfma_f32_16x16x32_bf16 v[140:143], v[174:177], v[214:217], v[140:143]
	v_mfma_f32_16x16x32_bf16 v[124:127], v[166:169], v[222:225], v[124:127]
	v_mfma_f32_16x16x32_bf16 v[116:119], v[174:177], v[222:225], v[116:119]
	v_mfma_f32_16x16x32_bf16 v[96:99], v[166:169], v[230:233], v[96:99]
	v_mfma_f32_16x16x32_bf16 v[92:95], v[174:177], v[230:233], v[92:95]
	v_mfma_f32_16x16x32_bf16 v[160:163], v[170:173], v[210:213], v[160:163]
	v_mfma_f32_16x16x32_bf16 v[156:159], v[178:181], v[210:213], v[156:159]
	v_mfma_f32_16x16x32_bf16 v[144:147], v[170:173], v[218:221], v[144:147]
	v_mfma_f32_16x16x32_bf16 v[140:143], v[178:181], v[218:221], v[140:143]
	v_mfma_f32_16x16x32_bf16 v[124:127], v[170:173], v[226:229], v[124:127]
	v_mfma_f32_16x16x32_bf16 v[116:119], v[178:181], v[226:229], v[116:119]
	v_mfma_f32_16x16x32_bf16 v[96:99], v[170:173], v[234:237], v[96:99]
	v_mfma_f32_16x16x32_bf16 v[92:95], v[178:181], v[234:237], v[92:95]
	s_setprio 0
	s_setprio 1
	v_mfma_f32_16x16x32_bf16 v[152:155], v[182:185], v[206:209], v[152:155]
	v_mfma_f32_16x16x32_bf16 v[148:151], v[190:193], v[206:209], v[148:151]
	v_mfma_f32_16x16x32_bf16 v[136:139], v[182:185], v[214:217], v[136:139]
	v_mfma_f32_16x16x32_bf16 v[132:135], v[190:193], v[214:217], v[132:135]
	v_mfma_f32_16x16x32_bf16 v[112:115], v[182:185], v[222:225], v[112:115]
	v_mfma_f32_16x16x32_bf16 v[108:111], v[190:193], v[222:225], v[108:111]
	v_mfma_f32_16x16x32_bf16 v[88:91], v[182:185], v[230:233], v[88:91]
	v_mfma_f32_16x16x32_bf16 v[80:83], v[190:193], v[230:233], v[80:83]
	v_mfma_f32_16x16x32_bf16 v[152:155], v[186:189], v[210:213], v[152:155]
	v_mfma_f32_16x16x32_bf16 v[148:151], v[194:197], v[210:213], v[148:151]
	v_mfma_f32_16x16x32_bf16 v[136:139], v[186:189], v[218:221], v[136:139]
	v_mfma_f32_16x16x32_bf16 v[132:135], v[194:197], v[218:221], v[132:135]
	v_mfma_f32_16x16x32_bf16 v[112:115], v[186:189], v[226:229], v[112:115]
	v_mfma_f32_16x16x32_bf16 v[108:111], v[194:197], v[226:229], v[108:111]
	v_mfma_f32_16x16x32_bf16 v[88:91], v[186:189], v[234:237], v[88:91]
	v_mfma_f32_16x16x32_bf16 v[80:83], v[194:197], v[234:237], v[80:83]
	s_setprio 0
	s_barrier
	ds_read_b128 v[206:209], v204 offset:49152
	ds_read_b128 v[210:213], v204 offset:50176
	ds_read_b128 v[214:217], v204 offset:51200
	ds_read_b128 v[218:221], v204 offset:52224
	ds_read_b128 v[222:225], v204 offset:53248
	ds_read_b128 v[226:229], v204 offset:54272
	ds_read_b128 v[230:233], v204 offset:55296
	ds_read_b128 v[234:237], v204 offset:56320
	s_add_u32 s14, s84, 0x80
	s_addc_u32 s15, s85, 0
	s_mov_b32 m0, s23
	s_nop 0
	global_load_lds_dwordx4 v199, s[14:15]
	s_add_u32 m0, m0, 0x2000
	s_nop 0
	global_load_lds_dwordx4 v201, s[14:15]
	s_add_u32 s14, s84, 0x40080
	s_addc_u32 s15, s85, 0
	s_mov_b32 m0, s25
	s_nop 0
	global_load_lds_dwordx4 v199, s[14:15]
	s_add_u32 m0, m0, 0x2000
	s_nop 0
	global_load_lds_dwordx4 v201, s[14:15]
	s_nop 0
	s_mov_b32 m0, s24
	s_nop 0
	global_load_lds_dwordx4 v198, s[70:71]
	s_add_u32 m0, m0, 0x2000
	s_nop 0
	global_load_lds_dwordx4 v200, s[70:71]
	s_waitcnt vmcnt(8)
	s_waitcnt lgkmcnt(0)
	s_barrier
	s_setprio 1
	v_mfma_f32_16x16x32_bf16 v[72:75], v[166:169], v[206:209], v[72:75]
	v_mfma_f32_16x16x32_bf16 v[68:71], v[174:177], v[206:209], v[68:71]
	v_mfma_f32_16x16x32_bf16 v[48:51], v[166:169], v[214:217], v[48:51]
	v_mfma_f32_16x16x32_bf16 v[44:47], v[174:177], v[214:217], v[44:47]
	v_mfma_f32_16x16x32_bf16 v[32:35], v[166:169], v[222:225], v[32:35]
	v_mfma_f32_16x16x32_bf16 v[28:31], v[174:177], v[222:225], v[28:31]
	v_mfma_f32_16x16x32_bf16 v[16:19], v[166:169], v[230:233], v[16:19]
	v_mfma_f32_16x16x32_bf16 v[12:15], v[174:177], v[230:233], v[12:15]
	v_mfma_f32_16x16x32_bf16 v[72:75], v[170:173], v[210:213], v[72:75]
	v_mfma_f32_16x16x32_bf16 v[68:71], v[178:181], v[210:213], v[68:71]
	v_mfma_f32_16x16x32_bf16 v[48:51], v[170:173], v[218:221], v[48:51]
	v_mfma_f32_16x16x32_bf16 v[44:47], v[178:181], v[218:221], v[44:47]
	v_mfma_f32_16x16x32_bf16 v[32:35], v[170:173], v[226:229], v[32:35]
	v_mfma_f32_16x16x32_bf16 v[28:31], v[178:181], v[226:229], v[28:31]
	v_mfma_f32_16x16x32_bf16 v[16:19], v[170:173], v[234:237], v[16:19]
	v_mfma_f32_16x16x32_bf16 v[12:15], v[178:181], v[234:237], v[12:15]
	s_setprio 0
	s_setprio 1
	v_mfma_f32_16x16x32_bf16 v[60:63], v[182:185], v[206:209], v[60:63]
	v_mfma_f32_16x16x32_bf16 v[56:59], v[190:193], v[206:209], v[56:59]
	v_mfma_f32_16x16x32_bf16 v[40:43], v[182:185], v[214:217], v[40:43]
	v_mfma_f32_16x16x32_bf16 v[36:39], v[190:193], v[214:217], v[36:39]
	v_mfma_f32_16x16x32_bf16 v[24:27], v[182:185], v[222:225], v[24:27]
	v_mfma_f32_16x16x32_bf16 v[20:23], v[190:193], v[222:225], v[20:23]
	v_mfma_f32_16x16x32_bf16 v[6:9], v[182:185], v[230:233], v[8:11]
	v_mfma_f32_16x16x32_bf16 v[2:5], v[190:193], v[230:233], v[2:5]
	v_mfma_f32_16x16x32_bf16 v[60:63], v[186:189], v[210:213], v[60:63]
	v_mfma_f32_16x16x32_bf16 v[56:59], v[194:197], v[210:213], v[56:59]
	v_mfma_f32_16x16x32_bf16 v[40:43], v[186:189], v[218:221], v[40:43]
	v_mfma_f32_16x16x32_bf16 v[36:39], v[194:197], v[218:221], v[36:39]
	v_mfma_f32_16x16x32_bf16 v[24:27], v[186:189], v[226:229], v[24:27]
	v_mfma_f32_16x16x32_bf16 v[20:23], v[194:197], v[226:229], v[20:23]
	v_mfma_f32_16x16x32_bf16 v[8:11], v[186:189], v[234:237], v[6:9]
	v_mfma_f32_16x16x32_bf16 v[4:7], v[194:197], v[234:237], v[2:5]
	s_setprio 0
	s_barrier
	s_add_u32 s68, s68, 0x100
	s_addc_u32 s69, s69, 0
	s_add_u32 vcc_lo, vcc_lo, 0x100
	s_addc_u32 vcc_hi, vcc_hi, 0
	s_add_u32 s76, s76, 0x100
	s_addc_u32 s77, s77, 0
	s_cmp_ge_u32 s91, s0
	s_mov_b32 s20, s91
	s_cbranch_scc0 .LBB0_442
	s_mov_b32 s20, 8
	s_andn2_b64 vcc, exec, s[60:61]
	s_mov_b64 s[60:61], 0
	s_cbranch_vccnz .LBB0_439
	s_and_b64 vcc, exec, s[18:19]
	s_cbranch_vccz .LBB0_446
	s_barrier

; #define PG8_STAGE(bufoff, gbase, voff) glds16s2((voff)[0], (voff)[1], (const void*)(gbase), ldsn + (unsigned)(bufoff))
; #define PG8_LDA(dst, b, h) do { _Pragma("unroll") for (int m = 0; m < 4; ++m) _Pragma("unroll") for (int k = 0; k < 2; ++k) dst[m][k] = *(const LAS bf16x8*)(lds + PG8_SA(b, h) + aoff + m * 2048 + k * 1024); } while (0)
; #define PG8_LDB(dst, b, h) do { _Pragma("unroll") for (int n = 0; n < 2; ++n) _Pragma("unroll") for (int k = 0; k < 2; ++k) dst[n][k] = *(const LAS bf16x8*)(lds + PG8_SB(b, h) + boff + n * 2048 + k * 1024); } while (0)
; #define PG8_MMA(ai, bj, At, Bt) do { __builtin_amdgcn_s_setprio(1); _Pragma("unroll") for (int m = 0; m < 4; ++m) _Pragma("unroll") for (int n = 0; n < 2; ++n) _Pragma("unroll") for (int k = 0; k < 2; ++k) \
;         acc[ai][bj][m][n] = __builtin_amdgcn_mfma_f32_16x16x32_bf16(Bt[n][k], At[m][k], acc[ai][bj][m][n], 0, 0, 0); __builtin_amdgcn_s_setprio(0); } while (0)
; #define PG8_BAR __builtin_amdgcn_s_barrier()
; template <class Epi, bool ALIGN_EPI, bool EARLY_DRAIN = true, class Pre = NoPre>
; __device__ __forceinline__ void gemm_phase(LAS unsigned char* lds, const Gemm g, const StaticOrder& S, const Epi& E, int wv, const Pre& pre = Pre()) {
;     ...
;             const bool last = (t == nt - 2);
;             const char* a1 = cA + (size_t)(t + 1) * kstep;
;             const char* a2 = last ? nA : cA + (size_t)(t + 2) * kstep; const char* b2 = last ? nB : cB + (size_t)(t + 2) * kstep;
;             const char* a3 = a2 + kstep; const char* b3 = b2 + kstep;
;             int lf_ = EARLY_DRAIN ? __builtin_amdgcn_readfirstlane(landed_flag) : landed_flag; if constexpr (EARLY_DRAIN) asm volatile("" : "+s"(lf_)); landed_flag = 0;
;             PG8_LDB(B0, 0, 0); PG8_LDB(B1, 0, 1); PG8_SCHED; PG8_LDA(At, 0, 0); PG8_STAGE(PG8_SA(1, 1), a1 + ahs, voffA);
;             if (!lf_) PG8_WAIT_V(8);
;             PG8_WAIT_L(0); PG8_BAR; PG8_MMA(0, 0, At, B0); PG8_MMA(0, 1, At, B1); PG8_BAR; PG8_SCHED;
;             PG8_LDA(At, 0, 1); PG8_STAGE(PG8_SB(0, 0), b2, voffB); PG8_STAGE(PG8_SB(0, 1), b2 + bhs, voffB); PG8_STAGE(PG8_SA(0, 0), a2, voffA);
;             if (!lf_) PG8_WAIT_V(8);
;             PG8_WAIT_L(0); PG8_BAR; PG8_MMA(1, 0, At, B0); PG8_MMA(1, 1, At, B1); PG8_BAR; PG8_SCHED;
;             PG8_LDB(B0, 1, 0); PG8_LDB(B1, 1, 1); PG8_SCHED; PG8_LDA(At, 1, 0); PG8_STAGE(PG8_SA(0, 1), a2 + ahs, voffA);
.LBB0_553:
	s_add_u32 s14, s86, 0x100
	s_addc_u32 s15, s87, 0
	s_waitcnt lgkmcnt(0)
	s_add_u32 s42, s84, 0x100
	s_addc_u32 s43, s85, 0
	s_barrier
	s_setprio 1
	v_mfma_f32_16x16x32_bf16 v[2:5], v[74:77], v[38:41], 0
	v_mfma_f32_16x16x32_bf16 v[6:9], v[86:89], v[38:41], 0
	v_mfma_f32_16x16x32_bf16 v[10:13], v[74:77], v[46:49], 0
	v_mfma_f32_16x16x32_bf16 v[14:17], v[86:89], v[46:49], 0
	v_mfma_f32_16x16x32_bf16 v[18:21], v[74:77], v[62:65], 0
	v_mfma_f32_16x16x32_bf16 v[22:25], v[86:89], v[62:65], 0
	v_mfma_f32_16x16x32_bf16 v[26:29], v[74:77], v[90:93], 0
	v_mfma_f32_16x16x32_bf16 v[30:33], v[86:89], v[90:93], 0
	v_mfma_f32_16x16x32_bf16 v[2:5], v[82:85], v[42:45], v[2:5]
	v_mfma_f32_16x16x32_bf16 v[6:9], v[96:99], v[42:45], v[6:9]
	v_mfma_f32_16x16x32_bf16 v[10:13], v[82:85], v[58:61], v[10:13]
	v_mfma_f32_16x16x32_bf16 v[14:17], v[96:99], v[58:61], v[14:17]
	v_mfma_f32_16x16x32_bf16 v[18:21], v[82:85], v[78:81], v[18:21]
	v_mfma_f32_16x16x32_bf16 v[22:25], v[96:99], v[78:81], v[22:25]
	v_mfma_f32_16x16x32_bf16 v[26:29], v[82:85], v[100:103], v[26:29]
	v_mfma_f32_16x16x32_bf16 v[30:33], v[96:99], v[100:103], v[30:33]
	s_setprio 0
	s_setprio 1
	v_mfma_f32_16x16x32_bf16 v[34:37], v[50:53], v[38:41], 0
	v_mfma_f32_16x16x32_bf16 v[38:41], v[66:69], v[38:41], 0
	v_mfma_f32_16x16x32_bf16 v[34:37], v[54:57], v[42:45], v[34:37]
	v_mfma_f32_16x16x32_bf16 v[38:41], v[70:73], v[42:45], v[38:41]
	v_mfma_f32_16x16x32_bf16 v[42:45], v[50:53], v[46:49], 0
	v_mfma_f32_16x16x32_bf16 v[46:49], v[66:69], v[46:49], 0
	v_mfma_f32_16x16x32_bf16 v[42:45], v[54:57], v[58:61], v[42:45]
	v_mfma_f32_16x16x32_bf16 v[46:49], v[70:73], v[58:61], v[46:49]
	v_mfma_f32_16x16x32_bf16 v[58:61], v[50:53], v[62:65], 0
	v_mfma_f32_16x16x32_bf16 v[62:65], v[66:69], v[62:65], 0
	v_mfma_f32_16x16x32_bf16 v[58:61], v[54:57], v[78:81], v[58:61]
	v_mfma_f32_16x16x32_bf16 v[62:65], v[70:73], v[78:81], v[62:65]
	v_mfma_f32_16x16x32_bf16 v[78:81], v[50:53], v[90:93], 0
	v_mfma_f32_16x16x32_bf16 v[90:93], v[66:69], v[90:93], 0
	v_mfma_f32_16x16x32_bf16 v[78:81], v[54:57], v[100:103], v[78:81]
	v_mfma_f32_16x16x32_bf16 v[92:95], v[70:73], v[100:103], v[90:93]
	s_setprio 0
	s_barrier
	ds_read_b128 v[162:165], v245 offset:16384
	ds_read_b128 v[166:169], v245 offset:17408
	ds_read_b128 v[154:157], v245 offset:18432
	ds_read_b128 v[158:161], v245 offset:19456
	ds_read_b128 v[146:149], v245 offset:20480
	ds_read_b128 v[150:153], v245 offset:21504
	ds_read_b128 v[110:113], v245 offset:22528
	ds_read_b128 v[126:129], v245 offset:23552
	s_mov_b32 m0, s22
	s_nop 0
	global_load_lds_dwordx4 v251, s[42:43]
	s_add_u32 m0, m0, 0x2000
	s_nop 0
	global_load_lds_dwordx4 v247, s[42:43]
	s_add_u32 s42, s84, 0x580100
	s_addc_u32 s43, s85, 0
	s_mov_b32 m0, s23
	s_nop 0
	global_load_lds_dwordx4 v251, s[42:43]
	s_add_u32 m0, m0, 0x2000
	s_nop 0
	global_load_lds_dwordx4 v247, s[42:43]
	v_cndmask_b32_e64 v90, 0, 1, s[88:89]
	s_mov_b32 m0, s13
	s_nop 0
	global_load_lds_dwordx4 v250, s[14:15]
	s_add_u32 m0, m0, 0x2000
	s_nop 0
	global_load_lds_dwordx4 v246, s[14:15]
	v_cmp_ne_u32_e64 s[42:43], 1, v90
	s_andn2_b64 vcc, exec, s[88:89]
	s_cbranch_vccnz .LBB0_555
	s_waitcnt vmcnt(8)
.LBB0_555:
	s_waitcnt lgkmcnt(0)
	s_barrier
	s_setprio 1
	v_mfma_f32_16x16x32_bf16 v[100:103], v[74:77], v[162:165], 0
	v_mfma_f32_16x16x32_bf16 v[114:117], v[74:77], v[154:157], 0
	v_mfma_f32_16x16x32_bf16 v[122:125], v[74:77], v[146:149], 0
	v_mfma_f32_16x16x32_bf16 v[74:77], v[74:77], v[110:113], 0
	v_mfma_f32_16x16x32_bf16 v[106:109], v[86:89], v[162:165], 0
	v_mfma_f32_16x16x32_bf16 v[118:121], v[86:89], v[154:157], 0
	v_mfma_f32_16x16x32_bf16 v[130:133], v[86:89], v[146:149], 0
	v_mfma_f32_16x16x32_bf16 v[134:137], v[82:85], v[126:129], v[74:77]
	v_mfma_f32_16x16x32_bf16 v[74:77], v[86:89], v[110:113], 0
	v_mfma_f32_16x16x32_bf16 v[102:105], v[82:85], v[166:169], v[100:103]
	v_mfma_f32_16x16x32_bf16 v[106:109], v[96:99], v[166:169], v[106:109]
	v_mfma_f32_16x16x32_bf16 v[114:117], v[82:85], v[158:161], v[114:117]
	v_mfma_f32_16x16x32_bf16 v[118:121], v[96:99], v[158:161], v[118:121]
	v_mfma_f32_16x16x32_bf16 v[122:125], v[82:85], v[150:153], v[122:125]
	v_mfma_f32_16x16x32_bf16 v[130:133], v[96:99], v[150:153], v[130:133]
	v_mfma_f32_16x16x32_bf16 v[138:141], v[96:99], v[126:129], v[74:77]
	s_setprio 0
	s_setprio 1
	v_mfma_f32_16x16x32_bf16 v[74:77], v[50:53], v[162:165], 0
	v_mfma_f32_16x16x32_bf16 v[142:145], v[54:57], v[166:169], v[74:77]
	v_mfma_f32_16x16x32_bf16 v[74:77], v[66:69], v[162:165], 0
	v_mfma_f32_16x16x32_bf16 v[166:169], v[70:73], v[166:169], v[74:77]
	v_mfma_f32_16x16x32_bf16 v[74:77], v[50:53], v[154:157], 0
	v_mfma_f32_16x16x32_bf16 v[170:173], v[54:57], v[158:161], v[74:77]
	v_mfma_f32_16x16x32_bf16 v[74:77], v[66:69], v[154:157], 0
	v_mfma_f32_16x16x32_bf16 v[174:177], v[70:73], v[158:161], v[74:77]
	v_mfma_f32_16x16x32_bf16 v[74:77], v[50:53], v[146:149], 0
	v_mfma_f32_16x16x32_bf16 v[50:53], v[50:53], v[110:113], 0
	v_mfma_f32_16x16x32_bf16 v[178:181], v[54:57], v[150:153], v[74:77]
	v_mfma_f32_16x16x32_bf16 v[74:77], v[66:69], v[146:149], 0
	v_mfma_f32_16x16x32_bf16 v[186:189], v[54:57], v[126:129], v[50:53]
	v_mfma_f32_16x16x32_bf16 v[50:53], v[66:69], v[110:113], 0
	v_mfma_f32_16x16x32_bf16 v[182:185], v[70:73], v[150:153], v[74:77]
	v_mfma_f32_16x16x32_bf16 v[190:193], v[70:73], v[126:129], v[50:53]
	s_setprio 0
	s_barrier
	v_add_u32_e32 v235, 0x18000, v244
	v_add_u32_e32 v248, 0x1c000, v244
	ds_read_b128 v[162:165], v235
	ds_read_b128 v[210:213], v235 offset:1024
	ds_read_b128 v[214:217], v235 offset:2048
	ds_read_b128 v[218:221], v235 offset:3072
	ds_read_b128 v[194:197], v248
	ds_read_b128 v[198:201], v248 offset:1024
	ds_read_b128 v[202:205], v248 offset:2048
	ds_read_b128 v[206:209], v248 offset:3072
	ds_read_b128 v[96:99], v245 offset:32768
	ds_read_b128 v[154:157], v245 offset:33792
	ds_read_b128 v[126:129], v245 offset:34816
	ds_read_b128 v[158:161], v245 offset:35840
	ds_read_b128 v[110:113], v245 offset:36864
	ds_read_b128 v[230:233], v245 offset:37888
	ds_read_b128 v[222:225], v245 offset:38912
	ds_read_b128 v[226:229], v245 offset:39936
	s_add_u32 s14, s86, 0x2100
	s_addc_u32 s15, s87, 0
	s_mov_b32 m0, s45
	s_nop 0
	global_load_lds_dwordx4 v250, s[14:15]
	s_add_u32 m0, m0, 0x2000
	s_nop 0
	global_load_lds_dwordx4 v246, s[14:15]
	s_and_b64 vcc, exec, s[42:43]
	s_cbranch_vccnz .LBB0_557
	s_waitcnt vmcnt(8)
; #define PG8_WAIT_V(n) asm volatile("s_waitcnt vmcnt(" #n ")" ::: "memory")
; template <class Epi, bool ALIGN_EPI, bool EARLY_DRAIN = true, class Pre = NoPre>
; __device__ __forceinline__ void gemm_phase(LAS unsigned char* lds, const Gemm g, const StaticOrder& S, const Epi& E, int wv, const Pre& pre = Pre()) {
;     ...
;         const char* nA = has_next ? g.A + (size_t)nxt.pm * g.a_tstep + (size_t)(nxt.pm >> 6) * g.a_pad : cA; const char* nB = has_next ? g.Bt + (size_t)nxt.pn * g.b_tstep : cB;
;         int landed_flag = fresh ? 1 : 0;
;         typename Epi::PF pf;
;         if constexpr (Epi::PREF) { int pt_ = lane_now(); asm volatile("" : "+v"(pt_)); E.prefetch(pf, cur, wr, wc, pt_ & 15, pt_ >> 4); }
;         for (int th = 0; th < nt; th += (Epi::MIDK ? nt / 2 : nt)) {
;         if constexpr (Epi::MIDK) { if (th) E.midk(acc, ui, wr, fr); }
;         for (int t = th; t < th + (Epi::MIDK ? nt / 2 : nt); t += 2) {
;             const bool last = (t == nt - 2);
;             const char* a1 = cA + (size_t)(t + 1) * kstep;
;             const char* a2 = last ? nA : cA + (size_t)(t + 2) * kstep; const char* b2 = last ? nB : cB + (size_t)(t + 2) * kstep;
;             const char* a3 = a2 + kstep; const char* b3 = b2 + kstep;
;             int lf_ = EARLY_DRAIN ? __builtin_amdgcn_readfirstlane(landed_flag) : landed_flag; if constexpr (EARLY_DRAIN) asm volatile("" : "+s"(lf_)); landed_flag = 0;
;             PG8_LDB(B0, 0, 0); PG8_LDB(B1, 0, 1); PG8_SCHED; PG8_LDA(At, 0, 0); PG8_STAGE(PG8_SA(1, 1), a1 + ahs, voffA);
;             if (!lf_) PG8_WAIT_V(8);
;             PG8_WAIT_L(0); PG8_BAR; PG8_MMA(0, 0, At, B0); PG8_MMA(0, 1, At, B1); PG8_BAR; PG8_SCHED;
;             PG8_LDA(At, 0, 1); PG8_STAGE(PG8_SB(0, 0), b2, voffB); PG8_STAGE(PG8_SB(0, 1), b2 + bhs, voffB); PG8_STAGE(PG8_SA(0, 0), a2, voffA);
;             if (!lf_) PG8_WAIT_V(8);
;             PG8_WAIT_L(0); PG8_BAR; PG8_MMA(1, 0, At, B0); PG8_MMA(1, 1, At, B1); PG8_BAR; PG8_SCHED;
;             PG8_LDB(B0, 1, 0); PG8_LDB(B1, 1, 1); PG8_SCHED; PG8_LDA(At, 1, 0); PG8_STAGE(PG8_SA(0, 1), a2 + ahs, voffA);
;             if (!lf_) PG8_WAIT_V(8);
;             PG8_WAIT_L(0); PG8_BAR; PG8_MMA(0, 0, At, B0); PG8_MMA(0, 1, At, B1); PG8_BAR; PG8_SCHED;
;             PG8_LDA(At, 1, 1); PG8_STAGE(PG8_SB(1, 0), b3, voffB); PG8_STAGE(PG8_SB(1, 1), b3 + bhs, voffB); PG8_STAGE(PG8_SA(1, 0), a3, voffA);
.LBB0_557:
	s_ashr_i32 s61, s60, 31
	s_lshl_b64 s[14:15], s[60:61], 18
	s_add_u32 s88, s5, s14
	s_addc_u32 s89, s12, s15
	s_and_b64 s[14:15], s[40:41], exec
	s_cselect_b32 s47, s89, s85
	s_cselect_b32 s50, s88, s84
	s_add_u32 s14, s86, 0x180
	s_waitcnt lgkmcnt(0)
	s_addc_u32 s15, s87, 0
	s_add_u32 s40, s84, 0x180
	s_addc_u32 s41, s85, 0
	s_barrier
	s_setprio 1
	v_mfma_f32_16x16x32_bf16 v[2:5], v[162:165], v[96:99], v[2:5]
	v_mfma_f32_16x16x32_bf16 v[70:73], v[210:213], v[154:157], v[2:5]
	v_mfma_f32_16x16x32_bf16 v[2:5], v[214:217], v[96:99], v[6:9]
	v_mfma_f32_16x16x32_bf16 v[146:149], v[218:221], v[154:157], v[2:5]
	v_mfma_f32_16x16x32_bf16 v[2:5], v[162:165], v[126:129], v[10:13]
	v_mfma_f32_16x16x32_bf16 v[74:77], v[210:213], v[158:161], v[2:5]
	v_mfma_f32_16x16x32_bf16 v[2:5], v[214:217], v[126:129], v[14:17]
	v_mfma_f32_16x16x32_bf16 v[150:153], v[218:221], v[158:161], v[2:5]
	v_mfma_f32_16x16x32_bf16 v[2:5], v[162:165], v[110:113], v[18:21]
	v_mfma_f32_16x16x32_bf16 v[82:85], v[210:213], v[230:233], v[2:5]
	v_mfma_f32_16x16x32_bf16 v[2:5], v[214:217], v[110:113], v[22:25]
	v_mfma_f32_16x16x32_bf16 v[66:69], v[218:221], v[230:233], v[2:5]
	v_mfma_f32_16x16x32_bf16 v[2:5], v[162:165], v[222:225], v[26:29]
	v_mfma_f32_16x16x32_bf16 v[54:57], v[210:213], v[226:229], v[2:5]
	v_mfma_f32_16x16x32_bf16 v[2:5], v[214:217], v[222:225], v[30:33]
	v_mfma_f32_16x16x32_bf16 v[50:53], v[218:221], v[226:229], v[2:5]
	s_setprio 0
	s_setprio 1
	v_mfma_f32_16x16x32_bf16 v[2:5], v[194:197], v[96:99], v[34:37]
	v_mfma_f32_16x16x32_bf16 v[88:91], v[198:201], v[154:157], v[2:5]
	v_mfma_f32_16x16x32_bf16 v[2:5], v[202:205], v[96:99], v[38:41]
	v_mfma_f32_16x16x32_bf16 v[154:157], v[206:209], v[154:157], v[2:5]
	v_mfma_f32_16x16x32_bf16 v[2:5], v[194:197], v[126:129], v[42:45]
	v_mfma_f32_16x16x32_bf16 v[98:101], v[198:201], v[158:161], v[2:5]
	v_mfma_f32_16x16x32_bf16 v[2:5], v[202:205], v[126:129], v[46:49]
	v_mfma_f32_16x16x32_bf16 v[158:161], v[206:209], v[158:161], v[2:5]
	v_mfma_f32_16x16x32_bf16 v[2:5], v[194:197], v[110:113], v[58:61]
	v_mfma_f32_16x16x32_bf16 v[126:129], v[198:201], v[230:233], v[2:5]
	v_mfma_f32_16x16x32_bf16 v[2:5], v[202:205], v[110:113], v[62:65]
	v_mfma_f32_16x16x32_bf16 v[110:113], v[206:209], v[230:233], v[2:5]
	v_mfma_f32_16x16x32_bf16 v[2:5], v[194:197], v[222:225], v[78:81]
	v_mfma_f32_16x16x32_bf16 v[62:65], v[198:201], v[226:229], v[2:5]
	v_mfma_f32_16x16x32_bf16 v[2:5], v[202:205], v[222:225], v[92:95]
	v_mfma_f32_16x16x32_bf16 v[58:61], v[206:209], v[226:229], v[2:5]
	s_setprio 0
	s_barrier
	ds_read_b128 v[10:13], v245 offset:49152
	ds_read_b128 v[14:17], v245 offset:50176
	ds_read_b128 v[22:25], v245 offset:51200
	ds_read_b128 v[78:81], v245 offset:52224
	ds_read_b128 v[92:95], v245 offset:53248
	ds_read_b128 v[222:225], v245 offset:54272
	ds_read_b128 v[226:229], v245 offset:55296
	ds_read_b128 v[230:233], v245 offset:56320
	s_mov_b32 m0, s64
	s_nop 0
	global_load_lds_dwordx4 v251, s[40:41]
	s_add_u32 m0, m0, 0x2000
	s_nop 0
	global_load_lds_dwordx4 v247, s[40:41]
	s_add_u32 s40, s84, 0x580180
	s_addc_u32 s41, s85, 0
	s_mov_b32 m0, s66
	s_nop 0
	global_load_lds_dwordx4 v251, s[40:41]
	s_add_u32 m0, m0, 0x2000
	s_nop 0
	global_load_lds_dwordx4 v247, s[40:41]
	s_nop 0
	s_mov_b32 m0, s65
	s_nop 0
	global_load_lds_dwordx4 v250, s[14:15]
	s_add_u32 m0, m0, 0x2000
	s_nop 0
	global_load_lds_dwordx4 v246, s[14:15]
	s_waitcnt vmcnt(8)
	s_waitcnt lgkmcnt(0)
	s_barrier
	s_setprio 1
	v_mfma_f32_16x16x32_bf16 v[2:5], v[162:165], v[10:13], v[102:105]
	v_mfma_f32_16x16x32_bf16 v[38:41], v[210:213], v[14:17], v[2:5]
	v_mfma_f32_16x16x32_bf16 v[2:5], v[214:217], v[10:13], v[106:109]
	v_mfma_f32_16x16x32_bf16 v[34:37], v[218:221], v[14:17], v[2:5]
	v_mfma_f32_16x16x32_bf16 v[2:5], v[162:165], v[22:25], v[114:117]
	v_mfma_f32_16x16x32_bf16 v[26:29], v[210:213], v[78:81], v[2:5]
	v_mfma_f32_16x16x32_bf16 v[2:5], v[214:217], v[22:25], v[118:121]
	v_mfma_f32_16x16x32_bf16 v[18:21], v[218:221], v[78:81], v[2:5]
	v_mfma_f32_16x16x32_bf16 v[2:5], v[162:165], v[92:95], v[122:125]
	v_mfma_f32_16x16x32_bf16 v[30:33], v[162:165], v[226:229], v[134:137]
	v_mfma_f32_16x16x32_bf16 v[6:9], v[210:213], v[222:225], v[2:5]
	v_mfma_f32_16x16x32_bf16 v[2:5], v[214:217], v[92:95], v[130:133]
	v_mfma_f32_16x16x32_bf16 v[106:109], v[210:213], v[230:233], v[30:33]
	v_mfma_f32_16x16x32_bf16 v[30:33], v[214:217], v[226:229], v[138:141]
	v_mfma_f32_16x16x32_bf16 v[2:5], v[218:221], v[222:225], v[2:5]
	v_mfma_f32_16x16x32_bf16 v[162:165], v[218:221], v[230:233], v[30:33]
	s_setprio 0
	s_setprio 1
	v_mfma_f32_16x16x32_bf16 v[30:33], v[194:197], v[10:13], v[142:145]
	v_mfma_f32_16x16x32_bf16 v[10:13], v[202:205], v[10:13], v[166:169]
	v_mfma_f32_16x16x32_bf16 v[42:45], v[206:209], v[14:17], v[10:13]
	v_mfma_f32_16x16x32_bf16 v[10:13], v[194:197], v[22:25], v[170:173]
	v_mfma_f32_16x16x32_bf16 v[46:49], v[198:201], v[14:17], v[30:33]
	v_mfma_f32_16x16x32_bf16 v[30:33], v[198:201], v[78:81], v[10:13]
	v_mfma_f32_16x16x32_bf16 v[10:13], v[202:205], v[22:25], v[174:177]
	v_mfma_f32_16x16x32_bf16 v[22:25], v[206:209], v[78:81], v[10:13]
	v_mfma_f32_16x16x32_bf16 v[10:13], v[194:197], v[92:95], v[178:181]
	v_mfma_f32_16x16x32_bf16 v[78:81], v[194:197], v[226:229], v[186:189]
	v_mfma_f32_16x16x32_bf16 v[14:17], v[198:201], v[222:225], v[10:13]
	v_mfma_f32_16x16x32_bf16 v[10:13], v[202:205], v[92:95], v[182:185]
	v_mfma_f32_16x16x32_bf16 v[114:117], v[198:201], v[230:233], v[78:81]
	v_mfma_f32_16x16x32_bf16 v[78:81], v[202:205], v[226:229], v[190:193]
	v_mfma_f32_16x16x32_bf16 v[10:13], v[206:209], v[222:225], v[10:13]
	v_mfma_f32_16x16x32_bf16 v[166:169], v[206:209], v[230:233], v[78:81]
	s_setprio 0
	s_barrier
	s_add_u32 s51, s86, 0x200
	s_addc_u32 s52, s87, 0
	s_add_u32 s53, s84, 0x200
	s_addc_u32 s61, s85, 0
	s_add_u32 s42, s86, 0x2180
	s_addc_u32 s43, s87, 0
	s_mov_b32 s0, 0
	s_branch .LBB0_559
; #define PG8_STAGE(bufoff, gbase, voff) glds16s2((voff)[0], (voff)[1], (const void*)(gbase), ldsn + (unsigned)(bufoff))
; #define PG8_LDA(dst, b, h) do { _Pragma("unroll") for (int m = 0; m < 4; ++m) _Pragma("unroll") for (int k = 0; k < 2; ++k) dst[m][k] = *(const LAS bf16x8*)(lds + PG8_SA(b, h) + aoff + m * 2048 + k * 1024); } while (0)
; #define PG8_WAIT_V(n) asm volatile("s_waitcnt vmcnt(" #n ")" ::: "memory")
; #define PG8_WAIT_L(n) asm volatile("s_waitcnt lgkmcnt(" #n ")" ::: "memory")
; template <class Epi, bool ALIGN_EPI, bool EARLY_DRAIN = true, class Pre = NoPre>
; __device__ __forceinline__ void gemm_phase(LAS unsigned char* lds, const Gemm g, const StaticOrder& S, const Epi& E, int wv, const Pre& pre = Pre()) {
;     ...
;         for (int t = th; t < th + (Epi::MIDK ? nt / 2 : nt); t += 2) {
;             const bool last = (t == nt - 2);
;             const char* a1 = cA + (size_t)(t + 1) * kstep;
;             const char* a2 = last ? nA : cA + (size_t)(t + 2) * kstep; const char* b2 = last ? nB : cB + (size_t)(t + 2) * kstep;
;             const char* a3 = a2 + kstep; const char* b3 = b2 + kstep;
;             int lf_ = EARLY_DRAIN ? __builtin_amdgcn_readfirstlane(landed_flag) : landed_flag; if constexpr (EARLY_DRAIN) asm volatile("" : "+s"(lf_)); landed_flag = 0;
;             PG8_LDB(B0, 0, 0); PG8_LDB(B1, 0, 1); PG8_SCHED; PG8_LDA(At, 0, 0); PG8_STAGE(PG8_SA(1, 1), a1 + ahs, voffA);
;             if (!lf_) PG8_WAIT_V(8);
;             PG8_WAIT_L(0); PG8_BAR; PG8_MMA(0, 0, At, B0); PG8_MMA(0, 1, At, B1); PG8_BAR; PG8_SCHED;
;             PG8_LDA(At, 0, 1); PG8_STAGE(PG8_SB(0, 0), b2, voffB); PG8_STAGE(PG8_SB(0, 1), b2 + bhs, voffB); PG8_STAGE(PG8_SA(0, 0), a2, voffA);
;             if (!lf_) PG8_WAIT_V(8);
;             PG8_WAIT_L(0); PG8_BAR; PG8_MMA(1, 0, At, B0); PG8_MMA(1, 1, At, B1); PG8_BAR; PG8_SCHED;
;             PG8_LDB(B0, 1, 0); PG8_LDB(B1, 1, 1); PG8_SCHED; PG8_LDA(At, 1, 0); PG8_STAGE(PG8_SA(0, 1), a2 + ahs, voffA);
;             if (!lf_) PG8_WAIT_V(8);
;             PG8_WAIT_L(0); PG8_BAR; PG8_MMA(0, 0, At, B0); PG8_MMA(0, 1, At, B1); PG8_BAR; PG8_SCHED;
;             PG8_LDA(At, 1, 1); PG8_STAGE(PG8_SB(1, 0), b3, voffB); PG8_STAGE(PG8_SB(1, 1), b3 + bhs, voffB); PG8_STAGE(PG8_SA(1, 0), a3, voffA);
;             PG8_WAIT_V(8); PG8_WAIT_L(0); PG8_BAR; PG8_MMA(1, 0, At, B0); PG8_MMA(1, 1, At, B1); PG8_BAR; PG8_SCHED;
.LBB0_558:
	s_add_u32 s14, s86, 0x80
	s_waitcnt lgkmcnt(0)
	s_addc_u32 s15, s87, 0
	s_add_u32 s40, s84, 0x80
	s_addc_u32 s41, s85, 0
	s_barrier
	s_setprio 1
	v_mfma_f32_16x16x32_bf16 v[78:81], v[178:181], v[154:157], v[78:81]
	v_mfma_f32_16x16x32_bf16 v[146:149], v[182:185], v[202:205], v[78:81]
	v_mfma_f32_16x16x32_bf16 v[78:81], v[178:181], v[126:129], v[92:95]
	v_mfma_f32_16x16x32_bf16 v[70:73], v[162:165], v[154:157], v[70:73]
	v_mfma_f32_16x16x32_bf16 v[74:77], v[162:165], v[126:129], v[74:77]
	v_mfma_f32_16x16x32_bf16 v[150:153], v[182:185], v[158:161], v[78:81]
	v_mfma_f32_16x16x32_bf16 v[78:81], v[162:165], v[194:197], v[82:85]
	v_mfma_f32_16x16x32_bf16 v[66:69], v[178:181], v[194:197], v[66:69]
	v_mfma_f32_16x16x32_bf16 v[54:57], v[162:165], v[186:189], v[54:57]
	v_mfma_f32_16x16x32_bf16 v[50:53], v[178:181], v[186:189], v[50:53]
	v_mfma_f32_16x16x32_bf16 v[70:73], v[174:177], v[202:205], v[70:73]
	v_mfma_f32_16x16x32_bf16 v[74:77], v[174:177], v[158:161], v[74:77]
	v_mfma_f32_16x16x32_bf16 v[82:85], v[174:177], v[198:201], v[78:81]
	v_mfma_f32_16x16x32_bf16 v[66:69], v[182:185], v[198:201], v[66:69]
	v_mfma_f32_16x16x32_bf16 v[54:57], v[174:177], v[190:193], v[54:57]
	v_mfma_f32_16x16x32_bf16 v[50:53], v[182:185], v[190:193], v[50:53]
	s_setprio 0
	s_setprio 1
	v_mfma_f32_16x16x32_bf16 v[78:81], v[138:141], v[154:157], v[86:89]
	v_mfma_f32_16x16x32_bf16 v[88:91], v[142:145], v[202:205], v[78:81]
	v_mfma_f32_16x16x32_bf16 v[78:81], v[166:169], v[154:157], v[102:105]
	v_mfma_f32_16x16x32_bf16 v[154:157], v[170:173], v[202:205], v[78:81]
	v_mfma_f32_16x16x32_bf16 v[78:81], v[138:141], v[126:129], v[96:99]
	v_mfma_f32_16x16x32_bf16 v[98:101], v[142:145], v[158:161], v[78:81]
	v_mfma_f32_16x16x32_bf16 v[78:81], v[166:169], v[126:129], v[118:121]
	v_mfma_f32_16x16x32_bf16 v[158:161], v[170:173], v[158:161], v[78:81]
	v_mfma_f32_16x16x32_bf16 v[78:81], v[138:141], v[194:197], v[122:125]
	v_mfma_f32_16x16x32_bf16 v[126:129], v[142:145], v[198:201], v[78:81]
	v_mfma_f32_16x16x32_bf16 v[78:81], v[166:169], v[194:197], v[110:113]
	v_mfma_f32_16x16x32_bf16 v[62:65], v[138:141], v[186:189], v[62:65]
	v_mfma_f32_16x16x32_bf16 v[58:61], v[166:169], v[186:189], v[58:61]
	v_mfma_f32_16x16x32_bf16 v[110:113], v[170:173], v[198:201], v[78:81]
	v_mfma_f32_16x16x32_bf16 v[62:65], v[142:145], v[190:193], v[62:65]
	v_mfma_f32_16x16x32_bf16 v[58:61], v[170:173], v[190:193], v[58:61]
	s_setprio 0
	s_barrier
	s_nop 0
	ds_read_b128 v[78:81], v245 offset:49152
	ds_read_b128 v[92:95], v245 offset:50176
	ds_read_b128 v[102:105], v245 offset:51200
	ds_read_b128 v[118:121], v245 offset:52224
	ds_read_b128 v[122:125], v245 offset:53248
	ds_read_b128 v[186:189], v245 offset:54272
	ds_read_b128 v[190:193], v245 offset:55296
	ds_read_b128 v[194:197], v245 offset:56320
	s_mov_b32 m0, s64
	s_nop 0
	global_load_lds_dwordx4 v251, s[40:41]
	s_add_u32 m0, m0, 0x2000
	s_nop 0
	global_load_lds_dwordx4 v247, s[40:41]
	s_add_u32 s40, s84, 0x580080
	s_addc_u32 s41, s85, 0
	s_mov_b32 m0, s66
	s_nop 0
	global_load_lds_dwordx4 v251, s[40:41]
	s_add_u32 m0, m0, 0x2000
	s_nop 0
	global_load_lds_dwordx4 v247, s[40:41]
	s_nop 0
	s_mov_b32 m0, s65
	s_nop 0
	global_load_lds_dwordx4 v250, s[14:15]
	s_add_u32 m0, m0, 0x2000
	s_nop 0
	global_load_lds_dwordx4 v246, s[14:15]
	s_waitcnt vmcnt(8)
	s_waitcnt lgkmcnt(0)
	s_barrier
	s_setprio 1
	v_mfma_f32_16x16x32_bf16 v[38:41], v[162:165], v[78:81], v[38:41]
	v_mfma_f32_16x16x32_bf16 v[34:37], v[178:181], v[78:81], v[34:37]
	v_mfma_f32_16x16x32_bf16 v[26:29], v[162:165], v[102:105], v[26:29]
	v_mfma_f32_16x16x32_bf16 v[18:21], v[178:181], v[102:105], v[18:21]
	v_mfma_f32_16x16x32_bf16 v[6:9], v[162:165], v[122:125], v[6:9]
	v_mfma_f32_16x16x32_bf16 v[2:5], v[178:181], v[122:125], v[2:5]
	v_mfma_f32_16x16x32_bf16 v[106:109], v[162:165], v[190:193], v[106:109]
	v_mfma_f32_16x16x32_bf16 v[130:133], v[178:181], v[190:193], v[130:133]
	v_mfma_f32_16x16x32_bf16 v[38:41], v[174:177], v[92:95], v[38:41]
	v_mfma_f32_16x16x32_bf16 v[34:37], v[182:185], v[92:95], v[34:37]
	v_mfma_f32_16x16x32_bf16 v[26:29], v[174:177], v[118:121], v[26:29]
	v_mfma_f32_16x16x32_bf16 v[18:21], v[182:185], v[118:121], v[18:21]
	v_mfma_f32_16x16x32_bf16 v[6:9], v[174:177], v[186:189], v[6:9]
	v_mfma_f32_16x16x32_bf16 v[2:5], v[182:185], v[186:189], v[2:5]
	v_mfma_f32_16x16x32_bf16 v[106:109], v[174:177], v[194:197], v[106:109]
	v_mfma_f32_16x16x32_bf16 v[162:165], v[182:185], v[194:197], v[130:133]
	s_setprio 0
	s_setprio 1
	v_mfma_f32_16x16x32_bf16 v[46:49], v[138:141], v[78:81], v[46:49]
	v_mfma_f32_16x16x32_bf16 v[42:45], v[166:169], v[78:81], v[42:45]
	v_mfma_f32_16x16x32_bf16 v[78:81], v[138:141], v[190:193], v[114:117]
	v_mfma_f32_16x16x32_bf16 v[30:33], v[138:141], v[102:105], v[30:33]
	v_mfma_f32_16x16x32_bf16 v[22:25], v[166:169], v[102:105], v[22:25]
	v_mfma_f32_16x16x32_bf16 v[14:17], v[138:141], v[122:125], v[14:17]
	v_mfma_f32_16x16x32_bf16 v[10:13], v[166:169], v[122:125], v[10:13]
	v_mfma_f32_16x16x32_bf16 v[114:117], v[142:145], v[194:197], v[78:81]
	v_mfma_f32_16x16x32_bf16 v[78:81], v[166:169], v[190:193], v[134:137]
	v_mfma_f32_16x16x32_bf16 v[46:49], v[142:145], v[92:95], v[46:49]
	v_mfma_f32_16x16x32_bf16 v[42:45], v[170:173], v[92:95], v[42:45]
	v_mfma_f32_16x16x32_bf16 v[30:33], v[142:145], v[118:121], v[30:33]
	v_mfma_f32_16x16x32_bf16 v[22:25], v[170:173], v[118:121], v[22:25]
	v_mfma_f32_16x16x32_bf16 v[14:17], v[142:145], v[186:189], v[14:17]
	v_mfma_f32_16x16x32_bf16 v[10:13], v[170:173], v[186:189], v[10:13]
	v_mfma_f32_16x16x32_bf16 v[166:169], v[170:173], v[194:197], v[78:81]
	s_setprio 0
	s_barrier
	s_add_i32 s0, s0, 2
	s_add_u32 s51, s51, 0x100
	s_addc_u32 s52, s52, 0
	s_add_u32 s53, s53, 0x100
	s_addc_u32 s61, s61, 0
	s_add_u32 s42, s42, 0x100
	s_addc_u32 s43, s43, 0
	s_cmp_gt_u32 s0, 13
	s_cbranch_scc1 .LBB0_565

; #define PG8_STAGE(bufoff, gbase, voff) glds16s2((voff)[0], (voff)[1], (const void*)(gbase), ldsn + (unsigned)(bufoff))
; #define PG8_LDA(dst, b, h) do { _Pragma("unroll") for (int m = 0; m < 4; ++m) _Pragma("unroll") for (int k = 0; k < 2; ++k) dst[m][k] = *(const LAS bf16x8*)(lds + PG8_SA(b, h) + aoff + m * 2048 + k * 1024); } while (0)
; #define PG8_LDB(dst, b, h) do { _Pragma("unroll") for (int n = 0; n < 2; ++n) _Pragma("unroll") for (int k = 0; k < 2; ++k) dst[n][k] = *(const LAS bf16x8*)(lds + PG8_SB(b, h) + boff + n * 2048 + k * 1024); } while (0)
; #define PG8_WAIT_V(n) asm volatile("s_waitcnt vmcnt(" #n ")" ::: "memory")
; #define PG8_WAIT_L(n) asm volatile("s_waitcnt lgkmcnt(" #n ")" ::: "memory")
; #define PG8_BAR __builtin_amdgcn_s_barrier()
; #define PG8_SCHED __builtin_amdgcn_sched_barrier(0)
; template <class Epi, bool ALIGN_EPI, bool EARLY_DRAIN = true, class Pre = NoPre>
; __device__ __forceinline__ void gemm_phase(LAS unsigned char* lds, const Gemm g, const StaticOrder& S, const Epi& E, int wv, const Pre& pre = Pre()) {
;     ...
;             const bool last = (t == nt - 2);
;             const char* a1 = cA + (size_t)(t + 1) * kstep;
;             const char* a2 = last ? nA : cA + (size_t)(t + 2) * kstep; const char* b2 = last ? nB : cB + (size_t)(t + 2) * kstep;
;             const char* a3 = a2 + kstep; const char* b3 = b2 + kstep;
;             int lf_ = EARLY_DRAIN ? __builtin_amdgcn_readfirstlane(landed_flag) : landed_flag; if constexpr (EARLY_DRAIN) asm volatile("" : "+s"(lf_)); landed_flag = 0;
;             PG8_LDB(B0, 0, 0); PG8_LDB(B1, 0, 1); PG8_SCHED; PG8_LDA(At, 0, 0); PG8_STAGE(PG8_SA(1, 1), a1 + ahs, voffA);
;             if (!lf_) PG8_WAIT_V(8);
;             PG8_WAIT_L(0); PG8_BAR; PG8_MMA(0, 0, At, B0); PG8_MMA(0, 1, At, B1); PG8_BAR; PG8_SCHED;
;             PG8_LDA(At, 0, 1); PG8_STAGE(PG8_SB(0, 0), b2, voffB); PG8_STAGE(PG8_SB(0, 1), b2 + bhs, voffB); PG8_STAGE(PG8_SA(0, 0), a2, voffA);
;             if (!lf_) PG8_WAIT_V(8);
;             PG8_WAIT_L(0); PG8_BAR; PG8_MMA(1, 0, At, B0); PG8_MMA(1, 1, At, B1); PG8_BAR; PG8_SCHED;
;             PG8_LDB(B0, 1, 0); PG8_LDB(B1, 1, 1); PG8_SCHED; PG8_LDA(At, 1, 0); PG8_STAGE(PG8_SA(0, 1), a2 + ahs, voffA);
;             if (!lf_) PG8_WAIT_V(8);
;             PG8_WAIT_L(0); PG8_BAR; PG8_MMA(0, 0, At, B0); PG8_MMA(0, 1, At, B1); PG8_BAR; PG8_SCHED;
.LBB0_561:
	s_waitcnt lgkmcnt(0)
	s_cmp_eq_u32 s0, 12
	s_cselect_b32 s87, s71, s52
	s_cselect_b32 s86, s70, s51
	s_cselect_b32 s85, s47, s61
	s_cselect_b32 s84, s50, s53
	s_barrier
	s_setprio 1
	v_mfma_f32_16x16x32_bf16 v[70:73], v[130:133], v[102:105], v[70:73]
	v_mfma_f32_16x16x32_bf16 v[78:81], v[178:181], v[102:105], v[146:149]
	v_mfma_f32_16x16x32_bf16 v[74:77], v[130:133], v[118:121], v[74:77]
	v_mfma_f32_16x16x32_bf16 v[92:95], v[178:181], v[118:121], v[150:153]
	v_mfma_f32_16x16x32_bf16 v[82:85], v[130:133], v[194:197], v[82:85]
	v_mfma_f32_16x16x32_bf16 v[66:69], v[178:181], v[194:197], v[66:69]
	v_mfma_f32_16x16x32_bf16 v[54:57], v[130:133], v[186:189], v[54:57]
	v_mfma_f32_16x16x32_bf16 v[50:53], v[178:181], v[186:189], v[50:53]
	v_mfma_f32_16x16x32_bf16 v[70:73], v[174:177], v[202:205], v[70:73]
	v_mfma_f32_16x16x32_bf16 v[78:81], v[182:185], v[202:205], v[78:81]
	v_mfma_f32_16x16x32_bf16 v[74:77], v[174:177], v[122:125], v[74:77]
	v_mfma_f32_16x16x32_bf16 v[92:95], v[182:185], v[122:125], v[92:95]
	v_mfma_f32_16x16x32_bf16 v[82:85], v[174:177], v[198:201], v[82:85]
	v_mfma_f32_16x16x32_bf16 v[66:69], v[182:185], v[198:201], v[66:69]
	v_mfma_f32_16x16x32_bf16 v[54:57], v[174:177], v[190:193], v[54:57]
	v_mfma_f32_16x16x32_bf16 v[50:53], v[182:185], v[190:193], v[50:53]
	s_setprio 0
	s_setprio 1
	v_mfma_f32_16x16x32_bf16 v[96:99], v[134:137], v[118:121], v[98:101]
	v_mfma_f32_16x16x32_bf16 v[118:121], v[142:145], v[118:121], v[158:161]
	v_mfma_f32_16x16x32_bf16 v[86:89], v[134:137], v[102:105], v[88:91]
	v_mfma_f32_16x16x32_bf16 v[102:105], v[142:145], v[102:105], v[154:157]
	v_mfma_f32_16x16x32_bf16 v[96:99], v[138:141], v[122:125], v[96:99]
	v_mfma_f32_16x16x32_bf16 v[118:121], v[170:173], v[122:125], v[118:121]
	v_mfma_f32_16x16x32_bf16 v[122:125], v[134:137], v[194:197], v[126:129]
	v_mfma_f32_16x16x32_bf16 v[110:113], v[142:145], v[194:197], v[110:113]
	v_mfma_f32_16x16x32_bf16 v[62:65], v[134:137], v[186:189], v[62:65]
	v_mfma_f32_16x16x32_bf16 v[58:61], v[142:145], v[186:189], v[58:61]
	v_mfma_f32_16x16x32_bf16 v[86:89], v[138:141], v[202:205], v[86:89]
	v_mfma_f32_16x16x32_bf16 v[102:105], v[170:173], v[202:205], v[102:105]
	v_mfma_f32_16x16x32_bf16 v[122:125], v[138:141], v[198:201], v[122:125]
	v_mfma_f32_16x16x32_bf16 v[110:113], v[170:173], v[198:201], v[110:113]
	v_mfma_f32_16x16x32_bf16 v[62:65], v[138:141], v[190:193], v[62:65]
	v_mfma_f32_16x16x32_bf16 v[58:61], v[170:173], v[190:193], v[58:61]
	s_setprio 0
	s_barrier
	ds_read_b128 v[190:193], v245 offset:16384
	ds_read_b128 v[194:197], v245 offset:17408
	ds_read_b128 v[158:161], v245 offset:18432
	ds_read_b128 v[186:189], v245 offset:19456
	ds_read_b128 v[150:153], v245 offset:20480
	ds_read_b128 v[154:157], v245 offset:21504
	ds_read_b128 v[126:129], v245 offset:22528
	ds_read_b128 v[146:149], v245 offset:23552
	s_mov_b32 m0, s22
	s_nop 0
	global_load_lds_dwordx4 v251, s[84:85]
	s_add_u32 m0, m0, 0x2000
	s_nop 0
	global_load_lds_dwordx4 v247, s[84:85]
	s_add_u32 s14, s84, 0x580000
	s_addc_u32 s15, s85, 0
	s_mov_b32 m0, s23
	s_nop 0
	global_load_lds_dwordx4 v251, s[14:15]
	s_add_u32 m0, m0, 0x2000
	s_nop 0
	global_load_lds_dwordx4 v247, s[14:15]
	s_mov_b32 m0, s13
	s_nop 0
	global_load_lds_dwordx4 v250, s[86:87]
	s_add_u32 m0, m0, 0x2000
	s_nop 0
	global_load_lds_dwordx4 v246, s[86:87]
	s_waitcnt vmcnt(8)
.LBB0_563:
	s_waitcnt lgkmcnt(0)
	s_barrier
	s_setprio 1
	v_mfma_f32_16x16x32_bf16 v[38:41], v[130:133], v[190:193], v[38:41]
	v_mfma_f32_16x16x32_bf16 v[34:37], v[178:181], v[190:193], v[34:37]
	v_mfma_f32_16x16x32_bf16 v[26:29], v[130:133], v[158:161], v[26:29]
	v_mfma_f32_16x16x32_bf16 v[18:21], v[178:181], v[158:161], v[18:21]
	v_mfma_f32_16x16x32_bf16 v[6:9], v[130:133], v[150:153], v[6:9]
	v_mfma_f32_16x16x32_bf16 v[2:5], v[178:181], v[150:153], v[2:5]
	v_mfma_f32_16x16x32_bf16 v[106:109], v[130:133], v[126:129], v[106:109]
	v_mfma_f32_16x16x32_bf16 v[130:133], v[178:181], v[126:129], v[162:165]
	v_mfma_f32_16x16x32_bf16 v[38:41], v[174:177], v[194:197], v[38:41]
	v_mfma_f32_16x16x32_bf16 v[34:37], v[182:185], v[194:197], v[34:37]
	v_mfma_f32_16x16x32_bf16 v[26:29], v[174:177], v[186:189], v[26:29]
	v_mfma_f32_16x16x32_bf16 v[18:21], v[182:185], v[186:189], v[18:21]
	v_mfma_f32_16x16x32_bf16 v[6:9], v[174:177], v[154:157], v[6:9]
	v_mfma_f32_16x16x32_bf16 v[2:5], v[182:185], v[154:157], v[2:5]
	v_mfma_f32_16x16x32_bf16 v[106:109], v[174:177], v[146:149], v[106:109]
	v_mfma_f32_16x16x32_bf16 v[130:133], v[182:185], v[146:149], v[130:133]
	s_setprio 0
	s_setprio 1
	v_mfma_f32_16x16x32_bf16 v[46:49], v[134:137], v[190:193], v[46:49]
	v_mfma_f32_16x16x32_bf16 v[42:45], v[142:145], v[190:193], v[42:45]
	v_mfma_f32_16x16x32_bf16 v[30:33], v[134:137], v[158:161], v[30:33]
	v_mfma_f32_16x16x32_bf16 v[22:25], v[142:145], v[158:161], v[22:25]
	v_mfma_f32_16x16x32_bf16 v[14:17], v[134:137], v[150:153], v[14:17]
	v_mfma_f32_16x16x32_bf16 v[10:13], v[142:145], v[150:153], v[10:13]
	v_mfma_f32_16x16x32_bf16 v[114:117], v[134:137], v[126:129], v[114:117]
	v_mfma_f32_16x16x32_bf16 v[126:129], v[142:145], v[126:129], v[166:169]
	v_mfma_f32_16x16x32_bf16 v[46:49], v[138:141], v[194:197], v[46:49]
	v_mfma_f32_16x16x32_bf16 v[42:45], v[170:173], v[194:197], v[42:45]
	v_mfma_f32_16x16x32_bf16 v[30:33], v[138:141], v[186:189], v[30:33]
	v_mfma_f32_16x16x32_bf16 v[22:25], v[170:173], v[186:189], v[22:25]
	v_mfma_f32_16x16x32_bf16 v[14:17], v[138:141], v[154:157], v[14:17]
	v_mfma_f32_16x16x32_bf16 v[10:13], v[170:173], v[154:157], v[10:13]
	v_mfma_f32_16x16x32_bf16 v[114:117], v[138:141], v[146:149], v[114:117]
	v_mfma_f32_16x16x32_bf16 v[134:137], v[170:173], v[146:149], v[126:129]
	s_setprio 0
	s_barrier
	ds_read_b128 v[162:165], v235
	ds_read_b128 v[174:177], v235 offset:1024
	ds_read_b128 v[178:181], v235 offset:2048
	ds_read_b128 v[182:185], v235 offset:3072
	ds_read_b128 v[138:141], v248
	ds_read_b128 v[142:145], v248 offset:1024
	ds_read_b128 v[166:169], v248 offset:2048
	ds_read_b128 v[170:173], v248 offset:3072
	ds_read_b128 v[154:157], v245 offset:32768
	ds_read_b128 v[202:205], v245 offset:33792
	ds_read_b128 v[126:129], v245 offset:34816
	ds_read_b128 v[158:161], v245 offset:35840
	ds_read_b128 v[194:197], v245 offset:36864
	ds_read_b128 v[198:201], v245 offset:37888
	ds_read_b128 v[186:189], v245 offset:38912
	ds_read_b128 v[190:193], v245 offset:39936
	s_add_u32 s14, s86, 0x2000
	s_addc_u32 s15, s87, 0
	s_mov_b32 m0, s45
	s_nop 0
	global_load_lds_dwordx4 v250, s[14:15]
	s_add_u32 m0, m0, 0x2000
	s_nop 0
	global_load_lds_dwordx4 v246, s[14:15]
	s_waitcnt vmcnt(8)
	s_branch .LBB0_558
	s_nop 0
	s_nop 0
	s_nop 0
	s_nop 0
	s_nop 0
	s_nop 0
	s_nop 0
	s_nop 0
	s_nop 0
	s_nop 0
	s_nop 0
	s_nop 0
	s_nop 0

; #define PG8_STAGE(bufoff, gbase, voff) glds16s2((voff)[0], (voff)[1], (const void*)(gbase), ldsn + (unsigned)(bufoff))
; #define PG8_LDA(dst, b, h) do { _Pragma("unroll") for (int m = 0; m < 4; ++m) _Pragma("unroll") for (int k = 0; k < 2; ++k) dst[m][k] = *(const LAS bf16x8*)(lds + PG8_SA(b, h) + aoff + m * 2048 + k * 1024); } while (0)
; #define PG8_LDB(dst, b, h) do { _Pragma("unroll") for (int n = 0; n < 2; ++n) _Pragma("unroll") for (int k = 0; k < 2; ++k) dst[n][k] = *(const LAS bf16x8*)(lds + PG8_SB(b, h) + boff + n * 2048 + k * 1024); } while (0)
; #define PG8_MMA(ai, bj, At, Bt) do { __builtin_amdgcn_s_setprio(1); _Pragma("unroll") for (int m = 0; m < 4; ++m) _Pragma("unroll") for (int n = 0; n < 2; ++n) _Pragma("unroll") for (int k = 0; k < 2; ++k) \
;         acc[ai][bj][m][n] = __builtin_amdgcn_mfma_f32_16x16x32_bf16(Bt[n][k], At[m][k], acc[ai][bj][m][n], 0, 0, 0); __builtin_amdgcn_s_setprio(0); } while (0)
; #define PG8_WAIT_V(n) asm volatile("s_waitcnt vmcnt(" #n ")" ::: "memory")
; template <class Epi, bool ALIGN_EPI, bool EARLY_DRAIN = true, class Pre = NoPre>
; __device__ __forceinline__ void gemm_phase(LAS unsigned char* lds, const Gemm g, const StaticOrder& S, const Epi& E, int wv, const Pre& pre = Pre()) {
;     ...
;         for (int t = th; t < th + (Epi::MIDK ? nt / 2 : nt); t += 2) {
;             const bool last = (t == nt - 2);
;             const char* a1 = cA + (size_t)(t + 1) * kstep;
;             const char* a2 = last ? nA : cA + (size_t)(t + 2) * kstep; const char* b2 = last ? nB : cB + (size_t)(t + 2) * kstep;
;             const char* a3 = a2 + kstep; const char* b3 = b2 + kstep;
;             int lf_ = EARLY_DRAIN ? __builtin_amdgcn_readfirstlane(landed_flag) : landed_flag; if constexpr (EARLY_DRAIN) asm volatile("" : "+s"(lf_)); landed_flag = 0;
;             PG8_LDB(B0, 0, 0); PG8_LDB(B1, 0, 1); PG8_SCHED; PG8_LDA(At, 0, 0); PG8_STAGE(PG8_SA(1, 1), a1 + ahs, voffA);
;             if (!lf_) PG8_WAIT_V(8);
;             PG8_WAIT_L(0); PG8_BAR; PG8_MMA(0, 0, At, B0); PG8_MMA(0, 1, At, B1); PG8_BAR; PG8_SCHED;
;             PG8_LDA(At, 0, 1); PG8_STAGE(PG8_SB(0, 0), b2, voffB); PG8_STAGE(PG8_SB(0, 1), b2 + bhs, voffB); PG8_STAGE(PG8_SA(0, 0), a2, voffA);
;             if (!lf_) PG8_WAIT_V(8);
;             PG8_WAIT_L(0); PG8_BAR; PG8_MMA(1, 0, At, B0); PG8_MMA(1, 1, At, B1); PG8_BAR; PG8_SCHED;
.LBB0_690:
	v_add_u32_e32 v174, 0x10000, v201
	v_add_u32_e32 v190, 0x14000, v201
	ds_read_b128 v[146:149], v174
	ds_read_b128 v[158:161], v174 offset:1024
	ds_read_b128 v[166:169], v174 offset:2048
	ds_read_b128 v[174:177], v174 offset:3072
	ds_read_b128 v[178:181], v190
	ds_read_b128 v[182:185], v190 offset:1024
	ds_read_b128 v[186:189], v190 offset:2048
	ds_read_b128 v[190:193], v190 offset:3072
	s_cmp_eq_u32 s80, 40
	s_cselect_b32 s68, s30, s52
	s_cselect_b32 s69, s31, s53
	s_cselect_b32 s60, s34, s70
	s_cselect_b32 s61, s35, s71
	s_add_u32 s40, s68, 0x80
	s_addc_u32 s41, s69, 0
	ds_read_b128 v[194:197], v202
	ds_read_b128 v[204:207], v202 offset:1024
	ds_read_b128 v[208:211], v202 offset:2048
	ds_read_b128 v[212:215], v202 offset:3072
	ds_read_b128 v[216:219], v202 offset:4096
	ds_read_b128 v[220:223], v202 offset:5120
	ds_read_b128 v[224:227], v202 offset:6144
	ds_read_b128 v[228:231], v202 offset:7168
	s_mov_b32 m0, s27
	s_nop 0
	global_load_lds_dwordx4 v0, s[36:37]
	s_add_u32 m0, m0, 0x2000
	s_nop 0
	global_load_lds_dwordx4 v199, s[36:37]
	s_waitcnt vmcnt(8)
	s_waitcnt lgkmcnt(0)
	s_barrier
	s_setprio 1
	v_mfma_f32_16x16x32_bf16 v[170:173], v[146:149], v[194:197], v[170:173]
	v_mfma_f32_16x16x32_bf16 v[162:165], v[166:169], v[194:197], v[162:165]
	v_mfma_f32_16x16x32_bf16 v[142:145], v[146:149], v[208:211], v[142:145]
	v_mfma_f32_16x16x32_bf16 v[138:141], v[166:169], v[208:211], v[138:141]
	v_mfma_f32_16x16x32_bf16 v[126:129], v[146:149], v[216:219], v[126:129]
	v_mfma_f32_16x16x32_bf16 v[122:125], v[166:169], v[216:219], v[122:125]
	v_mfma_f32_16x16x32_bf16 v[102:105], v[146:149], v[224:227], v[102:105]
	v_mfma_f32_16x16x32_bf16 v[98:101], v[166:169], v[224:227], v[98:101]
	v_mfma_f32_16x16x32_bf16 v[170:173], v[158:161], v[204:207], v[170:173]
	v_mfma_f32_16x16x32_bf16 v[162:165], v[174:177], v[204:207], v[162:165]
	v_mfma_f32_16x16x32_bf16 v[142:145], v[158:161], v[212:215], v[142:145]
	v_mfma_f32_16x16x32_bf16 v[138:141], v[174:177], v[212:215], v[138:141]
	v_mfma_f32_16x16x32_bf16 v[126:129], v[158:161], v[220:223], v[126:129]
	v_mfma_f32_16x16x32_bf16 v[122:125], v[174:177], v[220:223], v[122:125]
	v_mfma_f32_16x16x32_bf16 v[102:105], v[158:161], v[228:231], v[102:105]
	v_mfma_f32_16x16x32_bf16 v[98:101], v[174:177], v[228:231], v[98:101]
	s_setprio 0
	s_setprio 1
	v_mfma_f32_16x16x32_bf16 v[154:157], v[178:181], v[194:197], v[154:157]
	v_mfma_f32_16x16x32_bf16 v[150:153], v[186:189], v[194:197], v[150:153]
	v_mfma_f32_16x16x32_bf16 v[134:137], v[178:181], v[208:211], v[134:137]
	v_mfma_f32_16x16x32_bf16 v[130:133], v[186:189], v[208:211], v[130:133]
	v_mfma_f32_16x16x32_bf16 v[114:117], v[178:181], v[216:219], v[114:117]
	v_mfma_f32_16x16x32_bf16 v[106:109], v[186:189], v[216:219], v[106:109]
	v_mfma_f32_16x16x32_bf16 v[86:89], v[178:181], v[224:227], v[86:89]
	v_mfma_f32_16x16x32_bf16 v[82:85], v[186:189], v[224:227], v[82:85]
	v_mfma_f32_16x16x32_bf16 v[154:157], v[182:185], v[204:207], v[154:157]
	v_mfma_f32_16x16x32_bf16 v[150:153], v[190:193], v[204:207], v[150:153]
	v_mfma_f32_16x16x32_bf16 v[134:137], v[182:185], v[212:215], v[134:137]
	v_mfma_f32_16x16x32_bf16 v[130:133], v[190:193], v[212:215], v[130:133]
	v_mfma_f32_16x16x32_bf16 v[114:117], v[182:185], v[220:223], v[114:117]
	v_mfma_f32_16x16x32_bf16 v[106:109], v[190:193], v[220:223], v[106:109]
	v_mfma_f32_16x16x32_bf16 v[86:89], v[182:185], v[228:231], v[86:89]
	v_mfma_f32_16x16x32_bf16 v[82:85], v[190:193], v[228:231], v[82:85]
	s_setprio 0
	s_barrier
	ds_read_b128 v[194:197], v202 offset:16384
	ds_read_b128 v[204:207], v202 offset:17408
	ds_read_b128 v[208:211], v202 offset:18432
	ds_read_b128 v[212:215], v202 offset:19456
	ds_read_b128 v[216:219], v202 offset:20480
	ds_read_b128 v[220:223], v202 offset:21504
	ds_read_b128 v[224:227], v202 offset:22528
	ds_read_b128 v[228:231], v202 offset:23552
	s_mov_b32 m0, s10
	s_nop 0
	global_load_lds_dwordx4 v198, s[60:61]
	s_add_u32 m0, m0, 0x2000
	s_nop 0
	global_load_lds_dwordx4 v200, s[60:61]
	s_add_u32 s14, s60, 0xb0000
	s_addc_u32 s15, s61, 0
	s_mov_b32 m0, s12
	s_nop 0
	global_load_lds_dwordx4 v198, s[14:15]
	s_add_u32 m0, m0, 0x2000
	s_nop 0
	global_load_lds_dwordx4 v200, s[14:15]
	s_nop 0
	s_mov_b32 m0, s5
	s_nop 0
	global_load_lds_dwordx4 v0, s[68:69]
	s_add_u32 m0, m0, 0x2000
	s_nop 0
	global_load_lds_dwordx4 v199, s[68:69]
	s_waitcnt vmcnt(8)
	s_waitcnt lgkmcnt(0)
	s_barrier
	s_setprio 1
	v_mfma_f32_16x16x32_bf16 v[74:77], v[146:149], v[194:197], v[74:77]
	v_mfma_f32_16x16x32_bf16 v[70:73], v[166:169], v[194:197], v[70:73]
	v_mfma_f32_16x16x32_bf16 v[50:53], v[146:149], v[208:211], v[50:53]
	v_mfma_f32_16x16x32_bf16 v[46:49], v[166:169], v[208:211], v[46:49]
	v_mfma_f32_16x16x32_bf16 v[30:33], v[146:149], v[216:219], v[30:33]
	v_mfma_f32_16x16x32_bf16 v[26:29], v[166:169], v[216:219], v[26:29]
	v_mfma_f32_16x16x32_bf16 v[14:17], v[146:149], v[224:227], v[14:17]
	v_mfma_f32_16x16x32_bf16 v[10:13], v[166:169], v[224:227], v[10:13]
	v_mfma_f32_16x16x32_bf16 v[74:77], v[158:161], v[204:207], v[74:77]
	v_mfma_f32_16x16x32_bf16 v[70:73], v[174:177], v[204:207], v[70:73]
	v_mfma_f32_16x16x32_bf16 v[50:53], v[158:161], v[212:215], v[50:53]
	v_mfma_f32_16x16x32_bf16 v[46:49], v[174:177], v[212:215], v[46:49]
	v_mfma_f32_16x16x32_bf16 v[30:33], v[158:161], v[220:223], v[30:33]
	v_mfma_f32_16x16x32_bf16 v[26:29], v[174:177], v[220:223], v[26:29]
	v_mfma_f32_16x16x32_bf16 v[14:17], v[158:161], v[228:231], v[14:17]
	v_mfma_f32_16x16x32_bf16 v[10:13], v[174:177], v[228:231], v[10:13]
	s_setprio 0
	s_setprio 1
	v_mfma_f32_16x16x32_bf16 v[62:65], v[178:181], v[194:197], v[62:65]
	v_mfma_f32_16x16x32_bf16 v[58:61], v[186:189], v[194:197], v[58:61]
	v_mfma_f32_16x16x32_bf16 v[38:41], v[178:181], v[208:211], v[38:41]
	v_mfma_f32_16x16x32_bf16 v[34:37], v[186:189], v[208:211], v[34:37]
	v_mfma_f32_16x16x32_bf16 v[22:25], v[178:181], v[216:219], v[22:25]
	v_mfma_f32_16x16x32_bf16 v[18:21], v[186:189], v[216:219], v[18:21]
	v_mfma_f32_16x16x32_bf16 v[6:9], v[178:181], v[224:227], v[6:9]
	v_mfma_f32_16x16x32_bf16 v[2:5], v[186:189], v[224:227], v[2:5]
	v_mfma_f32_16x16x32_bf16 v[62:65], v[182:185], v[204:207], v[62:65]
	v_mfma_f32_16x16x32_bf16 v[58:61], v[190:193], v[204:207], v[58:61]
	v_mfma_f32_16x16x32_bf16 v[38:41], v[182:185], v[212:215], v[38:41]
	v_mfma_f32_16x16x32_bf16 v[34:37], v[190:193], v[212:215], v[34:37]
	v_mfma_f32_16x16x32_bf16 v[22:25], v[182:185], v[220:223], v[22:25]
	v_mfma_f32_16x16x32_bf16 v[18:21], v[190:193], v[220:223], v[18:21]
	v_mfma_f32_16x16x32_bf16 v[6:9], v[182:185], v[228:231], v[6:9]
	v_mfma_f32_16x16x32_bf16 v[2:5], v[190:193], v[228:231], v[2:5]
	s_setprio 0
	s_barrier
; #define PG8_STAGE(bufoff, gbase, voff) glds16s2((voff)[0], (voff)[1], (const void*)(gbase), ldsn + (unsigned)(bufoff))
; #define PG8_LDA(dst, b, h) do { _Pragma("unroll") for (int m = 0; m < 4; ++m) _Pragma("unroll") for (int k = 0; k < 2; ++k) dst[m][k] = *(const LAS bf16x8*)(lds + PG8_SA(b, h) + aoff + m * 2048 + k * 1024); } while (0)
; #define PG8_LDB(dst, b, h) do { _Pragma("unroll") for (int n = 0; n < 2; ++n) _Pragma("unroll") for (int k = 0; k < 2; ++k) dst[n][k] = *(const LAS bf16x8*)(lds + PG8_SB(b, h) + boff + n * 2048 + k * 1024); } while (0)
; #define PG8_MMA(ai, bj, At, Bt) do { __builtin_amdgcn_s_setprio(1); _Pragma("unroll") for (int m = 0; m < 4; ++m) _Pragma("unroll") for (int n = 0; n < 2; ++n) _Pragma("unroll") for (int k = 0; k < 2; ++k) \
;         acc[ai][bj][m][n] = __builtin_amdgcn_mfma_f32_16x16x32_bf16(Bt[n][k], At[m][k], acc[ai][bj][m][n], 0, 0, 0); __builtin_amdgcn_s_setprio(0); } while (0)
; #define PG8_WAIT_V(n) asm volatile("s_waitcnt vmcnt(" #n ")" ::: "memory")
; #define PG8_WAIT_L(n) asm volatile("s_waitcnt lgkmcnt(" #n ")" ::: "memory")
; #define PG8_BAR __builtin_amdgcn_s_barrier()
; #define PG8_SCHED __builtin_amdgcn_sched_barrier(0)
; template <class Epi, bool ALIGN_EPI, bool EARLY_DRAIN = true, class Pre = NoPre>
; __device__ __forceinline__ void gemm_phase(LAS unsigned char* lds, const Gemm g, const StaticOrder& S, const Epi& E, int wv, const Pre& pre = Pre()) {
;     ...
;             PG8_LDB(B0, 1, 0); PG8_LDB(B1, 1, 1); PG8_SCHED; PG8_LDA(At, 1, 0); PG8_STAGE(PG8_SA(0, 1), a2 + ahs, voffA);
;             if (!lf_) PG8_WAIT_V(8);
;             PG8_WAIT_L(0); PG8_BAR; PG8_MMA(0, 0, At, B0); PG8_MMA(0, 1, At, B1); PG8_BAR; PG8_SCHED;
;             PG8_LDA(At, 1, 1); PG8_STAGE(PG8_SB(1, 0), b3, voffB); PG8_STAGE(PG8_SB(1, 1), b3 + bhs, voffB); PG8_STAGE(PG8_SA(1, 0), a3, voffA);
;             PG8_WAIT_V(8); PG8_WAIT_L(0); PG8_BAR; PG8_MMA(1, 0, At, B0); PG8_MMA(1, 1, At, B1); PG8_BAR; PG8_SCHED;
;         }
;         }
;         if constexpr (ALIGN_EPI) { if (wr == 0) PG8_BAR; }
	v_add_u32_e32 v174, 0x18000, v201
	v_add_u32_e32 v190, 0x1c000, v201
	ds_read_b128 v[146:149], v174
	ds_read_b128 v[158:161], v174 offset:1024
	ds_read_b128 v[166:169], v174 offset:2048
	ds_read_b128 v[174:177], v174 offset:3072
	ds_read_b128 v[178:181], v190
	ds_read_b128 v[182:185], v190 offset:1024
	ds_read_b128 v[186:189], v190 offset:2048
	ds_read_b128 v[190:193], v190 offset:3072
	ds_read_b128 v[194:197], v202 offset:32768
	ds_read_b128 v[204:207], v202 offset:33792
	ds_read_b128 v[208:211], v202 offset:34816
	ds_read_b128 v[212:215], v202 offset:35840
	ds_read_b128 v[216:219], v202 offset:36864
	ds_read_b128 v[220:223], v202 offset:37888
	ds_read_b128 v[224:227], v202 offset:38912
	ds_read_b128 v[228:231], v202 offset:39936
	s_add_u32 s14, s68, 0xb0000
	s_addc_u32 s15, s69, 0
	s_mov_b32 m0, s13
	s_nop 0
	global_load_lds_dwordx4 v0, s[14:15]
	s_add_u32 m0, m0, 0x2000
	s_nop 0
	global_load_lds_dwordx4 v199, s[14:15]
	s_waitcnt vmcnt(8)
	s_waitcnt lgkmcnt(0)
	s_barrier
	s_setprio 1
	v_mfma_f32_16x16x32_bf16 v[170:173], v[146:149], v[194:197], v[170:173]
	v_mfma_f32_16x16x32_bf16 v[162:165], v[166:169], v[194:197], v[162:165]
	v_mfma_f32_16x16x32_bf16 v[142:145], v[146:149], v[208:211], v[142:145]
	v_mfma_f32_16x16x32_bf16 v[138:141], v[166:169], v[208:211], v[138:141]
	v_mfma_f32_16x16x32_bf16 v[126:129], v[146:149], v[216:219], v[126:129]
	v_mfma_f32_16x16x32_bf16 v[122:125], v[166:169], v[216:219], v[122:125]
	v_mfma_f32_16x16x32_bf16 v[102:105], v[146:149], v[224:227], v[102:105]
	v_mfma_f32_16x16x32_bf16 v[98:101], v[166:169], v[224:227], v[98:101]
	v_mfma_f32_16x16x32_bf16 v[170:173], v[158:161], v[204:207], v[170:173]
	v_mfma_f32_16x16x32_bf16 v[162:165], v[174:177], v[204:207], v[162:165]
	v_mfma_f32_16x16x32_bf16 v[142:145], v[158:161], v[212:215], v[142:145]
	v_mfma_f32_16x16x32_bf16 v[138:141], v[174:177], v[212:215], v[138:141]
	v_mfma_f32_16x16x32_bf16 v[126:129], v[158:161], v[220:223], v[126:129]
	v_mfma_f32_16x16x32_bf16 v[122:125], v[174:177], v[220:223], v[122:125]
	v_mfma_f32_16x16x32_bf16 v[102:105], v[158:161], v[228:231], v[102:105]
	v_mfma_f32_16x16x32_bf16 v[98:101], v[174:177], v[228:231], v[98:101]
	s_setprio 0
	s_setprio 1
	v_mfma_f32_16x16x32_bf16 v[154:157], v[178:181], v[194:197], v[154:157]
	v_mfma_f32_16x16x32_bf16 v[150:153], v[186:189], v[194:197], v[150:153]
	v_mfma_f32_16x16x32_bf16 v[134:137], v[178:181], v[208:211], v[134:137]
	v_mfma_f32_16x16x32_bf16 v[130:133], v[186:189], v[208:211], v[130:133]
	v_mfma_f32_16x16x32_bf16 v[114:117], v[178:181], v[216:219], v[114:117]
	v_mfma_f32_16x16x32_bf16 v[106:109], v[186:189], v[216:219], v[106:109]
	v_mfma_f32_16x16x32_bf16 v[86:89], v[178:181], v[224:227], v[86:89]
	v_mfma_f32_16x16x32_bf16 v[82:85], v[186:189], v[224:227], v[82:85]
	v_mfma_f32_16x16x32_bf16 v[154:157], v[182:185], v[204:207], v[154:157]
	v_mfma_f32_16x16x32_bf16 v[150:153], v[190:193], v[204:207], v[150:153]
	v_mfma_f32_16x16x32_bf16 v[134:137], v[182:185], v[212:215], v[134:137]
	v_mfma_f32_16x16x32_bf16 v[130:133], v[190:193], v[212:215], v[130:133]
	v_mfma_f32_16x16x32_bf16 v[114:117], v[182:185], v[220:223], v[114:117]
	v_mfma_f32_16x16x32_bf16 v[106:109], v[190:193], v[220:223], v[106:109]
	v_mfma_f32_16x16x32_bf16 v[86:89], v[182:185], v[228:231], v[86:89]
	v_mfma_f32_16x16x32_bf16 v[82:85], v[190:193], v[228:231], v[82:85]
	s_setprio 0
	s_barrier
	ds_read_b128 v[194:197], v202 offset:49152
	ds_read_b128 v[204:207], v202 offset:50176
	ds_read_b128 v[208:211], v202 offset:51200
	ds_read_b128 v[212:215], v202 offset:52224
	ds_read_b128 v[216:219], v202 offset:53248
	ds_read_b128 v[220:223], v202 offset:54272
	ds_read_b128 v[224:227], v202 offset:55296
	ds_read_b128 v[228:231], v202 offset:56320
	s_add_u32 s14, s60, 0x80
	s_addc_u32 s15, s61, 0
	s_mov_b32 m0, s24
	s_nop 0
	global_load_lds_dwordx4 v198, s[14:15]
	s_add_u32 m0, m0, 0x2000
	s_nop 0
	global_load_lds_dwordx4 v200, s[14:15]
	s_add_u32 s14, s60, 0xb0080
	s_addc_u32 s15, s61, 0
	s_mov_b32 m0, s26
	s_nop 0
	global_load_lds_dwordx4 v198, s[14:15]
	s_add_u32 m0, m0, 0x2000
	s_nop 0
	global_load_lds_dwordx4 v200, s[14:15]
	s_nop 0
	s_mov_b32 m0, s25
	s_nop 0
	global_load_lds_dwordx4 v0, s[40:41]
	s_add_u32 m0, m0, 0x2000
	s_nop 0
	global_load_lds_dwordx4 v199, s[40:41]
	s_waitcnt vmcnt(8)
	s_waitcnt lgkmcnt(0)
	s_barrier
	s_setprio 1
	v_mfma_f32_16x16x32_bf16 v[74:77], v[146:149], v[194:197], v[74:77]
	v_mfma_f32_16x16x32_bf16 v[70:73], v[166:169], v[194:197], v[70:73]
	v_mfma_f32_16x16x32_bf16 v[50:53], v[146:149], v[208:211], v[50:53]
	v_mfma_f32_16x16x32_bf16 v[46:49], v[166:169], v[208:211], v[46:49]
	v_mfma_f32_16x16x32_bf16 v[30:33], v[146:149], v[216:219], v[30:33]
	v_mfma_f32_16x16x32_bf16 v[26:29], v[166:169], v[216:219], v[26:29]
	v_mfma_f32_16x16x32_bf16 v[14:17], v[146:149], v[224:227], v[14:17]
	v_mfma_f32_16x16x32_bf16 v[10:13], v[166:169], v[224:227], v[10:13]
	v_mfma_f32_16x16x32_bf16 v[74:77], v[158:161], v[204:207], v[74:77]
	v_mfma_f32_16x16x32_bf16 v[70:73], v[174:177], v[204:207], v[70:73]
	v_mfma_f32_16x16x32_bf16 v[50:53], v[158:161], v[212:215], v[50:53]
	v_mfma_f32_16x16x32_bf16 v[46:49], v[174:177], v[212:215], v[46:49]
	v_mfma_f32_16x16x32_bf16 v[30:33], v[158:161], v[220:223], v[30:33]
	v_mfma_f32_16x16x32_bf16 v[26:29], v[174:177], v[220:223], v[26:29]
	v_mfma_f32_16x16x32_bf16 v[14:17], v[158:161], v[228:231], v[14:17]
	v_mfma_f32_16x16x32_bf16 v[10:13], v[174:177], v[228:231], v[10:13]
	s_setprio 0
	s_setprio 1
	v_mfma_f32_16x16x32_bf16 v[62:65], v[178:181], v[194:197], v[62:65]
	v_mfma_f32_16x16x32_bf16 v[58:61], v[186:189], v[194:197], v[58:61]
	v_mfma_f32_16x16x32_bf16 v[38:41], v[178:181], v[208:211], v[38:41]
	v_mfma_f32_16x16x32_bf16 v[34:37], v[186:189], v[208:211], v[34:37]
	v_mfma_f32_16x16x32_bf16 v[22:25], v[178:181], v[216:219], v[22:25]
	v_mfma_f32_16x16x32_bf16 v[18:21], v[186:189], v[216:219], v[18:21]
	v_mfma_f32_16x16x32_bf16 v[6:9], v[178:181], v[224:227], v[6:9]
	v_mfma_f32_16x16x32_bf16 v[2:5], v[186:189], v[224:227], v[2:5]
	v_mfma_f32_16x16x32_bf16 v[62:65], v[182:185], v[204:207], v[62:65]
	v_mfma_f32_16x16x32_bf16 v[58:61], v[190:193], v[204:207], v[58:61]
	v_mfma_f32_16x16x32_bf16 v[38:41], v[182:185], v[212:215], v[38:41]
	v_mfma_f32_16x16x32_bf16 v[34:37], v[190:193], v[212:215], v[34:37]
	v_mfma_f32_16x16x32_bf16 v[22:25], v[182:185], v[220:223], v[22:25]
	v_mfma_f32_16x16x32_bf16 v[18:21], v[190:193], v[220:223], v[18:21]
	v_mfma_f32_16x16x32_bf16 v[6:9], v[182:185], v[228:231], v[6:9]
	v_mfma_f32_16x16x32_bf16 v[2:5], v[190:193], v[228:231], v[2:5]
	s_setprio 0
	s_barrier
	s_add_i32 s80, s80, 2
	s_add_u32 s52, s52, 0x100
	s_addc_u32 s53, s53, 0
	s_add_u32 s70, s70, 0x100
	s_addc_u32 s71, s71, 0
	s_add_u32 s36, s36, 0x100
	s_addc_u32 s37, s37, 0
	s_cmp_gt_u32 s80, 41
	s_cbranch_scc0 .LBB0_690
	s_and_b64 vcc, exec, s[18:19]
	s_cbranch_vccz .LBB0_693
	s_barrier

; #define PG8_STAGE(bufoff, gbase, voff) glds16s2((voff)[0], (voff)[1], (const void*)(gbase), ldsn + (unsigned)(bufoff))
; #define PG8_LDA(dst, b, h) do { _Pragma("unroll") for (int m = 0; m < 4; ++m) _Pragma("unroll") for (int k = 0; k < 2; ++k) dst[m][k] = *(const LAS bf16x8*)(lds + PG8_SA(b, h) + aoff + m * 2048 + k * 1024); } while (0)
; #define PG8_LDB(dst, b, h) do { _Pragma("unroll") for (int n = 0; n < 2; ++n) _Pragma("unroll") for (int k = 0; k < 2; ++k) dst[n][k] = *(const LAS bf16x8*)(lds + PG8_SB(b, h) + boff + n * 2048 + k * 1024); } while (0)
; #define PG8_MMA(ai, bj, At, Bt) do { __builtin_amdgcn_s_setprio(1); _Pragma("unroll") for (int m = 0; m < 4; ++m) _Pragma("unroll") for (int n = 0; n < 2; ++n) _Pragma("unroll") for (int k = 0; k < 2; ++k) \
;         acc[ai][bj][m][n] = __builtin_amdgcn_mfma_f32_16x16x32_bf16(Bt[n][k], At[m][k], acc[ai][bj][m][n], 0, 0, 0); __builtin_amdgcn_s_setprio(0); } while (0)
; #define PG8_BAR __builtin_amdgcn_s_barrier()
; template <class Epi, bool ALIGN_EPI, bool EARLY_DRAIN = true, class Pre = NoPre>
; __device__ __forceinline__ void gemm_phase(LAS unsigned char* lds, const Gemm g, const StaticOrder& S, const Epi& E, int wv, const Pre& pre = Pre()) {
;     ...
;             const bool last = (t == nt - 2);
;             const char* a1 = cA + (size_t)(t + 1) * kstep;
;             const char* a2 = last ? nA : cA + (size_t)(t + 2) * kstep; const char* b2 = last ? nB : cB + (size_t)(t + 2) * kstep;
;             const char* a3 = a2 + kstep; const char* b3 = b2 + kstep;
;             int lf_ = EARLY_DRAIN ? __builtin_amdgcn_readfirstlane(landed_flag) : landed_flag; if constexpr (EARLY_DRAIN) asm volatile("" : "+s"(lf_)); landed_flag = 0;
;             PG8_LDB(B0, 0, 0); PG8_LDB(B1, 0, 1); PG8_SCHED; PG8_LDA(At, 0, 0); PG8_STAGE(PG8_SA(1, 1), a1 + ahs, voffA);
;             if (!lf_) PG8_WAIT_V(8);
;             PG8_WAIT_L(0); PG8_BAR; PG8_MMA(0, 0, At, B0); PG8_MMA(0, 1, At, B1); PG8_BAR; PG8_SCHED;
;             PG8_LDA(At, 0, 1); PG8_STAGE(PG8_SB(0, 0), b2, voffB); PG8_STAGE(PG8_SB(0, 1), b2 + bhs, voffB); PG8_STAGE(PG8_SA(0, 0), a2, voffA);
;             if (!lf_) PG8_WAIT_V(8);
;             PG8_WAIT_L(0); PG8_BAR; PG8_MMA(1, 0, At, B0); PG8_MMA(1, 1, At, B1); PG8_BAR; PG8_SCHED;
;             PG8_LDB(B0, 1, 0); PG8_LDB(B1, 1, 1); PG8_SCHED; PG8_LDA(At, 1, 0); PG8_STAGE(PG8_SA(0, 1), a2 + ahs, voffA);
.LBB0_729:
	s_add_u32 s14, s70, 0x100
	s_waitcnt lgkmcnt(0)
	s_addc_u32 s15, s71, 0
	s_add_u32 s24, s68, 0x100
	s_addc_u32 s25, s69, 0
	s_barrier
	s_setprio 1
	v_mfma_f32_16x16x32_bf16 v[2:5], v[82:85], v[38:41], 0
	v_mfma_f32_16x16x32_bf16 v[6:9], v[90:93], v[38:41], 0
	v_mfma_f32_16x16x32_bf16 v[10:13], v[82:85], v[46:49], 0
	v_mfma_f32_16x16x32_bf16 v[14:17], v[90:93], v[46:49], 0
	v_mfma_f32_16x16x32_bf16 v[18:21], v[82:85], v[54:57], 0
	v_mfma_f32_16x16x32_bf16 v[22:25], v[90:93], v[54:57], 0
	v_mfma_f32_16x16x32_bf16 v[26:29], v[82:85], v[62:65], 0
	v_mfma_f32_16x16x32_bf16 v[30:33], v[90:93], v[62:65], 0
	v_mfma_f32_16x16x32_bf16 v[2:5], v[86:89], v[42:45], v[2:5]
	v_mfma_f32_16x16x32_bf16 v[6:9], v[94:97], v[42:45], v[6:9]
	v_mfma_f32_16x16x32_bf16 v[10:13], v[86:89], v[50:53], v[10:13]
	v_mfma_f32_16x16x32_bf16 v[14:17], v[94:97], v[50:53], v[14:17]
	v_mfma_f32_16x16x32_bf16 v[18:21], v[86:89], v[58:61], v[18:21]
	v_mfma_f32_16x16x32_bf16 v[22:25], v[94:97], v[58:61], v[22:25]
	v_mfma_f32_16x16x32_bf16 v[26:29], v[86:89], v[98:101], v[26:29]
	v_mfma_f32_16x16x32_bf16 v[30:33], v[94:97], v[98:101], v[30:33]
	s_setprio 0
	s_setprio 1
	v_mfma_f32_16x16x32_bf16 v[34:37], v[66:69], v[38:41], 0
	v_mfma_f32_16x16x32_bf16 v[38:41], v[74:77], v[38:41], 0
	v_mfma_f32_16x16x32_bf16 v[34:37], v[70:73], v[42:45], v[34:37]
	v_mfma_f32_16x16x32_bf16 v[38:41], v[78:81], v[42:45], v[38:41]
	v_mfma_f32_16x16x32_bf16 v[42:45], v[66:69], v[46:49], 0
	v_mfma_f32_16x16x32_bf16 v[46:49], v[74:77], v[46:49], 0
	v_mfma_f32_16x16x32_bf16 v[42:45], v[70:73], v[50:53], v[42:45]
	v_mfma_f32_16x16x32_bf16 v[46:49], v[78:81], v[50:53], v[46:49]
	v_mfma_f32_16x16x32_bf16 v[50:53], v[66:69], v[54:57], 0
	v_mfma_f32_16x16x32_bf16 v[54:57], v[74:77], v[54:57], 0
	v_mfma_f32_16x16x32_bf16 v[50:53], v[70:73], v[58:61], v[50:53]
	v_mfma_f32_16x16x32_bf16 v[54:57], v[78:81], v[58:61], v[54:57]
	v_mfma_f32_16x16x32_bf16 v[58:61], v[66:69], v[62:65], 0
	v_mfma_f32_16x16x32_bf16 v[62:65], v[74:77], v[62:65], 0
	v_mfma_f32_16x16x32_bf16 v[58:61], v[70:73], v[98:101], v[58:61]
	v_mfma_f32_16x16x32_bf16 v[62:65], v[78:81], v[98:101], v[62:65]
	s_setprio 0
	s_barrier
	ds_read_b128 v[154:157], v250 offset:16384
	ds_read_b128 v[162:165], v250 offset:17408
	ds_read_b128 v[130:133], v250 offset:18432
	ds_read_b128 v[146:149], v250 offset:19456
	ds_read_b128 v[110:113], v250 offset:20480
	ds_read_b128 v[118:121], v250 offset:21504
	ds_read_b128 v[102:105], v250 offset:22528
	ds_read_b128 v[106:109], v250 offset:23552
	s_mov_b32 m0, s12
	s_nop 0
	global_load_lds_dwordx4 v230, s[24:25]
	s_add_u32 m0, m0, 0x2000
	s_nop 0
	global_load_lds_dwordx4 v232, s[24:25]
	s_add_u32 s24, s68, 0xb0100
	s_addc_u32 s25, s69, 0
	s_mov_b32 m0, s13
	s_nop 0
	global_load_lds_dwordx4 v230, s[24:25]
	s_add_u32 m0, m0, 0x2000
	s_nop 0
	global_load_lds_dwordx4 v232, s[24:25]
	v_cndmask_b32_e64 v98, 0, 1, s[84:85]
	s_mov_b32 m0, s10
	s_nop 0
	global_load_lds_dwordx4 v0, s[14:15]
	s_add_u32 m0, m0, 0x2000
	s_nop 0
	global_load_lds_dwordx4 v231, s[14:15]
	v_cmp_ne_u32_e64 s[38:39], 1, v98
	s_andn2_b64 vcc, exec, s[84:85]
	s_cbranch_vccnz .LBB0_731
	s_waitcnt vmcnt(8)
.LBB0_731:
	s_waitcnt lgkmcnt(0)
	s_barrier
	s_setprio 1
	v_mfma_f32_16x16x32_bf16 v[98:101], v[82:85], v[154:157], 0
	v_mfma_f32_16x16x32_bf16 v[122:125], v[82:85], v[130:133], 0
	v_mfma_f32_16x16x32_bf16 v[134:137], v[82:85], v[110:113], 0
	v_mfma_f32_16x16x32_bf16 v[82:85], v[82:85], v[102:105], 0
	v_mfma_f32_16x16x32_bf16 v[114:117], v[90:93], v[154:157], 0
	v_mfma_f32_16x16x32_bf16 v[126:129], v[90:93], v[130:133], 0
	v_mfma_f32_16x16x32_bf16 v[138:141], v[90:93], v[110:113], 0
	v_mfma_f32_16x16x32_bf16 v[142:145], v[86:89], v[106:109], v[82:85]
	v_mfma_f32_16x16x32_bf16 v[82:85], v[90:93], v[102:105], 0
	v_mfma_f32_16x16x32_bf16 v[98:101], v[86:89], v[162:165], v[98:101]
	v_mfma_f32_16x16x32_bf16 v[114:117], v[94:97], v[162:165], v[114:117]
	v_mfma_f32_16x16x32_bf16 v[122:125], v[86:89], v[146:149], v[122:125]
	v_mfma_f32_16x16x32_bf16 v[126:129], v[94:97], v[146:149], v[126:129]
	v_mfma_f32_16x16x32_bf16 v[134:137], v[86:89], v[118:121], v[134:137]
	v_mfma_f32_16x16x32_bf16 v[138:141], v[94:97], v[118:121], v[138:141]
	v_mfma_f32_16x16x32_bf16 v[150:153], v[94:97], v[106:109], v[82:85]
	s_setprio 0
	s_setprio 1
	v_mfma_f32_16x16x32_bf16 v[82:85], v[66:69], v[154:157], 0
	v_mfma_f32_16x16x32_bf16 v[158:161], v[70:73], v[162:165], v[82:85]
	v_mfma_f32_16x16x32_bf16 v[82:85], v[74:77], v[154:157], 0
	v_mfma_f32_16x16x32_bf16 v[166:169], v[78:81], v[162:165], v[82:85]
	v_mfma_f32_16x16x32_bf16 v[82:85], v[66:69], v[130:133], 0
	v_mfma_f32_16x16x32_bf16 v[170:173], v[70:73], v[146:149], v[82:85]
	v_mfma_f32_16x16x32_bf16 v[82:85], v[74:77], v[130:133], 0
	v_mfma_f32_16x16x32_bf16 v[174:177], v[78:81], v[146:149], v[82:85]
	v_mfma_f32_16x16x32_bf16 v[82:85], v[66:69], v[110:113], 0
	v_mfma_f32_16x16x32_bf16 v[66:69], v[66:69], v[102:105], 0
	v_mfma_f32_16x16x32_bf16 v[178:181], v[70:73], v[118:121], v[82:85]
	v_mfma_f32_16x16x32_bf16 v[82:85], v[74:77], v[110:113], 0
	v_mfma_f32_16x16x32_bf16 v[186:189], v[70:73], v[106:109], v[66:69]
	v_mfma_f32_16x16x32_bf16 v[66:69], v[74:77], v[102:105], 0
	v_mfma_f32_16x16x32_bf16 v[182:185], v[78:81], v[118:121], v[82:85]
	v_mfma_f32_16x16x32_bf16 v[190:193], v[78:81], v[106:109], v[66:69]
	s_setprio 0
	s_barrier
	v_add_u32_e32 v244, 0x18000, v233
	v_add_u32_e32 v245, 0x1c000, v233
	ds_read_b128 v[210:213], v244
	ds_read_b128 v[214:217], v244 offset:1024
	ds_read_b128 v[218:221], v244 offset:2048
	ds_read_b128 v[222:225], v244 offset:3072
	ds_read_b128 v[194:197], v245
	ds_read_b128 v[198:201], v245 offset:1024
	ds_read_b128 v[202:205], v245 offset:2048
	ds_read_b128 v[206:209], v245 offset:3072
	ds_read_b128 v[106:109], v250 offset:32768
	ds_read_b128 v[130:133], v250 offset:33792
	ds_read_b128 v[86:89], v250 offset:34816
	ds_read_b128 v[102:105], v250 offset:35840
	ds_read_b128 v[70:73], v250 offset:36864
	ds_read_b128 v[82:85], v250 offset:37888
	ds_read_b128 v[66:69], v250 offset:38912
	ds_read_b128 v[226:229], v250 offset:39936
	s_add_u32 s14, s70, 0xb0100
	s_addc_u32 s15, s71, 0
	s_mov_b32 m0, s99
	s_nop 0
	global_load_lds_dwordx4 v0, s[14:15]
	s_add_u32 m0, m0, 0x2000
	s_nop 0
	global_load_lds_dwordx4 v231, s[14:15]
	s_and_b64 vcc, exec, s[38:39]
	s_cbranch_vccnz .LBB0_733
	s_waitcnt vmcnt(8)
; #define PG8_WAIT_V(n) asm volatile("s_waitcnt vmcnt(" #n ")" ::: "memory")
; template <class Epi, bool ALIGN_EPI, bool EARLY_DRAIN = true, class Pre = NoPre>
; __device__ __forceinline__ void gemm_phase(LAS unsigned char* lds, const Gemm g, const StaticOrder& S, const Epi& E, int wv, const Pre& pre = Pre()) {
;     ...
;         const char* nA = has_next ? g.A + (size_t)nxt.pm * g.a_tstep + (size_t)(nxt.pm >> 6) * g.a_pad : cA; const char* nB = has_next ? g.Bt + (size_t)nxt.pn * g.b_tstep : cB;
;         int landed_flag = fresh ? 1 : 0;
;         typename Epi::PF pf;
;         if constexpr (Epi::PREF) { int pt_ = lane_now(); asm volatile("" : "+v"(pt_)); E.prefetch(pf, cur, wr, wc, pt_ & 15, pt_ >> 4); }
;         for (int th = 0; th < nt; th += (Epi::MIDK ? nt / 2 : nt)) {
;         if constexpr (Epi::MIDK) { if (th) E.midk(acc, ui, wr, fr); }
;         for (int t = th; t < th + (Epi::MIDK ? nt / 2 : nt); t += 2) {
;             const bool last = (t == nt - 2);
;             const char* a1 = cA + (size_t)(t + 1) * kstep;
;             const char* a2 = last ? nA : cA + (size_t)(t + 2) * kstep; const char* b2 = last ? nB : cB + (size_t)(t + 2) * kstep;
;             const char* a3 = a2 + kstep; const char* b3 = b2 + kstep;
;             int lf_ = EARLY_DRAIN ? __builtin_amdgcn_readfirstlane(landed_flag) : landed_flag; if constexpr (EARLY_DRAIN) asm volatile("" : "+s"(lf_)); landed_flag = 0;
;             PG8_LDB(B0, 0, 0); PG8_LDB(B1, 0, 1); PG8_SCHED; PG8_LDA(At, 0, 0); PG8_STAGE(PG8_SA(1, 1), a1 + ahs, voffA);
;             if (!lf_) PG8_WAIT_V(8);
;             PG8_WAIT_L(0); PG8_BAR; PG8_MMA(0, 0, At, B0); PG8_MMA(0, 1, At, B1); PG8_BAR; PG8_SCHED;
;             PG8_LDA(At, 0, 1); PG8_STAGE(PG8_SB(0, 0), b2, voffB); PG8_STAGE(PG8_SB(0, 1), b2 + bhs, voffB); PG8_STAGE(PG8_SA(0, 0), a2, voffA);
;             if (!lf_) PG8_WAIT_V(8);
;             PG8_WAIT_L(0); PG8_BAR; PG8_MMA(1, 0, At, B0); PG8_MMA(1, 1, At, B1); PG8_BAR; PG8_SCHED;
;             PG8_LDB(B0, 1, 0); PG8_LDB(B1, 1, 1); PG8_SCHED; PG8_LDA(At, 1, 0); PG8_STAGE(PG8_SA(0, 1), a2 + ahs, voffA);
;             if (!lf_) PG8_WAIT_V(8);
;             PG8_WAIT_L(0); PG8_BAR; PG8_MMA(0, 0, At, B0); PG8_MMA(0, 1, At, B1); PG8_BAR; PG8_SCHED;
;             PG8_LDA(At, 1, 1); PG8_STAGE(PG8_SB(1, 0), b3, voffB); PG8_STAGE(PG8_SB(1, 1), b3 + bhs, voffB); PG8_STAGE(PG8_SA(1, 0), a3, voffA);
.LBB0_733:
	s_add_u32 s14, s70, 0x180
	s_addc_u32 s15, s71, 0
	s_waitcnt lgkmcnt(0)
	s_add_u32 s24, s68, 0x180
	s_addc_u32 s25, s69, 0
	s_barrier
	s_setprio 1
	v_mfma_f32_16x16x32_bf16 v[2:5], v[210:213], v[106:109], v[2:5]
	v_mfma_f32_16x16x32_bf16 v[162:165], v[214:217], v[130:133], v[2:5]
	v_mfma_f32_16x16x32_bf16 v[2:5], v[218:221], v[106:109], v[6:9]
	v_mfma_f32_16x16x32_bf16 v[154:157], v[222:225], v[130:133], v[2:5]
	v_mfma_f32_16x16x32_bf16 v[2:5], v[210:213], v[86:89], v[10:13]
	v_mfma_f32_16x16x32_bf16 v[118:121], v[214:217], v[102:105], v[2:5]
	v_mfma_f32_16x16x32_bf16 v[2:5], v[218:221], v[86:89], v[14:17]
	v_mfma_f32_16x16x32_bf16 v[110:113], v[222:225], v[102:105], v[2:5]
	v_mfma_f32_16x16x32_bf16 v[2:5], v[210:213], v[70:73], v[18:21]
	v_mfma_f32_16x16x32_bf16 v[94:97], v[214:217], v[82:85], v[2:5]
	v_mfma_f32_16x16x32_bf16 v[2:5], v[218:221], v[70:73], v[22:25]
	v_mfma_f32_16x16x32_bf16 v[90:93], v[222:225], v[82:85], v[2:5]
	v_mfma_f32_16x16x32_bf16 v[2:5], v[210:213], v[66:69], v[26:29]
	v_mfma_f32_16x16x32_bf16 v[78:81], v[214:217], v[226:229], v[2:5]
	v_mfma_f32_16x16x32_bf16 v[2:5], v[218:221], v[66:69], v[30:33]
	v_mfma_f32_16x16x32_bf16 v[74:77], v[222:225], v[226:229], v[2:5]
	s_setprio 0
	s_setprio 1
	v_mfma_f32_16x16x32_bf16 v[2:5], v[194:197], v[106:109], v[34:37]
	v_mfma_f32_16x16x32_bf16 v[146:149], v[198:201], v[130:133], v[2:5]
	v_mfma_f32_16x16x32_bf16 v[2:5], v[202:205], v[106:109], v[38:41]
	v_mfma_f32_16x16x32_bf16 v[130:133], v[206:209], v[130:133], v[2:5]
	v_mfma_f32_16x16x32_bf16 v[2:5], v[194:197], v[86:89], v[42:45]
	v_mfma_f32_16x16x32_bf16 v[106:109], v[198:201], v[102:105], v[2:5]
	v_mfma_f32_16x16x32_bf16 v[2:5], v[202:205], v[86:89], v[46:49]
	v_mfma_f32_16x16x32_bf16 v[102:105], v[206:209], v[102:105], v[2:5]
	v_mfma_f32_16x16x32_bf16 v[2:5], v[194:197], v[70:73], v[50:53]
	v_mfma_f32_16x16x32_bf16 v[86:89], v[198:201], v[82:85], v[2:5]
	v_mfma_f32_16x16x32_bf16 v[2:5], v[202:205], v[70:73], v[54:57]
	v_mfma_f32_16x16x32_bf16 v[82:85], v[206:209], v[82:85], v[2:5]
	v_mfma_f32_16x16x32_bf16 v[2:5], v[194:197], v[66:69], v[58:61]
	v_mfma_f32_16x16x32_bf16 v[70:73], v[198:201], v[226:229], v[2:5]
	v_mfma_f32_16x16x32_bf16 v[2:5], v[202:205], v[66:69], v[62:65]
	v_mfma_f32_16x16x32_bf16 v[66:69], v[206:209], v[226:229], v[2:5]
	s_setprio 0
	s_barrier
	s_nop 4
	ds_read_b128 v[2:5], v250 offset:49152
	ds_read_b128 v[6:9], v250 offset:50176
	ds_read_b128 v[18:21], v250 offset:51200
	ds_read_b128 v[22:25], v250 offset:52224
	ds_read_b128 v[226:229], v250 offset:53248
	ds_read_b128 v[236:239], v250 offset:54272
	ds_read_b128 v[240:243], v250 offset:55296
	ds_read_b128 v[246:249], v250 offset:56320
	s_mov_b32 m0, s64
	s_nop 0
	global_load_lds_dwordx4 v230, s[24:25]
	s_add_u32 m0, m0, 0x2000
	s_nop 0
	global_load_lds_dwordx4 v232, s[24:25]
	s_add_u32 s24, s68, 0xb0180
	s_addc_u32 s25, s69, 0
	s_mov_b32 m0, s66
	s_nop 0
	global_load_lds_dwordx4 v230, s[24:25]
	s_add_u32 m0, m0, 0x2000
	s_nop 0
	global_load_lds_dwordx4 v232, s[24:25]
	s_nop 0
	s_mov_b32 m0, s65
	s_nop 0
	global_load_lds_dwordx4 v0, s[14:15]
	s_add_u32 m0, m0, 0x2000
	s_nop 0
	global_load_lds_dwordx4 v231, s[14:15]
	s_waitcnt vmcnt(8)
	s_waitcnt lgkmcnt(0)
	s_barrier
	s_setprio 1
	v_mfma_f32_16x16x32_bf16 v[10:13], v[210:213], v[2:5], v[98:101]
	v_mfma_f32_16x16x32_bf16 v[62:65], v[214:217], v[6:9], v[10:13]
	v_mfma_f32_16x16x32_bf16 v[10:13], v[218:221], v[2:5], v[114:117]
	v_mfma_f32_16x16x32_bf16 v[58:61], v[222:225], v[6:9], v[10:13]
	v_mfma_f32_16x16x32_bf16 v[10:13], v[210:213], v[18:21], v[122:125]
	v_mfma_f32_16x16x32_bf16 v[46:49], v[214:217], v[22:25], v[10:13]
	v_mfma_f32_16x16x32_bf16 v[10:13], v[218:221], v[18:21], v[126:129]
	v_mfma_f32_16x16x32_bf16 v[42:45], v[222:225], v[22:25], v[10:13]
	v_mfma_f32_16x16x32_bf16 v[10:13], v[210:213], v[226:229], v[134:137]
	v_mfma_f32_16x16x32_bf16 v[30:33], v[214:217], v[236:239], v[10:13]
	v_mfma_f32_16x16x32_bf16 v[10:13], v[218:221], v[226:229], v[138:141]
	v_mfma_f32_16x16x32_bf16 v[26:29], v[222:225], v[236:239], v[10:13]
	v_mfma_f32_16x16x32_bf16 v[10:13], v[210:213], v[240:243], v[142:145]
	v_mfma_f32_16x16x32_bf16 v[14:17], v[214:217], v[246:249], v[10:13]
	v_mfma_f32_16x16x32_bf16 v[10:13], v[218:221], v[240:243], v[150:153]
	v_mfma_f32_16x16x32_bf16 v[10:13], v[222:225], v[246:249], v[10:13]
	s_setprio 0
	s_setprio 1
	v_mfma_f32_16x16x32_bf16 v[34:37], v[194:197], v[2:5], v[158:161]
	v_mfma_f32_16x16x32_bf16 v[2:5], v[202:205], v[2:5], v[166:169]
	v_mfma_f32_16x16x32_bf16 v[50:53], v[206:209], v[6:9], v[2:5]
	v_mfma_f32_16x16x32_bf16 v[2:5], v[194:197], v[18:21], v[170:173]
	v_mfma_f32_16x16x32_bf16 v[38:41], v[198:201], v[22:25], v[2:5]
	v_mfma_f32_16x16x32_bf16 v[2:5], v[202:205], v[18:21], v[174:177]
	v_mfma_f32_16x16x32_bf16 v[54:57], v[198:201], v[6:9], v[34:37]
	v_mfma_f32_16x16x32_bf16 v[34:37], v[206:209], v[22:25], v[2:5]
	v_mfma_f32_16x16x32_bf16 v[2:5], v[194:197], v[226:229], v[178:181]
	v_mfma_f32_16x16x32_bf16 v[22:25], v[198:201], v[236:239], v[2:5]
	v_mfma_f32_16x16x32_bf16 v[2:5], v[202:205], v[226:229], v[182:185]
	v_mfma_f32_16x16x32_bf16 v[18:21], v[206:209], v[236:239], v[2:5]
	v_mfma_f32_16x16x32_bf16 v[2:5], v[194:197], v[240:243], v[186:189]
	v_mfma_f32_16x16x32_bf16 v[6:9], v[198:201], v[246:249], v[2:5]
	v_mfma_f32_16x16x32_bf16 v[2:5], v[202:205], v[240:243], v[190:193]
	v_mfma_f32_16x16x32_bf16 v[2:5], v[206:209], v[246:249], v[2:5]
	s_setprio 0
	s_barrier
	s_add_u32 s19, s70, 0x200
	s_addc_u32 s24, s71, 0
	s_add_u32 s25, s68, 0x200
	s_addc_u32 s26, s69, 0
	s_add_u32 s68, s70, 0xb0180
	s_addc_u32 s69, s71, 0
	s_mov_b32 s0, 0
	s_branch .LBB0_735
; #define PG8_STAGE(bufoff, gbase, voff) glds16s2((voff)[0], (voff)[1], (const void*)(gbase), ldsn + (unsigned)(bufoff))
; #define PG8_LDA(dst, b, h) do { _Pragma("unroll") for (int m = 0; m < 4; ++m) _Pragma("unroll") for (int k = 0; k < 2; ++k) dst[m][k] = *(const LAS bf16x8*)(lds + PG8_SA(b, h) + aoff + m * 2048 + k * 1024); } while (0)
; #define PG8_WAIT_V(n) asm volatile("s_waitcnt vmcnt(" #n ")" ::: "memory")
; #define PG8_WAIT_L(n) asm volatile("s_waitcnt lgkmcnt(" #n ")" ::: "memory")
; template <class Epi, bool ALIGN_EPI, bool EARLY_DRAIN = true, class Pre = NoPre>
; __device__ __forceinline__ void gemm_phase(LAS unsigned char* lds, const Gemm g, const StaticOrder& S, const Epi& E, int wv, const Pre& pre = Pre()) {
;     ...
;         for (int t = th; t < th + (Epi::MIDK ? nt / 2 : nt); t += 2) {
;             const bool last = (t == nt - 2);
;             const char* a1 = cA + (size_t)(t + 1) * kstep;
;             const char* a2 = last ? nA : cA + (size_t)(t + 2) * kstep; const char* b2 = last ? nB : cB + (size_t)(t + 2) * kstep;
;             const char* a3 = a2 + kstep; const char* b3 = b2 + kstep;
;             int lf_ = EARLY_DRAIN ? __builtin_amdgcn_readfirstlane(landed_flag) : landed_flag; if constexpr (EARLY_DRAIN) asm volatile("" : "+s"(lf_)); landed_flag = 0;
;             PG8_LDB(B0, 0, 0); PG8_LDB(B1, 0, 1); PG8_SCHED; PG8_LDA(At, 0, 0); PG8_STAGE(PG8_SA(1, 1), a1 + ahs, voffA);
;             if (!lf_) PG8_WAIT_V(8);
;             PG8_WAIT_L(0); PG8_BAR; PG8_MMA(0, 0, At, B0); PG8_MMA(0, 1, At, B1); PG8_BAR; PG8_SCHED;
;             PG8_LDA(At, 0, 1); PG8_STAGE(PG8_SB(0, 0), b2, voffB); PG8_STAGE(PG8_SB(0, 1), b2 + bhs, voffB); PG8_STAGE(PG8_SA(0, 0), a2, voffA);
;             if (!lf_) PG8_WAIT_V(8);
;             PG8_WAIT_L(0); PG8_BAR; PG8_MMA(1, 0, At, B0); PG8_MMA(1, 1, At, B1); PG8_BAR; PG8_SCHED;
;             PG8_LDB(B0, 1, 0); PG8_LDB(B1, 1, 1); PG8_SCHED; PG8_LDA(At, 1, 0); PG8_STAGE(PG8_SA(0, 1), a2 + ahs, voffA);
;             if (!lf_) PG8_WAIT_V(8);
;             PG8_WAIT_L(0); PG8_BAR; PG8_MMA(0, 0, At, B0); PG8_MMA(0, 1, At, B1); PG8_BAR; PG8_SCHED;
;             PG8_LDA(At, 1, 1); PG8_STAGE(PG8_SB(1, 0), b3, voffB); PG8_STAGE(PG8_SB(1, 1), b3 + bhs, voffB); PG8_STAGE(PG8_SA(1, 0), a3, voffA);
;             PG8_WAIT_V(8); PG8_WAIT_L(0); PG8_BAR; PG8_MMA(1, 0, At, B0); PG8_MMA(1, 1, At, B1); PG8_BAR; PG8_SCHED;
.LBB0_734:
	s_add_u32 s14, s84, 0x80
	s_waitcnt lgkmcnt(0)
	s_addc_u32 s15, s85, 0
	s_add_u32 s38, s70, 0x80
	s_addc_u32 s39, s71, 0
	s_barrier
	s_setprio 1
	v_mfma_f32_16x16x32_bf16 v[98:101], v[158:161], v[130:133], v[98:101]
	v_mfma_f32_16x16x32_bf16 v[162:165], v[166:169], v[202:205], v[98:101]
	v_mfma_f32_16x16x32_bf16 v[98:101], v[170:173], v[130:133], v[114:117]
	v_mfma_f32_16x16x32_bf16 v[154:157], v[174:177], v[202:205], v[98:101]
	v_mfma_f32_16x16x32_bf16 v[98:101], v[158:161], v[194:197], v[118:121]
	v_mfma_f32_16x16x32_bf16 v[118:121], v[166:169], v[198:201], v[98:101]
	v_mfma_f32_16x16x32_bf16 v[98:101], v[170:173], v[194:197], v[110:113]
	v_mfma_f32_16x16x32_bf16 v[94:97], v[158:161], v[186:189], v[94:97]
	v_mfma_f32_16x16x32_bf16 v[90:93], v[170:173], v[186:189], v[90:93]
	v_mfma_f32_16x16x32_bf16 v[78:81], v[158:161], v[178:181], v[78:81]
	v_mfma_f32_16x16x32_bf16 v[74:77], v[170:173], v[178:181], v[74:77]
	v_mfma_f32_16x16x32_bf16 v[110:113], v[174:177], v[198:201], v[98:101]
	v_mfma_f32_16x16x32_bf16 v[94:97], v[166:169], v[190:193], v[94:97]
	v_mfma_f32_16x16x32_bf16 v[90:93], v[174:177], v[190:193], v[90:93]
	v_mfma_f32_16x16x32_bf16 v[78:81], v[166:169], v[182:185], v[78:81]
	v_mfma_f32_16x16x32_bf16 v[74:77], v[174:177], v[182:185], v[74:77]
	s_setprio 0
	s_setprio 1
	v_mfma_f32_16x16x32_bf16 v[98:101], v[134:137], v[130:133], v[122:125]
	v_mfma_f32_16x16x32_bf16 v[146:149], v[138:141], v[202:205], v[98:101]
	v_mfma_f32_16x16x32_bf16 v[98:101], v[142:145], v[130:133], v[126:129]
	v_mfma_f32_16x16x32_bf16 v[130:133], v[150:153], v[202:205], v[98:101]
	v_mfma_f32_16x16x32_bf16 v[98:101], v[134:137], v[194:197], v[106:109]
	v_mfma_f32_16x16x32_bf16 v[106:109], v[138:141], v[198:201], v[98:101]
	v_mfma_f32_16x16x32_bf16 v[98:101], v[142:145], v[194:197], v[102:105]
	v_mfma_f32_16x16x32_bf16 v[86:89], v[134:137], v[186:189], v[86:89]
	v_mfma_f32_16x16x32_bf16 v[82:85], v[142:145], v[186:189], v[82:85]
	v_mfma_f32_16x16x32_bf16 v[70:73], v[134:137], v[178:181], v[70:73]
	v_mfma_f32_16x16x32_bf16 v[66:69], v[142:145], v[178:181], v[66:69]
	v_mfma_f32_16x16x32_bf16 v[102:105], v[150:153], v[198:201], v[98:101]
	v_mfma_f32_16x16x32_bf16 v[86:89], v[138:141], v[190:193], v[86:89]
	v_mfma_f32_16x16x32_bf16 v[82:85], v[150:153], v[190:193], v[82:85]
	v_mfma_f32_16x16x32_bf16 v[70:73], v[138:141], v[182:185], v[70:73]
	v_mfma_f32_16x16x32_bf16 v[66:69], v[150:153], v[182:185], v[66:69]
	s_setprio 0
	s_barrier
	ds_read_b128 v[98:101], v250 offset:49152
	ds_read_b128 v[114:117], v250 offset:50176
	ds_read_b128 v[122:125], v250 offset:51200
	ds_read_b128 v[126:129], v250 offset:52224
	ds_read_b128 v[178:181], v250 offset:53248
	ds_read_b128 v[182:185], v250 offset:54272
	ds_read_b128 v[186:189], v250 offset:55296
	ds_read_b128 v[190:193], v250 offset:56320
	s_mov_b32 m0, s64
	s_nop 0
	global_load_lds_dwordx4 v230, s[38:39]
	s_add_u32 m0, m0, 0x2000
	s_nop 0
	global_load_lds_dwordx4 v232, s[38:39]
	s_add_u32 s38, s70, 0xb0080
	s_addc_u32 s39, s71, 0
	s_mov_b32 m0, s66
	s_nop 0
	global_load_lds_dwordx4 v230, s[38:39]
	s_add_u32 m0, m0, 0x2000
	s_nop 0
	global_load_lds_dwordx4 v232, s[38:39]
	s_nop 0
	s_mov_b32 m0, s65
	s_nop 0
	global_load_lds_dwordx4 v0, s[14:15]
	s_add_u32 m0, m0, 0x2000
	s_nop 0
	global_load_lds_dwordx4 v231, s[14:15]
	s_waitcnt vmcnt(8)
	s_waitcnt lgkmcnt(0)
	s_barrier
	s_setprio 1
	v_mfma_f32_16x16x32_bf16 v[62:65], v[158:161], v[98:101], v[62:65]
	v_mfma_f32_16x16x32_bf16 v[58:61], v[170:173], v[98:101], v[58:61]
	v_mfma_f32_16x16x32_bf16 v[46:49], v[158:161], v[122:125], v[46:49]
	v_mfma_f32_16x16x32_bf16 v[42:45], v[170:173], v[122:125], v[42:45]
	v_mfma_f32_16x16x32_bf16 v[30:33], v[158:161], v[178:181], v[30:33]
	v_mfma_f32_16x16x32_bf16 v[26:29], v[170:173], v[178:181], v[26:29]
	v_mfma_f32_16x16x32_bf16 v[14:17], v[158:161], v[186:189], v[14:17]
	v_mfma_f32_16x16x32_bf16 v[10:13], v[170:173], v[186:189], v[10:13]
	v_mfma_f32_16x16x32_bf16 v[62:65], v[166:169], v[114:117], v[62:65]
	v_mfma_f32_16x16x32_bf16 v[58:61], v[174:177], v[114:117], v[58:61]
	v_mfma_f32_16x16x32_bf16 v[46:49], v[166:169], v[126:129], v[46:49]
	v_mfma_f32_16x16x32_bf16 v[42:45], v[174:177], v[126:129], v[42:45]
	v_mfma_f32_16x16x32_bf16 v[30:33], v[166:169], v[182:185], v[30:33]
	v_mfma_f32_16x16x32_bf16 v[26:29], v[174:177], v[182:185], v[26:29]
	v_mfma_f32_16x16x32_bf16 v[14:17], v[166:169], v[190:193], v[14:17]
	v_mfma_f32_16x16x32_bf16 v[10:13], v[174:177], v[190:193], v[10:13]
	s_setprio 0
	s_setprio 1
	v_mfma_f32_16x16x32_bf16 v[54:57], v[134:137], v[98:101], v[54:57]
	v_mfma_f32_16x16x32_bf16 v[50:53], v[142:145], v[98:101], v[50:53]
	v_mfma_f32_16x16x32_bf16 v[38:41], v[134:137], v[122:125], v[38:41]
	v_mfma_f32_16x16x32_bf16 v[34:37], v[142:145], v[122:125], v[34:37]
	v_mfma_f32_16x16x32_bf16 v[22:25], v[134:137], v[178:181], v[22:25]
	v_mfma_f32_16x16x32_bf16 v[18:21], v[142:145], v[178:181], v[18:21]
	v_mfma_f32_16x16x32_bf16 v[6:9], v[134:137], v[186:189], v[6:9]
	v_mfma_f32_16x16x32_bf16 v[2:5], v[142:145], v[186:189], v[2:5]
	v_mfma_f32_16x16x32_bf16 v[54:57], v[138:141], v[114:117], v[54:57]
	v_mfma_f32_16x16x32_bf16 v[50:53], v[150:153], v[114:117], v[50:53]
	v_mfma_f32_16x16x32_bf16 v[38:41], v[138:141], v[126:129], v[38:41]
	v_mfma_f32_16x16x32_bf16 v[34:37], v[150:153], v[126:129], v[34:37]
	v_mfma_f32_16x16x32_bf16 v[22:25], v[138:141], v[182:185], v[22:25]
	v_mfma_f32_16x16x32_bf16 v[18:21], v[150:153], v[182:185], v[18:21]
	v_mfma_f32_16x16x32_bf16 v[6:9], v[138:141], v[190:193], v[6:9]
	v_mfma_f32_16x16x32_bf16 v[2:5], v[150:153], v[190:193], v[2:5]
	s_setprio 0
	s_barrier
	s_add_i32 s0, s0, 2
	s_add_u32 s19, s19, 0x100
	s_addc_u32 s24, s24, 0
	s_add_u32 s25, s25, 0x100
	s_addc_u32 s26, s26, 0
	s_add_u32 s68, s68, 0x100
	s_addc_u32 s69, s69, 0
	s_cmp_gt_u32 s0, 41
	s_cbranch_scc1 .LBB0_741

; #define PG8_STAGE(bufoff, gbase, voff) glds16s2((voff)[0], (voff)[1], (const void*)(gbase), ldsn + (unsigned)(bufoff))
; #define PG8_LDA(dst, b, h) do { _Pragma("unroll") for (int m = 0; m < 4; ++m) _Pragma("unroll") for (int k = 0; k < 2; ++k) dst[m][k] = *(const LAS bf16x8*)(lds + PG8_SA(b, h) + aoff + m * 2048 + k * 1024); } while (0)
; #define PG8_LDB(dst, b, h) do { _Pragma("unroll") for (int n = 0; n < 2; ++n) _Pragma("unroll") for (int k = 0; k < 2; ++k) dst[n][k] = *(const LAS bf16x8*)(lds + PG8_SB(b, h) + boff + n * 2048 + k * 1024); } while (0)
; #define PG8_WAIT_V(n) asm volatile("s_waitcnt vmcnt(" #n ")" ::: "memory")
; #define PG8_WAIT_L(n) asm volatile("s_waitcnt lgkmcnt(" #n ")" ::: "memory")
; #define PG8_BAR __builtin_amdgcn_s_barrier()
; #define PG8_SCHED __builtin_amdgcn_sched_barrier(0)
; template <class Epi, bool ALIGN_EPI, bool EARLY_DRAIN = true, class Pre = NoPre>
; __device__ __forceinline__ void gemm_phase(LAS unsigned char* lds, const Gemm g, const StaticOrder& S, const Epi& E, int wv, const Pre& pre = Pre()) {
;     ...
;             const bool last = (t == nt - 2);
;             const char* a1 = cA + (size_t)(t + 1) * kstep;
;             const char* a2 = last ? nA : cA + (size_t)(t + 2) * kstep; const char* b2 = last ? nB : cB + (size_t)(t + 2) * kstep;
;             const char* a3 = a2 + kstep; const char* b3 = b2 + kstep;
;             int lf_ = EARLY_DRAIN ? __builtin_amdgcn_readfirstlane(landed_flag) : landed_flag; if constexpr (EARLY_DRAIN) asm volatile("" : "+s"(lf_)); landed_flag = 0;
;             PG8_LDB(B0, 0, 0); PG8_LDB(B1, 0, 1); PG8_SCHED; PG8_LDA(At, 0, 0); PG8_STAGE(PG8_SA(1, 1), a1 + ahs, voffA);
;             if (!lf_) PG8_WAIT_V(8);
;             PG8_WAIT_L(0); PG8_BAR; PG8_MMA(0, 0, At, B0); PG8_MMA(0, 1, At, B1); PG8_BAR; PG8_SCHED;
;             PG8_LDA(At, 0, 1); PG8_STAGE(PG8_SB(0, 0), b2, voffB); PG8_STAGE(PG8_SB(0, 1), b2 + bhs, voffB); PG8_STAGE(PG8_SA(0, 0), a2, voffA);
;             if (!lf_) PG8_WAIT_V(8);
;             PG8_WAIT_L(0); PG8_BAR; PG8_MMA(1, 0, At, B0); PG8_MMA(1, 1, At, B1); PG8_BAR; PG8_SCHED;
;             PG8_LDB(B0, 1, 0); PG8_LDB(B1, 1, 1); PG8_SCHED; PG8_LDA(At, 1, 0); PG8_STAGE(PG8_SA(0, 1), a2 + ahs, voffA);
;             if (!lf_) PG8_WAIT_V(8);
;             PG8_WAIT_L(0); PG8_BAR; PG8_MMA(0, 0, At, B0); PG8_MMA(0, 1, At, B1); PG8_BAR; PG8_SCHED;
.LBB0_737:
	s_waitcnt lgkmcnt(0)
	s_cmp_eq_u32 s0, 40
	s_cselect_b32 s85, s35, s24
	s_cselect_b32 s84, s34, s19
	s_cselect_b32 s71, s77, s26
	s_cselect_b32 s70, s76, s25
	s_barrier
	s_setprio 1
	v_mfma_f32_16x16x32_bf16 v[98:101], v[158:161], v[126:129], v[162:165]
	v_mfma_f32_16x16x32_bf16 v[114:117], v[170:173], v[126:129], v[154:157]
	v_mfma_f32_16x16x32_bf16 v[118:121], v[158:161], v[194:197], v[118:121]
	v_mfma_f32_16x16x32_bf16 v[110:113], v[170:173], v[194:197], v[110:113]
	v_mfma_f32_16x16x32_bf16 v[94:97], v[158:161], v[186:189], v[94:97]
	v_mfma_f32_16x16x32_bf16 v[90:93], v[170:173], v[186:189], v[90:93]
	v_mfma_f32_16x16x32_bf16 v[78:81], v[158:161], v[178:181], v[78:81]
	v_mfma_f32_16x16x32_bf16 v[74:77], v[170:173], v[178:181], v[74:77]
	v_mfma_f32_16x16x32_bf16 v[98:101], v[166:169], v[202:205], v[98:101]
	v_mfma_f32_16x16x32_bf16 v[114:117], v[174:177], v[202:205], v[114:117]
	v_mfma_f32_16x16x32_bf16 v[118:121], v[166:169], v[198:201], v[118:121]
	v_mfma_f32_16x16x32_bf16 v[110:113], v[174:177], v[198:201], v[110:113]
	v_mfma_f32_16x16x32_bf16 v[94:97], v[166:169], v[190:193], v[94:97]
	v_mfma_f32_16x16x32_bf16 v[90:93], v[174:177], v[190:193], v[90:93]
	v_mfma_f32_16x16x32_bf16 v[78:81], v[166:169], v[182:185], v[78:81]
	v_mfma_f32_16x16x32_bf16 v[74:77], v[174:177], v[182:185], v[74:77]
	s_setprio 0
	s_setprio 1
	v_mfma_f32_16x16x32_bf16 v[122:125], v[134:137], v[126:129], v[146:149]
	v_mfma_f32_16x16x32_bf16 v[126:129], v[142:145], v[126:129], v[130:133]
	v_mfma_f32_16x16x32_bf16 v[106:109], v[134:137], v[194:197], v[106:109]
	v_mfma_f32_16x16x32_bf16 v[102:105], v[142:145], v[194:197], v[102:105]
	v_mfma_f32_16x16x32_bf16 v[86:89], v[134:137], v[186:189], v[86:89]
	v_mfma_f32_16x16x32_bf16 v[82:85], v[142:145], v[186:189], v[82:85]
	v_mfma_f32_16x16x32_bf16 v[70:73], v[134:137], v[178:181], v[70:73]
	v_mfma_f32_16x16x32_bf16 v[66:69], v[142:145], v[178:181], v[66:69]
	v_mfma_f32_16x16x32_bf16 v[122:125], v[138:141], v[202:205], v[122:125]
	v_mfma_f32_16x16x32_bf16 v[126:129], v[150:153], v[202:205], v[126:129]
	v_mfma_f32_16x16x32_bf16 v[106:109], v[138:141], v[198:201], v[106:109]
	v_mfma_f32_16x16x32_bf16 v[102:105], v[150:153], v[198:201], v[102:105]
	v_mfma_f32_16x16x32_bf16 v[86:89], v[138:141], v[190:193], v[86:89]
	v_mfma_f32_16x16x32_bf16 v[82:85], v[150:153], v[190:193], v[82:85]
	v_mfma_f32_16x16x32_bf16 v[70:73], v[138:141], v[182:185], v[70:73]
	v_mfma_f32_16x16x32_bf16 v[66:69], v[150:153], v[182:185], v[66:69]
	s_setprio 0
	s_barrier
	ds_read_b128 v[186:189], v250 offset:16384
	ds_read_b128 v[190:193], v250 offset:17408
	ds_read_b128 v[178:181], v250 offset:18432
	ds_read_b128 v[182:185], v250 offset:19456
	ds_read_b128 v[154:157], v250 offset:20480
	ds_read_b128 v[162:165], v250 offset:21504
	ds_read_b128 v[130:133], v250 offset:22528
	ds_read_b128 v[146:149], v250 offset:23552
	s_mov_b32 m0, s12
	s_nop 0
	global_load_lds_dwordx4 v230, s[70:71]
	s_add_u32 m0, m0, 0x2000
	s_nop 0
	global_load_lds_dwordx4 v232, s[70:71]
	s_add_u32 s14, s70, 0xb0000
	s_addc_u32 s15, s71, 0
	s_mov_b32 m0, s13
	s_nop 0
	global_load_lds_dwordx4 v230, s[14:15]
	s_add_u32 m0, m0, 0x2000
	s_nop 0
	global_load_lds_dwordx4 v232, s[14:15]
	s_mov_b32 m0, s10
	s_nop 0
	global_load_lds_dwordx4 v0, s[84:85]
	s_add_u32 m0, m0, 0x2000
	s_nop 0
	global_load_lds_dwordx4 v231, s[84:85]
	s_waitcnt vmcnt(8)
.LBB0_739:
	s_waitcnt lgkmcnt(0)
	s_barrier
	s_setprio 1
	v_mfma_f32_16x16x32_bf16 v[62:65], v[158:161], v[186:189], v[62:65]
	v_mfma_f32_16x16x32_bf16 v[58:61], v[170:173], v[186:189], v[58:61]
	v_mfma_f32_16x16x32_bf16 v[46:49], v[158:161], v[178:181], v[46:49]
	v_mfma_f32_16x16x32_bf16 v[42:45], v[170:173], v[178:181], v[42:45]
	v_mfma_f32_16x16x32_bf16 v[30:33], v[158:161], v[154:157], v[30:33]
	v_mfma_f32_16x16x32_bf16 v[26:29], v[170:173], v[154:157], v[26:29]
	v_mfma_f32_16x16x32_bf16 v[14:17], v[158:161], v[130:133], v[14:17]
	v_mfma_f32_16x16x32_bf16 v[10:13], v[170:173], v[130:133], v[10:13]
	v_mfma_f32_16x16x32_bf16 v[62:65], v[166:169], v[190:193], v[62:65]
	v_mfma_f32_16x16x32_bf16 v[58:61], v[174:177], v[190:193], v[58:61]
	v_mfma_f32_16x16x32_bf16 v[46:49], v[166:169], v[182:185], v[46:49]
	v_mfma_f32_16x16x32_bf16 v[42:45], v[174:177], v[182:185], v[42:45]
	v_mfma_f32_16x16x32_bf16 v[30:33], v[166:169], v[162:165], v[30:33]
	v_mfma_f32_16x16x32_bf16 v[26:29], v[174:177], v[162:165], v[26:29]
	v_mfma_f32_16x16x32_bf16 v[14:17], v[166:169], v[146:149], v[14:17]
	v_mfma_f32_16x16x32_bf16 v[10:13], v[174:177], v[146:149], v[10:13]
	s_setprio 0
	s_setprio 1
	v_mfma_f32_16x16x32_bf16 v[54:57], v[134:137], v[186:189], v[54:57]
	v_mfma_f32_16x16x32_bf16 v[50:53], v[142:145], v[186:189], v[50:53]
	v_mfma_f32_16x16x32_bf16 v[38:41], v[134:137], v[178:181], v[38:41]
	v_mfma_f32_16x16x32_bf16 v[34:37], v[142:145], v[178:181], v[34:37]
	v_mfma_f32_16x16x32_bf16 v[22:25], v[134:137], v[154:157], v[22:25]
	v_mfma_f32_16x16x32_bf16 v[18:21], v[142:145], v[154:157], v[18:21]
	v_mfma_f32_16x16x32_bf16 v[6:9], v[134:137], v[130:133], v[6:9]
	v_mfma_f32_16x16x32_bf16 v[2:5], v[142:145], v[130:133], v[2:5]
	v_mfma_f32_16x16x32_bf16 v[54:57], v[138:141], v[190:193], v[54:57]
	v_mfma_f32_16x16x32_bf16 v[50:53], v[150:153], v[190:193], v[50:53]
	v_mfma_f32_16x16x32_bf16 v[38:41], v[138:141], v[182:185], v[38:41]
	v_mfma_f32_16x16x32_bf16 v[34:37], v[150:153], v[182:185], v[34:37]
	v_mfma_f32_16x16x32_bf16 v[22:25], v[138:141], v[162:165], v[22:25]
	v_mfma_f32_16x16x32_bf16 v[18:21], v[150:153], v[162:165], v[18:21]
	v_mfma_f32_16x16x32_bf16 v[6:9], v[138:141], v[146:149], v[6:9]
	v_mfma_f32_16x16x32_bf16 v[2:5], v[150:153], v[146:149], v[2:5]
	s_setprio 0
	s_barrier
	ds_read_b128 v[158:161], v244
	ds_read_b128 v[166:169], v244 offset:1024
	ds_read_b128 v[170:173], v244 offset:2048
	ds_read_b128 v[174:177], v244 offset:3072
	ds_read_b128 v[134:137], v245
	ds_read_b128 v[138:141], v245 offset:1024
	ds_read_b128 v[142:145], v245 offset:2048
	ds_read_b128 v[150:153], v245 offset:3072
	ds_read_b128 v[130:133], v250 offset:32768
	ds_read_b128 v[202:205], v250 offset:33792
	ds_read_b128 v[194:197], v250 offset:34816
	ds_read_b128 v[198:201], v250 offset:35840
	ds_read_b128 v[186:189], v250 offset:36864
	ds_read_b128 v[190:193], v250 offset:37888
	ds_read_b128 v[178:181], v250 offset:38912
	ds_read_b128 v[182:185], v250 offset:39936
	s_add_u32 s14, s84, 0xb0000
	s_addc_u32 s15, s85, 0
	s_mov_b32 m0, s99
	s_nop 0
	global_load_lds_dwordx4 v0, s[14:15]
	s_add_u32 m0, m0, 0x2000
	s_nop 0
	global_load_lds_dwordx4 v231, s[14:15]
	s_waitcnt vmcnt(8)
	s_branch .LBB0_734
	s_nop 0
	s_nop 0
	s_nop 0
	s_nop 0
	s_nop 0
	s_nop 0
	s_nop 0
	s_nop 0
	s_nop 0
	s_nop 0
	s_nop 0
	s_nop 0
	s_nop 0
